# v47 + load parts rescheduled: LDS-DMA loads issued before the LDS reads
# speedup vs baseline: 1.0004x; 1.0004x over previous
.LBB0_261:
	s_add_u32 s0, s76, 0xfff80080
	s_addc_u32 s1, s77, -1
	s_and_b64 s[84:85], s[84:85], exec
	s_cselect_b32 vcc_hi, s22, s1
	s_cselect_b32 vcc_lo, s23, s0
	s_cselect_b32 s85, s49, s58
	s_cselect_b32 s84, s57, s51
	s_add_i32 s0, 0, 0x10000
	s_add_i32 s1, 0, 0x14000
	s_add_i32 m0, s21, 0xc000
	s_nop 0
	global_load_lds_dwordx4 v138, s[76:77]
	s_add_i32 m0, s21, 0xe000
	s_nop 0
	global_load_lds_dwordx4 v140, s[76:77]
	v_add_u32_e32 v158, s0, v176
	v_add_u32_e32 v174, s1, v176
	ds_read_b128 v[146:149], v158
	ds_read_b128 v[150:153], v158 offset:1024
	ds_read_b128 v[154:157], v158 offset:2048
	ds_read_b128 v[158:161], v158 offset:3072
	ds_read_b128 v[162:165], v174
	ds_read_b128 v[166:169], v174 offset:1024
	ds_read_b128 v[170:173], v174 offset:2048
	ds_read_b128 v[178:181], v174 offset:3072
	ds_read_b128 v[182:185], v177
	ds_read_b128 v[186:189], v177 offset:1024
	ds_read_b128 v[190:193], v177 offset:2048
	ds_read_b128 v[204:207], v177 offset:3072
	ds_read_b128 v[208:211], v177 offset:4096
	ds_read_b128 v[212:215], v177 offset:5120
	ds_read_b128 v[216:219], v177 offset:6144
	ds_read_b128 v[220:223], v177 offset:7168
	s_waitcnt vmcnt(8)
	s_waitcnt lgkmcnt(0)
	s_barrier
	s_setprio 1
	s_waitcnt lgkmcnt(0)
	v_mfma_f32_16x16x32_bf16 v[126:129], v[146:149], v[182:185], v[126:129]
	v_mfma_f32_16x16x32_bf16 v[126:129], v[150:153], v[186:189], v[126:129]
	v_mfma_f32_16x16x32_bf16 v[122:125], v[158:161], v[186:189], v[122:125]
	v_mfma_f32_16x16x32_bf16 v[122:125], v[154:157], v[182:185], v[122:125]
	v_mfma_f32_16x16x32_bf16 v[118:121], v[162:165], v[182:185], v[118:121]
	v_mfma_f32_16x16x32_bf16 v[118:121], v[166:169], v[186:189], v[118:121]
	v_mfma_f32_16x16x32_bf16 v[114:117], v[178:181], v[186:189], v[114:117]
	v_mfma_f32_16x16x32_bf16 v[114:117], v[170:173], v[182:185], v[114:117]
	v_mfma_f32_16x16x32_bf16 v[98:101], v[170:173], v[190:193], v[98:101]
	v_mfma_f32_16x16x32_bf16 v[98:101], v[178:181], v[204:207], v[98:101]
	v_mfma_f32_16x16x32_bf16 v[102:105], v[166:169], v[204:207], v[102:105]
	v_mfma_f32_16x16x32_bf16 v[102:105], v[162:165], v[190:193], v[102:105]
	v_mfma_f32_16x16x32_bf16 v[106:109], v[154:157], v[190:193], v[106:109]
	v_mfma_f32_16x16x32_bf16 v[106:109], v[158:161], v[204:207], v[106:109]
	v_mfma_f32_16x16x32_bf16 v[110:113], v[150:153], v[204:207], v[110:113]
	v_mfma_f32_16x16x32_bf16 v[110:113], v[146:149], v[190:193], v[110:113]
	v_mfma_f32_16x16x32_bf16 v[94:97], v[146:149], v[208:211], v[94:97]
	v_mfma_f32_16x16x32_bf16 v[94:97], v[150:153], v[212:215], v[94:97]
	v_mfma_f32_16x16x32_bf16 v[90:93], v[158:161], v[212:215], v[90:93]
	v_mfma_f32_16x16x32_bf16 v[90:93], v[154:157], v[208:211], v[90:93]
	v_mfma_f32_16x16x32_bf16 v[86:89], v[162:165], v[208:211], v[86:89]
	v_mfma_f32_16x16x32_bf16 v[86:89], v[166:169], v[212:215], v[86:89]
	v_mfma_f32_16x16x32_bf16 v[82:85], v[178:181], v[212:215], v[82:85]
	v_mfma_f32_16x16x32_bf16 v[82:85], v[170:173], v[208:211], v[82:85]
	v_mfma_f32_16x16x32_bf16 v[66:69], v[170:173], v[216:219], v[66:69]
	v_mfma_f32_16x16x32_bf16 v[66:69], v[178:181], v[220:223], v[66:69]
	v_mfma_f32_16x16x32_bf16 v[70:73], v[166:169], v[220:223], v[70:73]
	v_mfma_f32_16x16x32_bf16 v[70:73], v[162:165], v[216:219], v[70:73]
	v_mfma_f32_16x16x32_bf16 v[74:77], v[154:157], v[216:219], v[74:77]
	v_mfma_f32_16x16x32_bf16 v[74:77], v[158:161], v[220:223], v[74:77]
	v_mfma_f32_16x16x32_bf16 v[78:81], v[150:153], v[220:223], v[78:81]
	v_mfma_f32_16x16x32_bf16 v[78:81], v[146:149], v[216:219], v[78:81]
	s_setprio 0
	s_barrier
	s_add_i32 s0, s0, s20
	s_mov_b32 m0, s0
	s_nop 0
	global_load_lds_dwordx4 v132, s[84:85]
	s_add_i32 m0, s0, 0x2000
	s_add_u32 s94, s84, 0x80000
	s_addc_u32 s95, s85, 0
	s_add_i32 s0, s1, s20
	global_load_lds_dwordx4 v130, s[84:85]
	s_mov_b32 m0, s0
	s_nop 0
	global_load_lds_dwordx4 v132, s[94:95]
	s_add_i32 m0, s0, 0x2000
	s_nop 0
	global_load_lds_dwordx4 v130, s[94:95]
	s_mov_b32 m0, s21
	s_nop 0
	global_load_lds_dwordx4 v132, vcc
	s_mov_b32 m0, s26
	s_nop 0
	global_load_lds_dwordx4 v130, vcc
	ds_read_b128 v[182:185], v177 offset:16384
	ds_read_b128 v[186:189], v177 offset:17408
	ds_read_b128 v[190:193], v177 offset:18432
	ds_read_b128 v[204:207], v177 offset:19456
	ds_read_b128 v[208:211], v177 offset:20480
	ds_read_b128 v[212:215], v177 offset:21504
	ds_read_b128 v[216:219], v177 offset:22528
	ds_read_b128 v[220:223], v177 offset:23552
	s_waitcnt vmcnt(8)
	s_waitcnt lgkmcnt(0)
	s_barrier
	s_setprio 1
	s_waitcnt lgkmcnt(0)
	v_mfma_f32_16x16x32_bf16 v[62:65], v[146:149], v[182:185], v[62:65]
	v_mfma_f32_16x16x32_bf16 v[62:65], v[150:153], v[186:189], v[62:65]
	v_mfma_f32_16x16x32_bf16 v[58:61], v[158:161], v[186:189], v[58:61]
	v_mfma_f32_16x16x32_bf16 v[58:61], v[154:157], v[182:185], v[58:61]
	v_mfma_f32_16x16x32_bf16 v[54:57], v[162:165], v[182:185], v[54:57]
	v_mfma_f32_16x16x32_bf16 v[54:57], v[166:169], v[186:189], v[54:57]
	v_mfma_f32_16x16x32_bf16 v[50:53], v[178:181], v[186:189], v[50:53]
	v_mfma_f32_16x16x32_bf16 v[50:53], v[170:173], v[182:185], v[50:53]
	v_mfma_f32_16x16x32_bf16 v[34:37], v[170:173], v[190:193], v[34:37]
	v_mfma_f32_16x16x32_bf16 v[34:37], v[178:181], v[204:207], v[34:37]
	v_mfma_f32_16x16x32_bf16 v[38:41], v[166:169], v[204:207], v[38:41]
	v_mfma_f32_16x16x32_bf16 v[38:41], v[162:165], v[190:193], v[38:41]
	v_mfma_f32_16x16x32_bf16 v[42:45], v[154:157], v[190:193], v[42:45]
	v_mfma_f32_16x16x32_bf16 v[42:45], v[158:161], v[204:207], v[42:45]
	v_mfma_f32_16x16x32_bf16 v[46:49], v[150:153], v[204:207], v[46:49]
	v_mfma_f32_16x16x32_bf16 v[46:49], v[146:149], v[190:193], v[46:49]
	v_mfma_f32_16x16x32_bf16 v[30:33], v[146:149], v[208:211], v[30:33]
	v_mfma_f32_16x16x32_bf16 v[30:33], v[150:153], v[212:215], v[30:33]
	v_mfma_f32_16x16x32_bf16 v[26:29], v[158:161], v[212:215], v[26:29]
	v_mfma_f32_16x16x32_bf16 v[26:29], v[154:157], v[208:211], v[26:29]
	v_mfma_f32_16x16x32_bf16 v[22:25], v[162:165], v[208:211], v[22:25]
	v_mfma_f32_16x16x32_bf16 v[22:25], v[166:169], v[212:215], v[22:25]
	v_mfma_f32_16x16x32_bf16 v[18:21], v[178:181], v[212:215], v[18:21]
	v_mfma_f32_16x16x32_bf16 v[18:21], v[170:173], v[208:211], v[18:21]
	v_mfma_f32_16x16x32_bf16 v[2:5], v[170:173], v[216:219], v[2:5]
	v_mfma_f32_16x16x32_bf16 v[2:5], v[178:181], v[220:223], v[2:5]
	v_mfma_f32_16x16x32_bf16 v[6:9], v[166:169], v[220:223], v[6:9]
	v_mfma_f32_16x16x32_bf16 v[6:9], v[162:165], v[216:219], v[6:9]
	v_mfma_f32_16x16x32_bf16 v[10:13], v[154:157], v[216:219], v[10:13]
	v_mfma_f32_16x16x32_bf16 v[10:13], v[158:161], v[220:223], v[10:13]
	v_mfma_f32_16x16x32_bf16 v[14:17], v[150:153], v[220:223], v[14:17]
	v_mfma_f32_16x16x32_bf16 v[14:17], v[146:149], v[216:219], v[14:17]
	s_setprio 0
	s_barrier
	s_add_i32 s0, 0, 0x18000
	s_add_i32 s1, 0, 0x1c000
	s_add_u32 s94, vcc_lo, 0x80000
	s_addc_u32 s95, vcc_hi, 0
	s_mov_b32 m0, s27
	s_nop 0
	global_load_lds_dwordx4 v132, s[94:95]
	s_mov_b32 m0, s29
	s_nop 0
	global_load_lds_dwordx4 v130, s[94:95]
	v_add_u32_e32 v158, s0, v176
	v_add_u32_e32 v178, s1, v176
	ds_read_b128 v[146:149], v158
	ds_read_b128 v[150:153], v158 offset:1024
	ds_read_b128 v[154:157], v158 offset:2048
	ds_read_b128 v[158:161], v158 offset:3072
	ds_read_b128 v[162:165], v178
	ds_read_b128 v[166:169], v178 offset:1024
	ds_read_b128 v[170:173], v178 offset:2048
	ds_read_b128 v[178:181], v178 offset:3072
	ds_read_b128 v[182:185], v177 offset:32768
	ds_read_b128 v[186:189], v177 offset:33792
	ds_read_b128 v[190:193], v177 offset:34816
	ds_read_b128 v[204:207], v177 offset:35840
	ds_read_b128 v[208:211], v177 offset:36864
	ds_read_b128 v[212:215], v177 offset:37888
	ds_read_b128 v[216:219], v177 offset:38912
	ds_read_b128 v[220:223], v177 offset:39936
	s_waitcnt vmcnt(8)
	s_waitcnt lgkmcnt(0)
	s_barrier
	s_setprio 1
	s_waitcnt lgkmcnt(0)
	v_mfma_f32_16x16x32_bf16 v[126:129], v[146:149], v[182:185], v[126:129]
	v_mfma_f32_16x16x32_bf16 v[126:129], v[150:153], v[186:189], v[126:129]
	v_mfma_f32_16x16x32_bf16 v[122:125], v[158:161], v[186:189], v[122:125]
	v_mfma_f32_16x16x32_bf16 v[122:125], v[154:157], v[182:185], v[122:125]
	v_mfma_f32_16x16x32_bf16 v[118:121], v[162:165], v[182:185], v[118:121]
	v_mfma_f32_16x16x32_bf16 v[118:121], v[166:169], v[186:189], v[118:121]
	v_mfma_f32_16x16x32_bf16 v[114:117], v[178:181], v[186:189], v[114:117]
	v_mfma_f32_16x16x32_bf16 v[114:117], v[170:173], v[182:185], v[114:117]
	v_mfma_f32_16x16x32_bf16 v[98:101], v[170:173], v[190:193], v[98:101]
	v_mfma_f32_16x16x32_bf16 v[98:101], v[178:181], v[204:207], v[98:101]
	v_mfma_f32_16x16x32_bf16 v[102:105], v[166:169], v[204:207], v[102:105]
	v_mfma_f32_16x16x32_bf16 v[102:105], v[162:165], v[190:193], v[102:105]
	v_mfma_f32_16x16x32_bf16 v[106:109], v[154:157], v[190:193], v[106:109]
	v_mfma_f32_16x16x32_bf16 v[106:109], v[158:161], v[204:207], v[106:109]
	v_mfma_f32_16x16x32_bf16 v[110:113], v[150:153], v[204:207], v[110:113]
	v_mfma_f32_16x16x32_bf16 v[110:113], v[146:149], v[190:193], v[110:113]
	v_mfma_f32_16x16x32_bf16 v[94:97], v[146:149], v[208:211], v[94:97]
	v_mfma_f32_16x16x32_bf16 v[94:97], v[150:153], v[212:215], v[94:97]
	v_mfma_f32_16x16x32_bf16 v[90:93], v[158:161], v[212:215], v[90:93]
	v_mfma_f32_16x16x32_bf16 v[90:93], v[154:157], v[208:211], v[90:93]
	v_mfma_f32_16x16x32_bf16 v[86:89], v[162:165], v[208:211], v[86:89]
	v_mfma_f32_16x16x32_bf16 v[86:89], v[166:169], v[212:215], v[86:89]
	v_mfma_f32_16x16x32_bf16 v[82:85], v[178:181], v[212:215], v[82:85]
	v_mfma_f32_16x16x32_bf16 v[82:85], v[170:173], v[208:211], v[82:85]
	v_mfma_f32_16x16x32_bf16 v[66:69], v[170:173], v[216:219], v[66:69]
	v_mfma_f32_16x16x32_bf16 v[66:69], v[178:181], v[220:223], v[66:69]
	v_mfma_f32_16x16x32_bf16 v[70:73], v[166:169], v[220:223], v[70:73]
	v_mfma_f32_16x16x32_bf16 v[70:73], v[162:165], v[216:219], v[70:73]
	v_mfma_f32_16x16x32_bf16 v[74:77], v[154:157], v[216:219], v[74:77]
	v_mfma_f32_16x16x32_bf16 v[74:77], v[158:161], v[220:223], v[74:77]
	v_mfma_f32_16x16x32_bf16 v[78:81], v[150:153], v[220:223], v[78:81]
	v_mfma_f32_16x16x32_bf16 v[78:81], v[146:149], v[216:219], v[78:81]
	s_setprio 0
	s_barrier
	s_add_u32 s98, s84, 0x80
	s_addc_u32 s99, s85, 0
	s_add_u32 s100, vcc_lo, 0x80
	s_addc_u32 s101, vcc_hi, 0
	s_add_i32 s0, s0, s20
	s_mov_b32 m0, s0
	s_nop 0
	global_load_lds_dwordx4 v132, s[98:99]
	s_add_i32 m0, s0, 0x2000
	s_add_u32 s84, s84, 0x80080
	s_addc_u32 s85, s85, 0
	s_add_i32 s0, s1, s20
	global_load_lds_dwordx4 v130, s[98:99]
	s_mov_b32 m0, s0
	s_nop 0
	global_load_lds_dwordx4 v132, s[84:85]
	s_add_i32 m0, s0, 0x2000
	s_nop 0
	global_load_lds_dwordx4 v130, s[84:85]
	s_mov_b32 m0, s40
	s_nop 0
	global_load_lds_dwordx4 v132, s[100:101]
	s_mov_b32 m0, s41
	s_nop 0
	global_load_lds_dwordx4 v130, s[100:101]
	ds_read_b128 v[182:185], v177 offset:49152
	ds_read_b128 v[186:189], v177 offset:50176
	ds_read_b128 v[190:193], v177 offset:51200
	ds_read_b128 v[204:207], v177 offset:52224
	ds_read_b128 v[208:211], v177 offset:53248
	ds_read_b128 v[212:215], v177 offset:54272
	ds_read_b128 v[216:219], v177 offset:55296
	ds_read_b128 v[220:223], v177 offset:56320
	s_waitcnt vmcnt(8)
	s_waitcnt lgkmcnt(0)
	s_barrier
	s_setprio 1
	s_waitcnt lgkmcnt(0)
	v_mfma_f32_16x16x32_bf16 v[62:65], v[146:149], v[182:185], v[62:65]
	v_mfma_f32_16x16x32_bf16 v[62:65], v[150:153], v[186:189], v[62:65]
	v_mfma_f32_16x16x32_bf16 v[58:61], v[158:161], v[186:189], v[58:61]
	v_mfma_f32_16x16x32_bf16 v[58:61], v[154:157], v[182:185], v[58:61]
	v_mfma_f32_16x16x32_bf16 v[54:57], v[162:165], v[182:185], v[54:57]
	v_mfma_f32_16x16x32_bf16 v[54:57], v[166:169], v[186:189], v[54:57]
	v_mfma_f32_16x16x32_bf16 v[50:53], v[178:181], v[186:189], v[50:53]
	v_mfma_f32_16x16x32_bf16 v[50:53], v[170:173], v[182:185], v[50:53]
	v_mfma_f32_16x16x32_bf16 v[34:37], v[170:173], v[190:193], v[34:37]
	v_mfma_f32_16x16x32_bf16 v[34:37], v[178:181], v[204:207], v[34:37]
	v_mfma_f32_16x16x32_bf16 v[38:41], v[166:169], v[204:207], v[38:41]
	v_mfma_f32_16x16x32_bf16 v[38:41], v[162:165], v[190:193], v[38:41]
	v_mfma_f32_16x16x32_bf16 v[42:45], v[154:157], v[190:193], v[42:45]
	v_mfma_f32_16x16x32_bf16 v[42:45], v[158:161], v[204:207], v[42:45]
	v_mfma_f32_16x16x32_bf16 v[46:49], v[150:153], v[204:207], v[46:49]
	v_mfma_f32_16x16x32_bf16 v[46:49], v[146:149], v[190:193], v[46:49]
	v_mfma_f32_16x16x32_bf16 v[30:33], v[146:149], v[208:211], v[30:33]
	v_mfma_f32_16x16x32_bf16 v[30:33], v[150:153], v[212:215], v[30:33]
	v_mfma_f32_16x16x32_bf16 v[26:29], v[158:161], v[212:215], v[26:29]
	v_mfma_f32_16x16x32_bf16 v[26:29], v[154:157], v[208:211], v[26:29]
	v_mfma_f32_16x16x32_bf16 v[22:25], v[162:165], v[208:211], v[22:25]
	v_mfma_f32_16x16x32_bf16 v[22:25], v[166:169], v[212:215], v[22:25]
	v_mfma_f32_16x16x32_bf16 v[18:21], v[178:181], v[212:215], v[18:21]
	v_mfma_f32_16x16x32_bf16 v[18:21], v[170:173], v[208:211], v[18:21]
	v_mfma_f32_16x16x32_bf16 v[2:5], v[170:173], v[216:219], v[2:5]
	v_mfma_f32_16x16x32_bf16 v[2:5], v[178:181], v[220:223], v[2:5]
	v_mfma_f32_16x16x32_bf16 v[6:9], v[166:169], v[220:223], v[6:9]
	v_mfma_f32_16x16x32_bf16 v[6:9], v[162:165], v[216:219], v[6:9]
	v_mfma_f32_16x16x32_bf16 v[10:13], v[154:157], v[216:219], v[10:13]
	v_mfma_f32_16x16x32_bf16 v[10:13], v[158:161], v[220:223], v[10:13]
	v_mfma_f32_16x16x32_bf16 v[14:17], v[150:153], v[220:223], v[14:17]
	v_mfma_f32_16x16x32_bf16 v[14:17], v[146:149], v[216:219], v[14:17]
	s_setprio 0
	s_barrier
	s_add_i32 s65, s65, 2
	s_add_u32 s76, s76, 0x100
	s_addc_u32 s77, s77, 0
	s_add_u32 s51, s51, 0x100
	s_addc_u32 s58, s58, 0
	s_cmp_gt_u32 s65, 29
	s_cbranch_scc1 .LBB0_264

.Lpeel_disp_ine:
	s_cmp_lg_u32 s65, -2
	s_cbranch_scc1 .LBB0_261
	s_add_u32 s0, s76, 0xfff80080
	s_addc_u32 s1, s77, -1
	s_and_b64 s[84:85], s[84:85], exec
	s_cselect_b32 vcc_hi, s22, s1
	s_cselect_b32 vcc_lo, s23, s0
	s_cselect_b32 s85, s49, s58
	s_cselect_b32 s84, s57, s51
	s_add_i32 s0, 0, 0x10000
	s_add_i32 s1, 0, 0x14000
	s_add_i32 m0, s21, 0xc000
	s_nop 0
	global_load_lds_dwordx4 v138, s[76:77]
	s_add_i32 m0, s21, 0xe000
	s_nop 0
	global_load_lds_dwordx4 v140, s[76:77]
	v_add_u32_e32 v158, s0, v176
	v_add_u32_e32 v174, s1, v176
	ds_read_b128 v[146:149], v158
	ds_read_b128 v[150:153], v158 offset:1024
	ds_read_b128 v[154:157], v158 offset:2048
	ds_read_b128 v[158:161], v158 offset:3072
	ds_read_b128 v[162:165], v174
	ds_read_b128 v[166:169], v174 offset:1024
	ds_read_b128 v[170:173], v174 offset:2048
	ds_read_b128 v[178:181], v174 offset:3072
	ds_read_b128 v[182:185], v177
	ds_read_b128 v[186:189], v177 offset:1024
	ds_read_b128 v[190:193], v177 offset:2048
	ds_read_b128 v[204:207], v177 offset:3072
	ds_read_b128 v[208:211], v177 offset:4096
	ds_read_b128 v[212:215], v177 offset:5120
	ds_read_b128 v[216:219], v177 offset:6144
	ds_read_b128 v[220:223], v177 offset:7168
	s_waitcnt vmcnt(8)
	s_waitcnt lgkmcnt(0)
	s_barrier
	s_setprio 1
	s_waitcnt lgkmcnt(0)
	v_mfma_f32_16x16x32_bf16 v[126:129], v[146:149], v[182:185], 0
	v_mfma_f32_16x16x32_bf16 v[126:129], v[150:153], v[186:189], v[126:129]
	v_mfma_f32_16x16x32_bf16 v[122:125], v[158:161], v[186:189], 0
	v_mfma_f32_16x16x32_bf16 v[122:125], v[154:157], v[182:185], v[122:125]
	v_mfma_f32_16x16x32_bf16 v[118:121], v[162:165], v[182:185], 0
	v_mfma_f32_16x16x32_bf16 v[118:121], v[166:169], v[186:189], v[118:121]
	v_mfma_f32_16x16x32_bf16 v[114:117], v[178:181], v[186:189], 0
	v_mfma_f32_16x16x32_bf16 v[114:117], v[170:173], v[182:185], v[114:117]
	v_mfma_f32_16x16x32_bf16 v[98:101], v[170:173], v[190:193], 0
	v_mfma_f32_16x16x32_bf16 v[98:101], v[178:181], v[204:207], v[98:101]
	v_mfma_f32_16x16x32_bf16 v[102:105], v[166:169], v[204:207], 0
	v_mfma_f32_16x16x32_bf16 v[102:105], v[162:165], v[190:193], v[102:105]
	v_mfma_f32_16x16x32_bf16 v[106:109], v[154:157], v[190:193], 0
	v_mfma_f32_16x16x32_bf16 v[106:109], v[158:161], v[204:207], v[106:109]
	v_mfma_f32_16x16x32_bf16 v[110:113], v[150:153], v[204:207], 0
	v_mfma_f32_16x16x32_bf16 v[110:113], v[146:149], v[190:193], v[110:113]
	v_mfma_f32_16x16x32_bf16 v[94:97], v[146:149], v[208:211], 0
	v_mfma_f32_16x16x32_bf16 v[94:97], v[150:153], v[212:215], v[94:97]
	v_mfma_f32_16x16x32_bf16 v[90:93], v[158:161], v[212:215], 0
	v_mfma_f32_16x16x32_bf16 v[90:93], v[154:157], v[208:211], v[90:93]
	v_mfma_f32_16x16x32_bf16 v[86:89], v[162:165], v[208:211], 0
	v_mfma_f32_16x16x32_bf16 v[86:89], v[166:169], v[212:215], v[86:89]
	v_mfma_f32_16x16x32_bf16 v[82:85], v[178:181], v[212:215], 0
	v_mfma_f32_16x16x32_bf16 v[82:85], v[170:173], v[208:211], v[82:85]
	v_mfma_f32_16x16x32_bf16 v[66:69], v[170:173], v[216:219], 0
	v_mfma_f32_16x16x32_bf16 v[66:69], v[178:181], v[220:223], v[66:69]
	v_mfma_f32_16x16x32_bf16 v[70:73], v[166:169], v[220:223], 0
	v_mfma_f32_16x16x32_bf16 v[70:73], v[162:165], v[216:219], v[70:73]
	v_mfma_f32_16x16x32_bf16 v[74:77], v[154:157], v[216:219], 0
	v_mfma_f32_16x16x32_bf16 v[74:77], v[158:161], v[220:223], v[74:77]
	v_mfma_f32_16x16x32_bf16 v[78:81], v[150:153], v[220:223], 0
	v_mfma_f32_16x16x32_bf16 v[78:81], v[146:149], v[216:219], v[78:81]
	s_setprio 0
	s_barrier
	s_add_i32 s0, s0, s20
	s_mov_b32 m0, s0
	s_nop 0
	global_load_lds_dwordx4 v132, s[84:85]
	s_add_i32 m0, s0, 0x2000
	s_add_u32 s94, s84, 0x80000
	s_addc_u32 s95, s85, 0
	s_add_i32 s0, s1, s20
	global_load_lds_dwordx4 v130, s[84:85]
	s_mov_b32 m0, s0
	s_nop 0
	global_load_lds_dwordx4 v132, s[94:95]
	s_add_i32 m0, s0, 0x2000
	s_nop 0
	global_load_lds_dwordx4 v130, s[94:95]
	s_mov_b32 m0, s21
	s_nop 0
	global_load_lds_dwordx4 v132, vcc
	s_mov_b32 m0, s26
	s_nop 0
	global_load_lds_dwordx4 v130, vcc
	ds_read_b128 v[182:185], v177 offset:16384
	ds_read_b128 v[186:189], v177 offset:17408
	ds_read_b128 v[190:193], v177 offset:18432
	ds_read_b128 v[204:207], v177 offset:19456
	ds_read_b128 v[208:211], v177 offset:20480
	ds_read_b128 v[212:215], v177 offset:21504
	ds_read_b128 v[216:219], v177 offset:22528
	ds_read_b128 v[220:223], v177 offset:23552
	s_waitcnt vmcnt(8)
	s_waitcnt lgkmcnt(0)
	s_barrier
	s_setprio 1
	s_waitcnt lgkmcnt(0)
	v_mfma_f32_16x16x32_bf16 v[62:65], v[146:149], v[182:185], 0
	v_mfma_f32_16x16x32_bf16 v[62:65], v[150:153], v[186:189], v[62:65]
	v_mfma_f32_16x16x32_bf16 v[58:61], v[158:161], v[186:189], 0
	v_mfma_f32_16x16x32_bf16 v[58:61], v[154:157], v[182:185], v[58:61]
	v_mfma_f32_16x16x32_bf16 v[54:57], v[162:165], v[182:185], 0
	v_mfma_f32_16x16x32_bf16 v[54:57], v[166:169], v[186:189], v[54:57]
	v_mfma_f32_16x16x32_bf16 v[50:53], v[178:181], v[186:189], 0
	v_mfma_f32_16x16x32_bf16 v[50:53], v[170:173], v[182:185], v[50:53]
	v_mfma_f32_16x16x32_bf16 v[34:37], v[170:173], v[190:193], 0
	v_mfma_f32_16x16x32_bf16 v[34:37], v[178:181], v[204:207], v[34:37]
	v_mfma_f32_16x16x32_bf16 v[38:41], v[166:169], v[204:207], 0
	v_mfma_f32_16x16x32_bf16 v[38:41], v[162:165], v[190:193], v[38:41]
	v_mfma_f32_16x16x32_bf16 v[42:45], v[154:157], v[190:193], 0
	v_mfma_f32_16x16x32_bf16 v[42:45], v[158:161], v[204:207], v[42:45]
	v_mfma_f32_16x16x32_bf16 v[46:49], v[150:153], v[204:207], 0
	v_mfma_f32_16x16x32_bf16 v[46:49], v[146:149], v[190:193], v[46:49]
	v_mfma_f32_16x16x32_bf16 v[30:33], v[146:149], v[208:211], 0
	v_mfma_f32_16x16x32_bf16 v[30:33], v[150:153], v[212:215], v[30:33]
	v_mfma_f32_16x16x32_bf16 v[26:29], v[158:161], v[212:215], 0
	v_mfma_f32_16x16x32_bf16 v[26:29], v[154:157], v[208:211], v[26:29]
	v_mfma_f32_16x16x32_bf16 v[22:25], v[162:165], v[208:211], 0
	v_mfma_f32_16x16x32_bf16 v[22:25], v[166:169], v[212:215], v[22:25]
	v_mfma_f32_16x16x32_bf16 v[18:21], v[178:181], v[212:215], 0
	v_mfma_f32_16x16x32_bf16 v[18:21], v[170:173], v[208:211], v[18:21]
	v_mfma_f32_16x16x32_bf16 v[2:5], v[170:173], v[216:219], 0
	v_mfma_f32_16x16x32_bf16 v[2:5], v[178:181], v[220:223], v[2:5]
	v_mfma_f32_16x16x32_bf16 v[6:9], v[166:169], v[220:223], 0
	v_mfma_f32_16x16x32_bf16 v[6:9], v[162:165], v[216:219], v[6:9]
	v_mfma_f32_16x16x32_bf16 v[10:13], v[154:157], v[216:219], 0
	v_mfma_f32_16x16x32_bf16 v[10:13], v[158:161], v[220:223], v[10:13]
	v_mfma_f32_16x16x32_bf16 v[14:17], v[150:153], v[220:223], 0
	v_mfma_f32_16x16x32_bf16 v[14:17], v[146:149], v[216:219], v[14:17]
	s_setprio 0
	s_barrier
	s_add_i32 s0, 0, 0x18000
	s_add_i32 s1, 0, 0x1c000
	s_add_u32 s94, vcc_lo, 0x80000
	s_addc_u32 s95, vcc_hi, 0
	s_mov_b32 m0, s27
	s_nop 0
	global_load_lds_dwordx4 v132, s[94:95]
	s_mov_b32 m0, s29
	s_nop 0
	global_load_lds_dwordx4 v130, s[94:95]
	v_add_u32_e32 v158, s0, v176
	v_add_u32_e32 v178, s1, v176
	ds_read_b128 v[146:149], v158
	ds_read_b128 v[150:153], v158 offset:1024
	ds_read_b128 v[154:157], v158 offset:2048
	ds_read_b128 v[158:161], v158 offset:3072
	ds_read_b128 v[162:165], v178
	ds_read_b128 v[166:169], v178 offset:1024
	ds_read_b128 v[170:173], v178 offset:2048
	ds_read_b128 v[178:181], v178 offset:3072
	ds_read_b128 v[182:185], v177 offset:32768
	ds_read_b128 v[186:189], v177 offset:33792
	ds_read_b128 v[190:193], v177 offset:34816
	ds_read_b128 v[204:207], v177 offset:35840
	ds_read_b128 v[208:211], v177 offset:36864
	ds_read_b128 v[212:215], v177 offset:37888
	ds_read_b128 v[216:219], v177 offset:38912
	ds_read_b128 v[220:223], v177 offset:39936
	s_waitcnt vmcnt(8)
	s_waitcnt lgkmcnt(0)
	s_barrier
	s_setprio 1
	s_waitcnt lgkmcnt(0)
	v_mfma_f32_16x16x32_bf16 v[126:129], v[146:149], v[182:185], v[126:129]
	v_mfma_f32_16x16x32_bf16 v[126:129], v[150:153], v[186:189], v[126:129]
	v_mfma_f32_16x16x32_bf16 v[122:125], v[158:161], v[186:189], v[122:125]
	v_mfma_f32_16x16x32_bf16 v[122:125], v[154:157], v[182:185], v[122:125]
	v_mfma_f32_16x16x32_bf16 v[118:121], v[162:165], v[182:185], v[118:121]
	v_mfma_f32_16x16x32_bf16 v[118:121], v[166:169], v[186:189], v[118:121]
	v_mfma_f32_16x16x32_bf16 v[114:117], v[178:181], v[186:189], v[114:117]
	v_mfma_f32_16x16x32_bf16 v[114:117], v[170:173], v[182:185], v[114:117]
	v_mfma_f32_16x16x32_bf16 v[98:101], v[170:173], v[190:193], v[98:101]
	v_mfma_f32_16x16x32_bf16 v[98:101], v[178:181], v[204:207], v[98:101]
	v_mfma_f32_16x16x32_bf16 v[102:105], v[166:169], v[204:207], v[102:105]
	v_mfma_f32_16x16x32_bf16 v[102:105], v[162:165], v[190:193], v[102:105]
	v_mfma_f32_16x16x32_bf16 v[106:109], v[154:157], v[190:193], v[106:109]
	v_mfma_f32_16x16x32_bf16 v[106:109], v[158:161], v[204:207], v[106:109]
	v_mfma_f32_16x16x32_bf16 v[110:113], v[150:153], v[204:207], v[110:113]
	v_mfma_f32_16x16x32_bf16 v[110:113], v[146:149], v[190:193], v[110:113]
	v_mfma_f32_16x16x32_bf16 v[94:97], v[146:149], v[208:211], v[94:97]
	v_mfma_f32_16x16x32_bf16 v[94:97], v[150:153], v[212:215], v[94:97]
	v_mfma_f32_16x16x32_bf16 v[90:93], v[158:161], v[212:215], v[90:93]
	v_mfma_f32_16x16x32_bf16 v[90:93], v[154:157], v[208:211], v[90:93]
	v_mfma_f32_16x16x32_bf16 v[86:89], v[162:165], v[208:211], v[86:89]
	v_mfma_f32_16x16x32_bf16 v[86:89], v[166:169], v[212:215], v[86:89]
	v_mfma_f32_16x16x32_bf16 v[82:85], v[178:181], v[212:215], v[82:85]
	v_mfma_f32_16x16x32_bf16 v[82:85], v[170:173], v[208:211], v[82:85]
	v_mfma_f32_16x16x32_bf16 v[66:69], v[170:173], v[216:219], v[66:69]
	v_mfma_f32_16x16x32_bf16 v[66:69], v[178:181], v[220:223], v[66:69]
	v_mfma_f32_16x16x32_bf16 v[70:73], v[166:169], v[220:223], v[70:73]
	v_mfma_f32_16x16x32_bf16 v[70:73], v[162:165], v[216:219], v[70:73]
	v_mfma_f32_16x16x32_bf16 v[74:77], v[154:157], v[216:219], v[74:77]
	v_mfma_f32_16x16x32_bf16 v[74:77], v[158:161], v[220:223], v[74:77]
	v_mfma_f32_16x16x32_bf16 v[78:81], v[150:153], v[220:223], v[78:81]
	v_mfma_f32_16x16x32_bf16 v[78:81], v[146:149], v[216:219], v[78:81]
	s_setprio 0
	s_barrier
	s_add_u32 s98, s84, 0x80
	s_addc_u32 s99, s85, 0
	s_add_u32 s100, vcc_lo, 0x80
	s_addc_u32 s101, vcc_hi, 0
	s_add_i32 s0, s0, s20
	s_mov_b32 m0, s0
	s_nop 0
	global_load_lds_dwordx4 v132, s[98:99]
	s_add_i32 m0, s0, 0x2000
	s_add_u32 s84, s84, 0x80080
	s_addc_u32 s85, s85, 0
	s_add_i32 s0, s1, s20
	global_load_lds_dwordx4 v130, s[98:99]
	s_mov_b32 m0, s0
	s_nop 0
	global_load_lds_dwordx4 v132, s[84:85]
	s_add_i32 m0, s0, 0x2000
	s_nop 0
	global_load_lds_dwordx4 v130, s[84:85]
	s_mov_b32 m0, s40
	s_nop 0
	global_load_lds_dwordx4 v132, s[100:101]
	s_mov_b32 m0, s41
	s_nop 0
	global_load_lds_dwordx4 v130, s[100:101]
	ds_read_b128 v[182:185], v177 offset:49152
	ds_read_b128 v[186:189], v177 offset:50176
	ds_read_b128 v[190:193], v177 offset:51200
	ds_read_b128 v[204:207], v177 offset:52224
	ds_read_b128 v[208:211], v177 offset:53248
	ds_read_b128 v[212:215], v177 offset:54272
	ds_read_b128 v[216:219], v177 offset:55296
	ds_read_b128 v[220:223], v177 offset:56320
	s_waitcnt vmcnt(8)
	s_waitcnt lgkmcnt(0)
	s_barrier
	s_setprio 1
	s_waitcnt lgkmcnt(0)
	v_mfma_f32_16x16x32_bf16 v[62:65], v[146:149], v[182:185], v[62:65]
	v_mfma_f32_16x16x32_bf16 v[62:65], v[150:153], v[186:189], v[62:65]
	v_mfma_f32_16x16x32_bf16 v[58:61], v[158:161], v[186:189], v[58:61]
	v_mfma_f32_16x16x32_bf16 v[58:61], v[154:157], v[182:185], v[58:61]
	v_mfma_f32_16x16x32_bf16 v[54:57], v[162:165], v[182:185], v[54:57]
	v_mfma_f32_16x16x32_bf16 v[54:57], v[166:169], v[186:189], v[54:57]
	v_mfma_f32_16x16x32_bf16 v[50:53], v[178:181], v[186:189], v[50:53]
	v_mfma_f32_16x16x32_bf16 v[50:53], v[170:173], v[182:185], v[50:53]
	v_mfma_f32_16x16x32_bf16 v[34:37], v[170:173], v[190:193], v[34:37]
	v_mfma_f32_16x16x32_bf16 v[34:37], v[178:181], v[204:207], v[34:37]
	v_mfma_f32_16x16x32_bf16 v[38:41], v[166:169], v[204:207], v[38:41]
	v_mfma_f32_16x16x32_bf16 v[38:41], v[162:165], v[190:193], v[38:41]
	v_mfma_f32_16x16x32_bf16 v[42:45], v[154:157], v[190:193], v[42:45]
	v_mfma_f32_16x16x32_bf16 v[42:45], v[158:161], v[204:207], v[42:45]
	v_mfma_f32_16x16x32_bf16 v[46:49], v[150:153], v[204:207], v[46:49]
	v_mfma_f32_16x16x32_bf16 v[46:49], v[146:149], v[190:193], v[46:49]
	v_mfma_f32_16x16x32_bf16 v[30:33], v[146:149], v[208:211], v[30:33]
	v_mfma_f32_16x16x32_bf16 v[30:33], v[150:153], v[212:215], v[30:33]
	v_mfma_f32_16x16x32_bf16 v[26:29], v[158:161], v[212:215], v[26:29]
	v_mfma_f32_16x16x32_bf16 v[26:29], v[154:157], v[208:211], v[26:29]
	v_mfma_f32_16x16x32_bf16 v[22:25], v[162:165], v[208:211], v[22:25]
	v_mfma_f32_16x16x32_bf16 v[22:25], v[166:169], v[212:215], v[22:25]
	v_mfma_f32_16x16x32_bf16 v[18:21], v[178:181], v[212:215], v[18:21]
	v_mfma_f32_16x16x32_bf16 v[18:21], v[170:173], v[208:211], v[18:21]
	v_mfma_f32_16x16x32_bf16 v[2:5], v[170:173], v[216:219], v[2:5]
	v_mfma_f32_16x16x32_bf16 v[2:5], v[178:181], v[220:223], v[2:5]
	v_mfma_f32_16x16x32_bf16 v[6:9], v[166:169], v[220:223], v[6:9]
	v_mfma_f32_16x16x32_bf16 v[6:9], v[162:165], v[216:219], v[6:9]
	v_mfma_f32_16x16x32_bf16 v[10:13], v[154:157], v[216:219], v[10:13]
	v_mfma_f32_16x16x32_bf16 v[10:13], v[158:161], v[220:223], v[10:13]
	v_mfma_f32_16x16x32_bf16 v[14:17], v[150:153], v[220:223], v[14:17]
	v_mfma_f32_16x16x32_bf16 v[14:17], v[146:149], v[216:219], v[14:17]
	s_setprio 0
	s_barrier
	s_add_i32 s65, s65, 2
	s_add_u32 s76, s76, 0x100
	s_addc_u32 s77, s77, 0
	s_add_u32 s51, s51, 0x100
	s_addc_u32 s58, s58, 0
	s_cmp_gt_u32 s65, 29
	s_cbranch_scc1 .LBB0_264
	s_branch .LBB0_262

.LBB0_285:
	s_add_u32 s0, s76, 0xfff80080
	s_addc_u32 s1, s77, -1
	s_and_b64 s[70:71], s[70:71], exec
	s_cselect_b32 vcc_hi, s21, s1
	s_cselect_b32 vcc_lo, s22, s0
	s_cselect_b32 s71, s23, s41
	s_cselect_b32 s70, s39, s7
	s_add_i32 s0, 0, 0x10000
	s_add_i32 s1, 0, 0x14000
	s_add_i32 m0, s67, 0xc000
	s_nop 0
	global_load_lds_dwordx4 v170, s[76:77]
	s_add_i32 m0, s67, 0xe000
	s_nop 0
	global_load_lds_dwordx4 v172, s[76:77]
	v_add_u32_e32 v146, s0, v1
	v_add_u32_e32 v174, s1, v1
	ds_read_b128 v[134:137], v146
	ds_read_b128 v[138:141], v146 offset:1024
	ds_read_b128 v[142:145], v146 offset:2048
	ds_read_b128 v[146:149], v146 offset:3072
	ds_read_b128 v[150:153], v174
	ds_read_b128 v[154:157], v174 offset:1024
	ds_read_b128 v[158:161], v174 offset:2048
	ds_read_b128 v[174:177], v174 offset:3072
	ds_read_b128 v[178:181], v222
	ds_read_b128 v[182:185], v222 offset:1024
	ds_read_b128 v[186:189], v222 offset:2048
	ds_read_b128 v[190:193], v222 offset:3072
	ds_read_b128 v[204:207], v222 offset:4096
	ds_read_b128 v[208:211], v222 offset:5120
	ds_read_b128 v[212:215], v222 offset:6144
	ds_read_b128 v[216:219], v222 offset:7168
	s_waitcnt vmcnt(8)
	s_waitcnt lgkmcnt(0)
	s_barrier
	s_setprio 1
	s_waitcnt lgkmcnt(0)
	v_mfma_f32_16x16x32_bf16 v[126:129], v[134:137], v[178:181], v[126:129]
	v_mfma_f32_16x16x32_bf16 v[126:129], v[138:141], v[182:185], v[126:129]
	v_mfma_f32_16x16x32_bf16 v[122:125], v[146:149], v[182:185], v[122:125]
	v_mfma_f32_16x16x32_bf16 v[122:125], v[142:145], v[178:181], v[122:125]
	v_mfma_f32_16x16x32_bf16 v[118:121], v[150:153], v[178:181], v[118:121]
	v_mfma_f32_16x16x32_bf16 v[118:121], v[154:157], v[182:185], v[118:121]
	v_mfma_f32_16x16x32_bf16 v[114:117], v[174:177], v[182:185], v[114:117]
	v_mfma_f32_16x16x32_bf16 v[114:117], v[158:161], v[178:181], v[114:117]
	v_mfma_f32_16x16x32_bf16 v[98:101], v[158:161], v[186:189], v[98:101]
	v_mfma_f32_16x16x32_bf16 v[98:101], v[174:177], v[190:193], v[98:101]
	v_mfma_f32_16x16x32_bf16 v[102:105], v[154:157], v[190:193], v[102:105]
	v_mfma_f32_16x16x32_bf16 v[102:105], v[150:153], v[186:189], v[102:105]
	v_mfma_f32_16x16x32_bf16 v[106:109], v[142:145], v[186:189], v[106:109]
	v_mfma_f32_16x16x32_bf16 v[106:109], v[146:149], v[190:193], v[106:109]
	v_mfma_f32_16x16x32_bf16 v[110:113], v[138:141], v[190:193], v[110:113]
	v_mfma_f32_16x16x32_bf16 v[110:113], v[134:137], v[186:189], v[110:113]
	v_mfma_f32_16x16x32_bf16 v[94:97], v[134:137], v[204:207], v[94:97]
	v_mfma_f32_16x16x32_bf16 v[94:97], v[138:141], v[208:211], v[94:97]
	v_mfma_f32_16x16x32_bf16 v[90:93], v[146:149], v[208:211], v[90:93]
	v_mfma_f32_16x16x32_bf16 v[90:93], v[142:145], v[204:207], v[90:93]
	v_mfma_f32_16x16x32_bf16 v[86:89], v[150:153], v[204:207], v[86:89]
	v_mfma_f32_16x16x32_bf16 v[86:89], v[154:157], v[208:211], v[86:89]
	v_mfma_f32_16x16x32_bf16 v[82:85], v[174:177], v[208:211], v[82:85]
	v_mfma_f32_16x16x32_bf16 v[82:85], v[158:161], v[204:207], v[82:85]
	v_mfma_f32_16x16x32_bf16 v[66:69], v[158:161], v[212:215], v[66:69]
	v_mfma_f32_16x16x32_bf16 v[66:69], v[174:177], v[216:219], v[66:69]
	v_mfma_f32_16x16x32_bf16 v[70:73], v[154:157], v[216:219], v[70:73]
	v_mfma_f32_16x16x32_bf16 v[70:73], v[150:153], v[212:215], v[70:73]
	v_mfma_f32_16x16x32_bf16 v[74:77], v[142:145], v[212:215], v[74:77]
	v_mfma_f32_16x16x32_bf16 v[74:77], v[146:149], v[216:219], v[74:77]
	v_mfma_f32_16x16x32_bf16 v[78:81], v[138:141], v[216:219], v[78:81]
	v_mfma_f32_16x16x32_bf16 v[78:81], v[134:137], v[212:215], v[78:81]
	s_setprio 0
	s_barrier
	s_add_i32 s0, s0, s54
	s_mov_b32 m0, s0
	s_nop 0
	global_load_lds_dwordx4 v164, s[70:71]
	s_add_i32 m0, s0, 0x2000
	s_add_u32 s44, s70, 0x80000
	s_addc_u32 s45, s71, 0
	s_add_i32 s0, s1, s54
	global_load_lds_dwordx4 v162, s[70:71]
	s_mov_b32 m0, s0
	s_nop 0
	global_load_lds_dwordx4 v164, s[44:45]
	s_add_i32 m0, s0, 0x2000
	s_nop 0
	global_load_lds_dwordx4 v162, s[44:45]
	s_mov_b32 m0, s67
	s_nop 0
	global_load_lds_dwordx4 v164, vcc
	s_mov_b32 m0, s68
	s_nop 0
	global_load_lds_dwordx4 v162, vcc
	ds_read_b128 v[178:181], v222 offset:16384
	ds_read_b128 v[182:185], v222 offset:17408
	ds_read_b128 v[186:189], v222 offset:18432
	ds_read_b128 v[190:193], v222 offset:19456
	ds_read_b128 v[204:207], v222 offset:20480
	ds_read_b128 v[208:211], v222 offset:21504
	ds_read_b128 v[212:215], v222 offset:22528
	ds_read_b128 v[216:219], v222 offset:23552
	s_waitcnt vmcnt(8)
	s_waitcnt lgkmcnt(0)
	s_barrier
	s_setprio 1
	s_waitcnt lgkmcnt(0)
	v_mfma_f32_16x16x32_bf16 v[62:65], v[134:137], v[178:181], v[62:65]
	v_mfma_f32_16x16x32_bf16 v[62:65], v[138:141], v[182:185], v[62:65]
	v_mfma_f32_16x16x32_bf16 v[58:61], v[146:149], v[182:185], v[58:61]
	v_mfma_f32_16x16x32_bf16 v[58:61], v[142:145], v[178:181], v[58:61]
	v_mfma_f32_16x16x32_bf16 v[54:57], v[150:153], v[178:181], v[54:57]
	v_mfma_f32_16x16x32_bf16 v[54:57], v[154:157], v[182:185], v[54:57]
	v_mfma_f32_16x16x32_bf16 v[50:53], v[174:177], v[182:185], v[50:53]
	v_mfma_f32_16x16x32_bf16 v[50:53], v[158:161], v[178:181], v[50:53]
	v_mfma_f32_16x16x32_bf16 v[34:37], v[158:161], v[186:189], v[34:37]
	v_mfma_f32_16x16x32_bf16 v[34:37], v[174:177], v[190:193], v[34:37]
	v_mfma_f32_16x16x32_bf16 v[38:41], v[154:157], v[190:193], v[38:41]
	v_mfma_f32_16x16x32_bf16 v[38:41], v[150:153], v[186:189], v[38:41]
	v_mfma_f32_16x16x32_bf16 v[42:45], v[142:145], v[186:189], v[42:45]
	v_mfma_f32_16x16x32_bf16 v[42:45], v[146:149], v[190:193], v[42:45]
	v_mfma_f32_16x16x32_bf16 v[46:49], v[138:141], v[190:193], v[46:49]
	v_mfma_f32_16x16x32_bf16 v[46:49], v[134:137], v[186:189], v[46:49]
	v_mfma_f32_16x16x32_bf16 v[30:33], v[134:137], v[204:207], v[30:33]
	v_mfma_f32_16x16x32_bf16 v[30:33], v[138:141], v[208:211], v[30:33]
	v_mfma_f32_16x16x32_bf16 v[26:29], v[146:149], v[208:211], v[26:29]
	v_mfma_f32_16x16x32_bf16 v[26:29], v[142:145], v[204:207], v[26:29]
	v_mfma_f32_16x16x32_bf16 v[22:25], v[150:153], v[204:207], v[22:25]
	v_mfma_f32_16x16x32_bf16 v[22:25], v[154:157], v[208:211], v[22:25]
	v_mfma_f32_16x16x32_bf16 v[18:21], v[174:177], v[208:211], v[18:21]
	v_mfma_f32_16x16x32_bf16 v[18:21], v[158:161], v[204:207], v[18:21]
	v_mfma_f32_16x16x32_bf16 v[2:5], v[158:161], v[212:215], v[2:5]
	v_mfma_f32_16x16x32_bf16 v[2:5], v[174:177], v[216:219], v[2:5]
	v_mfma_f32_16x16x32_bf16 v[6:9], v[154:157], v[216:219], v[6:9]
	v_mfma_f32_16x16x32_bf16 v[6:9], v[150:153], v[212:215], v[6:9]
	v_mfma_f32_16x16x32_bf16 v[10:13], v[142:145], v[212:215], v[10:13]
	v_mfma_f32_16x16x32_bf16 v[10:13], v[146:149], v[216:219], v[10:13]
	v_mfma_f32_16x16x32_bf16 v[14:17], v[138:141], v[216:219], v[14:17]
	v_mfma_f32_16x16x32_bf16 v[14:17], v[134:137], v[212:215], v[14:17]
	s_setprio 0
	s_barrier
	s_add_i32 s0, 0, 0x18000
	s_add_i32 s1, 0, 0x1c000
	s_add_u32 s44, vcc_lo, 0x80000
	s_addc_u32 s45, vcc_hi, 0
	s_mov_b32 m0, s8
	s_nop 0
	global_load_lds_dwordx4 v164, s[44:45]
	s_mov_b32 m0, s9
	s_nop 0
	global_load_lds_dwordx4 v162, s[44:45]
	v_add_u32_e32 v146, s0, v1
	v_add_u32_e32 v174, s1, v1
	ds_read_b128 v[134:137], v146
	ds_read_b128 v[138:141], v146 offset:1024
	ds_read_b128 v[142:145], v146 offset:2048
	ds_read_b128 v[146:149], v146 offset:3072
	ds_read_b128 v[150:153], v174
	ds_read_b128 v[154:157], v174 offset:1024
	ds_read_b128 v[158:161], v174 offset:2048
	ds_read_b128 v[174:177], v174 offset:3072
	ds_read_b128 v[178:181], v222 offset:32768
	ds_read_b128 v[182:185], v222 offset:33792
	ds_read_b128 v[186:189], v222 offset:34816
	ds_read_b128 v[190:193], v222 offset:35840
	ds_read_b128 v[204:207], v222 offset:36864
	ds_read_b128 v[208:211], v222 offset:37888
	ds_read_b128 v[212:215], v222 offset:38912
	ds_read_b128 v[216:219], v222 offset:39936
	s_waitcnt vmcnt(8)
	s_waitcnt lgkmcnt(0)
	s_barrier
	s_setprio 1
	s_waitcnt lgkmcnt(0)
	v_mfma_f32_16x16x32_bf16 v[126:129], v[134:137], v[178:181], v[126:129]
	v_mfma_f32_16x16x32_bf16 v[126:129], v[138:141], v[182:185], v[126:129]
	v_mfma_f32_16x16x32_bf16 v[122:125], v[146:149], v[182:185], v[122:125]
	v_mfma_f32_16x16x32_bf16 v[122:125], v[142:145], v[178:181], v[122:125]
	v_mfma_f32_16x16x32_bf16 v[118:121], v[150:153], v[178:181], v[118:121]
	v_mfma_f32_16x16x32_bf16 v[118:121], v[154:157], v[182:185], v[118:121]
	v_mfma_f32_16x16x32_bf16 v[114:117], v[174:177], v[182:185], v[114:117]
	v_mfma_f32_16x16x32_bf16 v[114:117], v[158:161], v[178:181], v[114:117]
	v_mfma_f32_16x16x32_bf16 v[98:101], v[158:161], v[186:189], v[98:101]
	v_mfma_f32_16x16x32_bf16 v[98:101], v[174:177], v[190:193], v[98:101]
	v_mfma_f32_16x16x32_bf16 v[102:105], v[154:157], v[190:193], v[102:105]
	v_mfma_f32_16x16x32_bf16 v[102:105], v[150:153], v[186:189], v[102:105]
	v_mfma_f32_16x16x32_bf16 v[106:109], v[142:145], v[186:189], v[106:109]
	v_mfma_f32_16x16x32_bf16 v[106:109], v[146:149], v[190:193], v[106:109]
	v_mfma_f32_16x16x32_bf16 v[110:113], v[138:141], v[190:193], v[110:113]
	v_mfma_f32_16x16x32_bf16 v[110:113], v[134:137], v[186:189], v[110:113]
	v_mfma_f32_16x16x32_bf16 v[94:97], v[134:137], v[204:207], v[94:97]
	v_mfma_f32_16x16x32_bf16 v[94:97], v[138:141], v[208:211], v[94:97]
	v_mfma_f32_16x16x32_bf16 v[90:93], v[146:149], v[208:211], v[90:93]
	v_mfma_f32_16x16x32_bf16 v[90:93], v[142:145], v[204:207], v[90:93]
	v_mfma_f32_16x16x32_bf16 v[86:89], v[150:153], v[204:207], v[86:89]
	v_mfma_f32_16x16x32_bf16 v[86:89], v[154:157], v[208:211], v[86:89]
	v_mfma_f32_16x16x32_bf16 v[82:85], v[174:177], v[208:211], v[82:85]
	v_mfma_f32_16x16x32_bf16 v[82:85], v[158:161], v[204:207], v[82:85]
	v_mfma_f32_16x16x32_bf16 v[66:69], v[158:161], v[212:215], v[66:69]
	v_mfma_f32_16x16x32_bf16 v[66:69], v[174:177], v[216:219], v[66:69]
	v_mfma_f32_16x16x32_bf16 v[70:73], v[154:157], v[216:219], v[70:73]
	v_mfma_f32_16x16x32_bf16 v[70:73], v[150:153], v[212:215], v[70:73]
	v_mfma_f32_16x16x32_bf16 v[74:77], v[142:145], v[212:215], v[74:77]
	v_mfma_f32_16x16x32_bf16 v[74:77], v[146:149], v[216:219], v[74:77]
	v_mfma_f32_16x16x32_bf16 v[78:81], v[138:141], v[216:219], v[78:81]
	v_mfma_f32_16x16x32_bf16 v[78:81], v[134:137], v[212:215], v[78:81]
	s_setprio 0
	s_barrier
	s_add_u32 s98, s70, 0x80
	s_addc_u32 s99, s71, 0
	s_add_u32 s100, vcc_lo, 0x80
	s_addc_u32 s101, vcc_hi, 0
	s_add_i32 s0, s0, s54
	s_mov_b32 m0, s0
	s_nop 0
	global_load_lds_dwordx4 v164, s[98:99]
	s_add_i32 m0, s0, 0x2000
	s_add_u32 s44, s70, 0x80080
	s_addc_u32 s45, s71, 0
	s_add_i32 s0, s1, s54
	global_load_lds_dwordx4 v162, s[98:99]
	s_mov_b32 m0, s0
	s_nop 0
	global_load_lds_dwordx4 v164, s[44:45]
	s_add_i32 m0, s0, 0x2000
	s_nop 0
	global_load_lds_dwordx4 v162, s[44:45]
	s_mov_b32 m0, s27
	s_nop 0
	global_load_lds_dwordx4 v164, s[100:101]
	s_mov_b32 m0, s26
	s_nop 0
	global_load_lds_dwordx4 v162, s[100:101]
	ds_read_b128 v[178:181], v222 offset:49152
	ds_read_b128 v[182:185], v222 offset:50176
	ds_read_b128 v[186:189], v222 offset:51200
	ds_read_b128 v[190:193], v222 offset:52224
	ds_read_b128 v[204:207], v222 offset:53248
	ds_read_b128 v[208:211], v222 offset:54272
	ds_read_b128 v[212:215], v222 offset:55296
	ds_read_b128 v[216:219], v222 offset:56320
	s_waitcnt vmcnt(8)
	s_waitcnt lgkmcnt(0)
	s_barrier
	s_setprio 1
	s_waitcnt lgkmcnt(0)
	v_mfma_f32_16x16x32_bf16 v[62:65], v[134:137], v[178:181], v[62:65]
	v_mfma_f32_16x16x32_bf16 v[62:65], v[138:141], v[182:185], v[62:65]
	v_mfma_f32_16x16x32_bf16 v[58:61], v[146:149], v[182:185], v[58:61]
	v_mfma_f32_16x16x32_bf16 v[58:61], v[142:145], v[178:181], v[58:61]
	v_mfma_f32_16x16x32_bf16 v[54:57], v[150:153], v[178:181], v[54:57]
	v_mfma_f32_16x16x32_bf16 v[54:57], v[154:157], v[182:185], v[54:57]
	v_mfma_f32_16x16x32_bf16 v[50:53], v[174:177], v[182:185], v[50:53]
	v_mfma_f32_16x16x32_bf16 v[50:53], v[158:161], v[178:181], v[50:53]
	v_mfma_f32_16x16x32_bf16 v[34:37], v[158:161], v[186:189], v[34:37]
	v_mfma_f32_16x16x32_bf16 v[34:37], v[174:177], v[190:193], v[34:37]
	v_mfma_f32_16x16x32_bf16 v[38:41], v[154:157], v[190:193], v[38:41]
	v_mfma_f32_16x16x32_bf16 v[38:41], v[150:153], v[186:189], v[38:41]
	v_mfma_f32_16x16x32_bf16 v[42:45], v[142:145], v[186:189], v[42:45]
	v_mfma_f32_16x16x32_bf16 v[42:45], v[146:149], v[190:193], v[42:45]
	v_mfma_f32_16x16x32_bf16 v[46:49], v[138:141], v[190:193], v[46:49]
	v_mfma_f32_16x16x32_bf16 v[46:49], v[134:137], v[186:189], v[46:49]
	v_mfma_f32_16x16x32_bf16 v[30:33], v[134:137], v[204:207], v[30:33]
	v_mfma_f32_16x16x32_bf16 v[30:33], v[138:141], v[208:211], v[30:33]
	v_mfma_f32_16x16x32_bf16 v[26:29], v[146:149], v[208:211], v[26:29]
	v_mfma_f32_16x16x32_bf16 v[26:29], v[142:145], v[204:207], v[26:29]
	v_mfma_f32_16x16x32_bf16 v[22:25], v[150:153], v[204:207], v[22:25]
	v_mfma_f32_16x16x32_bf16 v[22:25], v[154:157], v[208:211], v[22:25]
	v_mfma_f32_16x16x32_bf16 v[18:21], v[174:177], v[208:211], v[18:21]
	v_mfma_f32_16x16x32_bf16 v[18:21], v[158:161], v[204:207], v[18:21]
	v_mfma_f32_16x16x32_bf16 v[2:5], v[158:161], v[212:215], v[2:5]
	v_mfma_f32_16x16x32_bf16 v[2:5], v[174:177], v[216:219], v[2:5]
	v_mfma_f32_16x16x32_bf16 v[6:9], v[154:157], v[216:219], v[6:9]
	v_mfma_f32_16x16x32_bf16 v[6:9], v[150:153], v[212:215], v[6:9]
	v_mfma_f32_16x16x32_bf16 v[10:13], v[142:145], v[212:215], v[10:13]
	v_mfma_f32_16x16x32_bf16 v[10:13], v[146:149], v[216:219], v[10:13]
	v_mfma_f32_16x16x32_bf16 v[14:17], v[138:141], v[216:219], v[14:17]
	v_mfma_f32_16x16x32_bf16 v[14:17], v[134:137], v[212:215], v[14:17]
	s_setprio 0
	s_barrier
	s_add_i32 s43, s43, 2
	s_add_u32 s76, s76, 0x100
	s_addc_u32 s77, s77, 0
	s_add_u32 s7, s7, 0x100
	s_addc_u32 s41, s41, 0
	s_cmp_gt_u32 s43, 29
	s_cbranch_scc1 .LBB0_288

.Lpeel_disp_ino:
	s_cmp_lg_u32 s43, -2
	s_cbranch_scc1 .LBB0_285
	s_add_u32 s0, s76, 0xfff80080
	s_addc_u32 s1, s77, -1
	s_and_b64 s[70:71], s[70:71], exec
	s_cselect_b32 vcc_hi, s21, s1
	s_cselect_b32 vcc_lo, s22, s0
	s_cselect_b32 s71, s23, s41
	s_cselect_b32 s70, s39, s7
	s_add_i32 s0, 0, 0x10000
	s_add_i32 s1, 0, 0x14000
	s_add_i32 m0, s67, 0xc000
	s_nop 0
	global_load_lds_dwordx4 v170, s[76:77]
	s_add_i32 m0, s67, 0xe000
	s_nop 0
	global_load_lds_dwordx4 v172, s[76:77]
	v_add_u32_e32 v146, s0, v1
	v_add_u32_e32 v174, s1, v1
	ds_read_b128 v[134:137], v146
	ds_read_b128 v[138:141], v146 offset:1024
	ds_read_b128 v[142:145], v146 offset:2048
	ds_read_b128 v[146:149], v146 offset:3072
	ds_read_b128 v[150:153], v174
	ds_read_b128 v[154:157], v174 offset:1024
	ds_read_b128 v[158:161], v174 offset:2048
	ds_read_b128 v[174:177], v174 offset:3072
	ds_read_b128 v[178:181], v222
	ds_read_b128 v[182:185], v222 offset:1024
	ds_read_b128 v[186:189], v222 offset:2048
	ds_read_b128 v[190:193], v222 offset:3072
	ds_read_b128 v[204:207], v222 offset:4096
	ds_read_b128 v[208:211], v222 offset:5120
	ds_read_b128 v[212:215], v222 offset:6144
	ds_read_b128 v[216:219], v222 offset:7168
	s_waitcnt vmcnt(8)
	s_waitcnt lgkmcnt(0)
	s_barrier
	s_setprio 1
	s_waitcnt lgkmcnt(0)
	v_mfma_f32_16x16x32_bf16 v[126:129], v[134:137], v[178:181], 0
	v_mfma_f32_16x16x32_bf16 v[126:129], v[138:141], v[182:185], v[126:129]
	v_mfma_f32_16x16x32_bf16 v[122:125], v[146:149], v[182:185], 0
	v_mfma_f32_16x16x32_bf16 v[122:125], v[142:145], v[178:181], v[122:125]
	v_mfma_f32_16x16x32_bf16 v[118:121], v[150:153], v[178:181], 0
	v_mfma_f32_16x16x32_bf16 v[118:121], v[154:157], v[182:185], v[118:121]
	v_mfma_f32_16x16x32_bf16 v[114:117], v[174:177], v[182:185], 0
	v_mfma_f32_16x16x32_bf16 v[114:117], v[158:161], v[178:181], v[114:117]
	v_mfma_f32_16x16x32_bf16 v[98:101], v[158:161], v[186:189], 0
	v_mfma_f32_16x16x32_bf16 v[98:101], v[174:177], v[190:193], v[98:101]
	v_mfma_f32_16x16x32_bf16 v[102:105], v[154:157], v[190:193], 0
	v_mfma_f32_16x16x32_bf16 v[102:105], v[150:153], v[186:189], v[102:105]
	v_mfma_f32_16x16x32_bf16 v[106:109], v[142:145], v[186:189], 0
	v_mfma_f32_16x16x32_bf16 v[106:109], v[146:149], v[190:193], v[106:109]
	v_mfma_f32_16x16x32_bf16 v[110:113], v[138:141], v[190:193], 0
	v_mfma_f32_16x16x32_bf16 v[110:113], v[134:137], v[186:189], v[110:113]
	v_mfma_f32_16x16x32_bf16 v[94:97], v[134:137], v[204:207], 0
	v_mfma_f32_16x16x32_bf16 v[94:97], v[138:141], v[208:211], v[94:97]
	v_mfma_f32_16x16x32_bf16 v[90:93], v[146:149], v[208:211], 0
	v_mfma_f32_16x16x32_bf16 v[90:93], v[142:145], v[204:207], v[90:93]
	v_mfma_f32_16x16x32_bf16 v[86:89], v[150:153], v[204:207], 0
	v_mfma_f32_16x16x32_bf16 v[86:89], v[154:157], v[208:211], v[86:89]
	v_mfma_f32_16x16x32_bf16 v[82:85], v[174:177], v[208:211], 0
	v_mfma_f32_16x16x32_bf16 v[82:85], v[158:161], v[204:207], v[82:85]
	v_mfma_f32_16x16x32_bf16 v[66:69], v[158:161], v[212:215], 0
	v_mfma_f32_16x16x32_bf16 v[66:69], v[174:177], v[216:219], v[66:69]
	v_mfma_f32_16x16x32_bf16 v[70:73], v[154:157], v[216:219], 0
	v_mfma_f32_16x16x32_bf16 v[70:73], v[150:153], v[212:215], v[70:73]
	v_mfma_f32_16x16x32_bf16 v[74:77], v[142:145], v[212:215], 0
	v_mfma_f32_16x16x32_bf16 v[74:77], v[146:149], v[216:219], v[74:77]
	v_mfma_f32_16x16x32_bf16 v[78:81], v[138:141], v[216:219], 0
	v_mfma_f32_16x16x32_bf16 v[78:81], v[134:137], v[212:215], v[78:81]
	s_setprio 0
	s_barrier
	s_add_i32 s0, s0, s54
	s_mov_b32 m0, s0
	s_nop 0
	global_load_lds_dwordx4 v164, s[70:71]
	s_add_i32 m0, s0, 0x2000
	s_add_u32 s44, s70, 0x80000
	s_addc_u32 s45, s71, 0
	s_add_i32 s0, s1, s54
	global_load_lds_dwordx4 v162, s[70:71]
	s_mov_b32 m0, s0
	s_nop 0
	global_load_lds_dwordx4 v164, s[44:45]
	s_add_i32 m0, s0, 0x2000
	s_nop 0
	global_load_lds_dwordx4 v162, s[44:45]
	s_mov_b32 m0, s67
	s_nop 0
	global_load_lds_dwordx4 v164, vcc
	s_mov_b32 m0, s68
	s_nop 0
	global_load_lds_dwordx4 v162, vcc
	ds_read_b128 v[178:181], v222 offset:16384
	ds_read_b128 v[182:185], v222 offset:17408
	ds_read_b128 v[186:189], v222 offset:18432
	ds_read_b128 v[190:193], v222 offset:19456
	ds_read_b128 v[204:207], v222 offset:20480
	ds_read_b128 v[208:211], v222 offset:21504
	ds_read_b128 v[212:215], v222 offset:22528
	ds_read_b128 v[216:219], v222 offset:23552
	s_waitcnt vmcnt(8)
	s_waitcnt lgkmcnt(0)
	s_barrier
	s_setprio 1
	s_waitcnt lgkmcnt(0)
	v_mfma_f32_16x16x32_bf16 v[62:65], v[134:137], v[178:181], 0
	v_mfma_f32_16x16x32_bf16 v[62:65], v[138:141], v[182:185], v[62:65]
	v_mfma_f32_16x16x32_bf16 v[58:61], v[146:149], v[182:185], 0
	v_mfma_f32_16x16x32_bf16 v[58:61], v[142:145], v[178:181], v[58:61]
	v_mfma_f32_16x16x32_bf16 v[54:57], v[150:153], v[178:181], 0
	v_mfma_f32_16x16x32_bf16 v[54:57], v[154:157], v[182:185], v[54:57]
	v_mfma_f32_16x16x32_bf16 v[50:53], v[174:177], v[182:185], 0
	v_mfma_f32_16x16x32_bf16 v[50:53], v[158:161], v[178:181], v[50:53]
	v_mfma_f32_16x16x32_bf16 v[34:37], v[158:161], v[186:189], 0
	v_mfma_f32_16x16x32_bf16 v[34:37], v[174:177], v[190:193], v[34:37]
	v_mfma_f32_16x16x32_bf16 v[38:41], v[154:157], v[190:193], 0
	v_mfma_f32_16x16x32_bf16 v[38:41], v[150:153], v[186:189], v[38:41]
	v_mfma_f32_16x16x32_bf16 v[42:45], v[142:145], v[186:189], 0
	v_mfma_f32_16x16x32_bf16 v[42:45], v[146:149], v[190:193], v[42:45]
	v_mfma_f32_16x16x32_bf16 v[46:49], v[138:141], v[190:193], 0
	v_mfma_f32_16x16x32_bf16 v[46:49], v[134:137], v[186:189], v[46:49]
	v_mfma_f32_16x16x32_bf16 v[30:33], v[134:137], v[204:207], 0
	v_mfma_f32_16x16x32_bf16 v[30:33], v[138:141], v[208:211], v[30:33]
	v_mfma_f32_16x16x32_bf16 v[26:29], v[146:149], v[208:211], 0
	v_mfma_f32_16x16x32_bf16 v[26:29], v[142:145], v[204:207], v[26:29]
	v_mfma_f32_16x16x32_bf16 v[22:25], v[150:153], v[204:207], 0
	v_mfma_f32_16x16x32_bf16 v[22:25], v[154:157], v[208:211], v[22:25]
	v_mfma_f32_16x16x32_bf16 v[18:21], v[174:177], v[208:211], 0
	v_mfma_f32_16x16x32_bf16 v[18:21], v[158:161], v[204:207], v[18:21]
	v_mfma_f32_16x16x32_bf16 v[2:5], v[158:161], v[212:215], 0
	v_mfma_f32_16x16x32_bf16 v[2:5], v[174:177], v[216:219], v[2:5]
	v_mfma_f32_16x16x32_bf16 v[6:9], v[154:157], v[216:219], 0
	v_mfma_f32_16x16x32_bf16 v[6:9], v[150:153], v[212:215], v[6:9]
	v_mfma_f32_16x16x32_bf16 v[10:13], v[142:145], v[212:215], 0
	v_mfma_f32_16x16x32_bf16 v[10:13], v[146:149], v[216:219], v[10:13]
	v_mfma_f32_16x16x32_bf16 v[14:17], v[138:141], v[216:219], 0
	v_mfma_f32_16x16x32_bf16 v[14:17], v[134:137], v[212:215], v[14:17]
	s_setprio 0
	s_barrier
	s_add_i32 s0, 0, 0x18000
	s_add_i32 s1, 0, 0x1c000
	s_add_u32 s44, vcc_lo, 0x80000
	s_addc_u32 s45, vcc_hi, 0
	s_mov_b32 m0, s8
	s_nop 0
	global_load_lds_dwordx4 v164, s[44:45]
	s_mov_b32 m0, s9
	s_nop 0
	global_load_lds_dwordx4 v162, s[44:45]
	v_add_u32_e32 v146, s0, v1
	v_add_u32_e32 v174, s1, v1
	ds_read_b128 v[134:137], v146
	ds_read_b128 v[138:141], v146 offset:1024
	ds_read_b128 v[142:145], v146 offset:2048
	ds_read_b128 v[146:149], v146 offset:3072
	ds_read_b128 v[150:153], v174
	ds_read_b128 v[154:157], v174 offset:1024
	ds_read_b128 v[158:161], v174 offset:2048
	ds_read_b128 v[174:177], v174 offset:3072
	ds_read_b128 v[178:181], v222 offset:32768
	ds_read_b128 v[182:185], v222 offset:33792
	ds_read_b128 v[186:189], v222 offset:34816
	ds_read_b128 v[190:193], v222 offset:35840
	ds_read_b128 v[204:207], v222 offset:36864
	ds_read_b128 v[208:211], v222 offset:37888
	ds_read_b128 v[212:215], v222 offset:38912
	ds_read_b128 v[216:219], v222 offset:39936
	s_waitcnt vmcnt(8)
	s_waitcnt lgkmcnt(0)
	s_barrier
	s_setprio 1
	s_waitcnt lgkmcnt(0)
	v_mfma_f32_16x16x32_bf16 v[126:129], v[134:137], v[178:181], v[126:129]
	v_mfma_f32_16x16x32_bf16 v[126:129], v[138:141], v[182:185], v[126:129]
	v_mfma_f32_16x16x32_bf16 v[122:125], v[146:149], v[182:185], v[122:125]
	v_mfma_f32_16x16x32_bf16 v[122:125], v[142:145], v[178:181], v[122:125]
	v_mfma_f32_16x16x32_bf16 v[118:121], v[150:153], v[178:181], v[118:121]
	v_mfma_f32_16x16x32_bf16 v[118:121], v[154:157], v[182:185], v[118:121]
	v_mfma_f32_16x16x32_bf16 v[114:117], v[174:177], v[182:185], v[114:117]
	v_mfma_f32_16x16x32_bf16 v[114:117], v[158:161], v[178:181], v[114:117]
	v_mfma_f32_16x16x32_bf16 v[98:101], v[158:161], v[186:189], v[98:101]
	v_mfma_f32_16x16x32_bf16 v[98:101], v[174:177], v[190:193], v[98:101]
	v_mfma_f32_16x16x32_bf16 v[102:105], v[154:157], v[190:193], v[102:105]
	v_mfma_f32_16x16x32_bf16 v[102:105], v[150:153], v[186:189], v[102:105]
	v_mfma_f32_16x16x32_bf16 v[106:109], v[142:145], v[186:189], v[106:109]
	v_mfma_f32_16x16x32_bf16 v[106:109], v[146:149], v[190:193], v[106:109]
	v_mfma_f32_16x16x32_bf16 v[110:113], v[138:141], v[190:193], v[110:113]
	v_mfma_f32_16x16x32_bf16 v[110:113], v[134:137], v[186:189], v[110:113]
	v_mfma_f32_16x16x32_bf16 v[94:97], v[134:137], v[204:207], v[94:97]
	v_mfma_f32_16x16x32_bf16 v[94:97], v[138:141], v[208:211], v[94:97]
	v_mfma_f32_16x16x32_bf16 v[90:93], v[146:149], v[208:211], v[90:93]
	v_mfma_f32_16x16x32_bf16 v[90:93], v[142:145], v[204:207], v[90:93]
	v_mfma_f32_16x16x32_bf16 v[86:89], v[150:153], v[204:207], v[86:89]
	v_mfma_f32_16x16x32_bf16 v[86:89], v[154:157], v[208:211], v[86:89]
	v_mfma_f32_16x16x32_bf16 v[82:85], v[174:177], v[208:211], v[82:85]
	v_mfma_f32_16x16x32_bf16 v[82:85], v[158:161], v[204:207], v[82:85]
	v_mfma_f32_16x16x32_bf16 v[66:69], v[158:161], v[212:215], v[66:69]
	v_mfma_f32_16x16x32_bf16 v[66:69], v[174:177], v[216:219], v[66:69]
	v_mfma_f32_16x16x32_bf16 v[70:73], v[154:157], v[216:219], v[70:73]
	v_mfma_f32_16x16x32_bf16 v[70:73], v[150:153], v[212:215], v[70:73]
	v_mfma_f32_16x16x32_bf16 v[74:77], v[142:145], v[212:215], v[74:77]
	v_mfma_f32_16x16x32_bf16 v[74:77], v[146:149], v[216:219], v[74:77]
	v_mfma_f32_16x16x32_bf16 v[78:81], v[138:141], v[216:219], v[78:81]
	v_mfma_f32_16x16x32_bf16 v[78:81], v[134:137], v[212:215], v[78:81]
	s_setprio 0
	s_barrier
	s_add_u32 s98, s70, 0x80
	s_addc_u32 s99, s71, 0
	s_add_u32 s100, vcc_lo, 0x80
	s_addc_u32 s101, vcc_hi, 0
	s_add_i32 s0, s0, s54
	s_mov_b32 m0, s0
	s_nop 0
	global_load_lds_dwordx4 v164, s[98:99]
	s_add_i32 m0, s0, 0x2000
	s_add_u32 s44, s70, 0x80080
	s_addc_u32 s45, s71, 0
	s_add_i32 s0, s1, s54
	global_load_lds_dwordx4 v162, s[98:99]
	s_mov_b32 m0, s0
	s_nop 0
	global_load_lds_dwordx4 v164, s[44:45]
	s_add_i32 m0, s0, 0x2000
	s_nop 0
	global_load_lds_dwordx4 v162, s[44:45]
	s_mov_b32 m0, s27
	s_nop 0
	global_load_lds_dwordx4 v164, s[100:101]
	s_mov_b32 m0, s26
	s_nop 0
	global_load_lds_dwordx4 v162, s[100:101]
	ds_read_b128 v[178:181], v222 offset:49152
	ds_read_b128 v[182:185], v222 offset:50176
	ds_read_b128 v[186:189], v222 offset:51200
	ds_read_b128 v[190:193], v222 offset:52224
	ds_read_b128 v[204:207], v222 offset:53248
	ds_read_b128 v[208:211], v222 offset:54272
	ds_read_b128 v[212:215], v222 offset:55296
	ds_read_b128 v[216:219], v222 offset:56320
	s_waitcnt vmcnt(8)
	s_waitcnt lgkmcnt(0)
	s_barrier
	s_setprio 1
	s_waitcnt lgkmcnt(0)
	v_mfma_f32_16x16x32_bf16 v[62:65], v[134:137], v[178:181], v[62:65]
	v_mfma_f32_16x16x32_bf16 v[62:65], v[138:141], v[182:185], v[62:65]
	v_mfma_f32_16x16x32_bf16 v[58:61], v[146:149], v[182:185], v[58:61]
	v_mfma_f32_16x16x32_bf16 v[58:61], v[142:145], v[178:181], v[58:61]
	v_mfma_f32_16x16x32_bf16 v[54:57], v[150:153], v[178:181], v[54:57]
	v_mfma_f32_16x16x32_bf16 v[54:57], v[154:157], v[182:185], v[54:57]
	v_mfma_f32_16x16x32_bf16 v[50:53], v[174:177], v[182:185], v[50:53]
	v_mfma_f32_16x16x32_bf16 v[50:53], v[158:161], v[178:181], v[50:53]
	v_mfma_f32_16x16x32_bf16 v[34:37], v[158:161], v[186:189], v[34:37]
	v_mfma_f32_16x16x32_bf16 v[34:37], v[174:177], v[190:193], v[34:37]
	v_mfma_f32_16x16x32_bf16 v[38:41], v[154:157], v[190:193], v[38:41]
	v_mfma_f32_16x16x32_bf16 v[38:41], v[150:153], v[186:189], v[38:41]
	v_mfma_f32_16x16x32_bf16 v[42:45], v[142:145], v[186:189], v[42:45]
	v_mfma_f32_16x16x32_bf16 v[42:45], v[146:149], v[190:193], v[42:45]
	v_mfma_f32_16x16x32_bf16 v[46:49], v[138:141], v[190:193], v[46:49]
	v_mfma_f32_16x16x32_bf16 v[46:49], v[134:137], v[186:189], v[46:49]
	v_mfma_f32_16x16x32_bf16 v[30:33], v[134:137], v[204:207], v[30:33]
	v_mfma_f32_16x16x32_bf16 v[30:33], v[138:141], v[208:211], v[30:33]
	v_mfma_f32_16x16x32_bf16 v[26:29], v[146:149], v[208:211], v[26:29]
	v_mfma_f32_16x16x32_bf16 v[26:29], v[142:145], v[204:207], v[26:29]
	v_mfma_f32_16x16x32_bf16 v[22:25], v[150:153], v[204:207], v[22:25]
	v_mfma_f32_16x16x32_bf16 v[22:25], v[154:157], v[208:211], v[22:25]
	v_mfma_f32_16x16x32_bf16 v[18:21], v[174:177], v[208:211], v[18:21]
	v_mfma_f32_16x16x32_bf16 v[18:21], v[158:161], v[204:207], v[18:21]
	v_mfma_f32_16x16x32_bf16 v[2:5], v[158:161], v[212:215], v[2:5]
	v_mfma_f32_16x16x32_bf16 v[2:5], v[174:177], v[216:219], v[2:5]
	v_mfma_f32_16x16x32_bf16 v[6:9], v[154:157], v[216:219], v[6:9]
	v_mfma_f32_16x16x32_bf16 v[6:9], v[150:153], v[212:215], v[6:9]
	v_mfma_f32_16x16x32_bf16 v[10:13], v[142:145], v[212:215], v[10:13]
	v_mfma_f32_16x16x32_bf16 v[10:13], v[146:149], v[216:219], v[10:13]
	v_mfma_f32_16x16x32_bf16 v[14:17], v[138:141], v[216:219], v[14:17]
	v_mfma_f32_16x16x32_bf16 v[14:17], v[134:137], v[212:215], v[14:17]
	s_setprio 0
	s_barrier
	s_add_i32 s43, s43, 2
	s_add_u32 s76, s76, 0x100
	s_addc_u32 s77, s77, 0
	s_add_u32 s7, s7, 0x100
	s_addc_u32 s41, s41, 0
	s_cmp_gt_u32 s43, 29
	s_cbranch_scc1 .LBB0_288
	s_branch .LBB0_286

.LBB0_509:
	s_add_u32 s90, s76, 0x100
	s_addc_u32 s91, s77, 0
	s_and_b64 s[0:1], s[70:71], exec
	s_cselect_b32 vcc_hi, s22, s91
	s_cselect_b32 vcc_lo, s23, s90
	s_cselect_b32 s71, s41, s53
	s_cselect_b32 s70, s44, s51
	s_add_i32 s0, 0, 0x10000
	s_add_i32 s18, 0, 0x14000
	s_add_i32 m0, s29, 0xc000
	s_nop 0
	global_load_lds_dwordx4 v210, s[76:77]
	s_add_i32 m0, s29, 0xe000
	s_nop 0
	global_load_lds_dwordx4 v212, s[76:77]
	v_add_u32_e32 v114, s0, v1
	v_add_u32_e32 v154, s18, v1
	ds_read_b128 v[78:81], v114
	ds_read_b128 v[90:93], v114 offset:1024
	ds_read_b128 v[102:105], v114 offset:2048
	ds_read_b128 v[114:117], v114 offset:3072
	ds_read_b128 v[126:129], v154
	ds_read_b128 v[134:137], v154 offset:1024
	ds_read_b128 v[142:145], v154 offset:2048
	ds_read_b128 v[154:157], v154 offset:3072
	ds_read_b128 v[158:161], v237
	ds_read_b128 v[162:165], v237 offset:1024
	ds_read_b128 v[166:169], v237 offset:2048
	ds_read_b128 v[178:181], v237 offset:3072
	ds_read_b128 v[182:185], v237 offset:4096
	ds_read_b128 v[186:189], v237 offset:5120
	ds_read_b128 v[190:193], v237 offset:6144
	ds_read_b128 v[214:217], v237 offset:7168
	s_waitcnt vmcnt(8)
	s_waitcnt lgkmcnt(0)
	s_barrier
	s_setprio 1
	s_waitcnt lgkmcnt(0)
	v_mfma_f32_16x16x32_bf16 v[174:177], v[78:81], v[158:161], v[174:177]
	v_mfma_f32_16x16x32_bf16 v[174:177], v[90:93], v[162:165], v[174:177]
	v_mfma_f32_16x16x32_bf16 v[170:173], v[114:117], v[162:165], v[170:173]
	v_mfma_f32_16x16x32_bf16 v[170:173], v[102:105], v[158:161], v[170:173]
	v_mfma_f32_16x16x32_bf16 v[150:153], v[126:129], v[158:161], v[150:153]
	v_mfma_f32_16x16x32_bf16 v[150:153], v[134:137], v[162:165], v[150:153]
	v_mfma_f32_16x16x32_bf16 v[146:149], v[154:157], v[162:165], v[146:149]
	v_mfma_f32_16x16x32_bf16 v[146:149], v[142:145], v[158:161], v[146:149]
	v_mfma_f32_16x16x32_bf16 v[118:121], v[142:145], v[166:169], v[118:121]
	v_mfma_f32_16x16x32_bf16 v[118:121], v[154:157], v[178:181], v[118:121]
	v_mfma_f32_16x16x32_bf16 v[122:125], v[134:137], v[178:181], v[122:125]
	v_mfma_f32_16x16x32_bf16 v[122:125], v[126:129], v[166:169], v[122:125]
	v_mfma_f32_16x16x32_bf16 v[130:133], v[102:105], v[166:169], v[130:133]
	v_mfma_f32_16x16x32_bf16 v[130:133], v[114:117], v[178:181], v[130:133]
	v_mfma_f32_16x16x32_bf16 v[138:141], v[90:93], v[178:181], v[138:141]
	v_mfma_f32_16x16x32_bf16 v[138:141], v[78:81], v[166:169], v[138:141]
	v_mfma_f32_16x16x32_bf16 v[110:113], v[78:81], v[182:185], v[110:113]
	v_mfma_f32_16x16x32_bf16 v[110:113], v[90:93], v[186:189], v[110:113]
	v_mfma_f32_16x16x32_bf16 v[106:109], v[114:117], v[186:189], v[106:109]
	v_mfma_f32_16x16x32_bf16 v[106:109], v[102:105], v[182:185], v[106:109]
	v_mfma_f32_16x16x32_bf16 v[98:101], v[126:129], v[182:185], v[98:101]
	v_mfma_f32_16x16x32_bf16 v[98:101], v[134:137], v[186:189], v[98:101]
	v_mfma_f32_16x16x32_bf16 v[94:97], v[154:157], v[186:189], v[94:97]
	v_mfma_f32_16x16x32_bf16 v[94:97], v[142:145], v[182:185], v[94:97]
	v_mfma_f32_16x16x32_bf16 v[66:69], v[142:145], v[190:193], v[66:69]
	v_mfma_f32_16x16x32_bf16 v[66:69], v[154:157], v[214:217], v[66:69]
	v_mfma_f32_16x16x32_bf16 v[74:77], v[134:137], v[214:217], v[74:77]
	v_mfma_f32_16x16x32_bf16 v[74:77], v[126:129], v[190:193], v[74:77]
	v_mfma_f32_16x16x32_bf16 v[82:85], v[102:105], v[190:193], v[82:85]
	v_mfma_f32_16x16x32_bf16 v[82:85], v[114:117], v[214:217], v[82:85]
	v_mfma_f32_16x16x32_bf16 v[86:89], v[90:93], v[214:217], v[86:89]
	v_mfma_f32_16x16x32_bf16 v[86:89], v[78:81], v[190:193], v[86:89]
	s_setprio 0
	s_barrier
	s_add_i32 s0, s0, s28
	s_mov_b32 m0, s0
	s_nop 0
	global_load_lds_dwordx4 v194, s[70:71]
	s_add_i32 m0, s0, 0x2000
	s_add_u32 s0, s70, 0x80000
	s_addc_u32 s1, s71, 0
	s_add_i32 s18, s18, s28
	global_load_lds_dwordx4 v204, s[70:71]
	s_mov_b32 m0, s18
	s_nop 0
	global_load_lds_dwordx4 v194, s[0:1]
	s_add_i32 m0, s18, 0x2000
	s_nop 0
	global_load_lds_dwordx4 v204, s[0:1]
	s_mov_b32 m0, s29
	s_nop 0
	global_load_lds_dwordx4 v194, vcc
	s_mov_b32 m0, s31
	s_nop 0
	global_load_lds_dwordx4 v204, vcc
	ds_read_b128 v[158:161], v237 offset:16384
	ds_read_b128 v[162:165], v237 offset:17408
	ds_read_b128 v[166:169], v237 offset:18432
	ds_read_b128 v[178:181], v237 offset:19456
	ds_read_b128 v[182:185], v237 offset:20480
	ds_read_b128 v[186:189], v237 offset:21504
	ds_read_b128 v[190:193], v237 offset:22528
	ds_read_b128 v[214:217], v237 offset:23552
	s_waitcnt vmcnt(8)
	s_waitcnt lgkmcnt(0)
	s_barrier
	s_setprio 1
	s_waitcnt lgkmcnt(0)
	v_mfma_f32_16x16x32_bf16 v[62:65], v[78:81], v[158:161], v[62:65]
	v_mfma_f32_16x16x32_bf16 v[62:65], v[90:93], v[162:165], v[62:65]
	v_mfma_f32_16x16x32_bf16 v[58:61], v[114:117], v[162:165], v[58:61]
	v_mfma_f32_16x16x32_bf16 v[58:61], v[102:105], v[158:161], v[58:61]
	v_mfma_f32_16x16x32_bf16 v[54:57], v[126:129], v[158:161], v[54:57]
	v_mfma_f32_16x16x32_bf16 v[54:57], v[134:137], v[162:165], v[54:57]
	v_mfma_f32_16x16x32_bf16 v[50:53], v[154:157], v[162:165], v[50:53]
	v_mfma_f32_16x16x32_bf16 v[50:53], v[142:145], v[158:161], v[50:53]
	v_mfma_f32_16x16x32_bf16 v[34:37], v[142:145], v[166:169], v[34:37]
	v_mfma_f32_16x16x32_bf16 v[34:37], v[154:157], v[178:181], v[34:37]
	v_mfma_f32_16x16x32_bf16 v[38:41], v[134:137], v[178:181], v[38:41]
	v_mfma_f32_16x16x32_bf16 v[38:41], v[126:129], v[166:169], v[38:41]
	v_mfma_f32_16x16x32_bf16 v[42:45], v[102:105], v[166:169], v[42:45]
	v_mfma_f32_16x16x32_bf16 v[42:45], v[114:117], v[178:181], v[42:45]
	v_mfma_f32_16x16x32_bf16 v[46:49], v[90:93], v[178:181], v[46:49]
	v_mfma_f32_16x16x32_bf16 v[46:49], v[78:81], v[166:169], v[46:49]
	v_mfma_f32_16x16x32_bf16 v[30:33], v[78:81], v[182:185], v[30:33]
	v_mfma_f32_16x16x32_bf16 v[30:33], v[90:93], v[186:189], v[30:33]
	v_mfma_f32_16x16x32_bf16 v[26:29], v[114:117], v[186:189], v[26:29]
	v_mfma_f32_16x16x32_bf16 v[26:29], v[102:105], v[182:185], v[26:29]
	v_mfma_f32_16x16x32_bf16 v[22:25], v[126:129], v[182:185], v[22:25]
	v_mfma_f32_16x16x32_bf16 v[22:25], v[134:137], v[186:189], v[22:25]
	v_mfma_f32_16x16x32_bf16 v[18:21], v[154:157], v[186:189], v[18:21]
	v_mfma_f32_16x16x32_bf16 v[18:21], v[142:145], v[182:185], v[18:21]
	v_mfma_f32_16x16x32_bf16 v[2:5], v[142:145], v[190:193], v[2:5]
	v_mfma_f32_16x16x32_bf16 v[2:5], v[154:157], v[214:217], v[2:5]
	v_mfma_f32_16x16x32_bf16 v[6:9], v[134:137], v[214:217], v[6:9]
	v_mfma_f32_16x16x32_bf16 v[6:9], v[126:129], v[190:193], v[6:9]
	v_mfma_f32_16x16x32_bf16 v[10:13], v[102:105], v[190:193], v[10:13]
	v_mfma_f32_16x16x32_bf16 v[10:13], v[114:117], v[214:217], v[10:13]
	v_mfma_f32_16x16x32_bf16 v[14:17], v[90:93], v[214:217], v[14:17]
	v_mfma_f32_16x16x32_bf16 v[14:17], v[78:81], v[190:193], v[14:17]
	s_setprio 0
	s_barrier
	s_add_i32 s18, 0, 0x18000
	s_add_i32 s19, 0, 0x1c000
	s_add_u32 s0, vcc_lo, 0x80000
	s_addc_u32 s1, vcc_hi, 0
	s_mov_b32 m0, s33
	s_nop 0
	global_load_lds_dwordx4 v194, s[0:1]
	s_mov_b32 m0, s43
	s_nop 0
	global_load_lds_dwordx4 v204, s[0:1]
	v_add_u32_e32 v114, s18, v1
	v_add_u32_e32 v154, s19, v1
	ds_read_b128 v[78:81], v114
	ds_read_b128 v[90:93], v114 offset:1024
	ds_read_b128 v[102:105], v114 offset:2048
	ds_read_b128 v[114:117], v114 offset:3072
	ds_read_b128 v[126:129], v154
	ds_read_b128 v[134:137], v154 offset:1024
	ds_read_b128 v[142:145], v154 offset:2048
	ds_read_b128 v[154:157], v154 offset:3072
	ds_read_b128 v[158:161], v237 offset:32768
	ds_read_b128 v[162:165], v237 offset:33792
	ds_read_b128 v[166:169], v237 offset:34816
	ds_read_b128 v[178:181], v237 offset:35840
	ds_read_b128 v[182:185], v237 offset:36864
	ds_read_b128 v[186:189], v237 offset:37888
	ds_read_b128 v[190:193], v237 offset:38912
	ds_read_b128 v[214:217], v237 offset:39936
	s_waitcnt vmcnt(8)
	s_waitcnt lgkmcnt(0)
	s_barrier
	s_setprio 1
	s_waitcnt lgkmcnt(0)
	v_mfma_f32_16x16x32_bf16 v[174:177], v[78:81], v[158:161], v[174:177]
	v_mfma_f32_16x16x32_bf16 v[174:177], v[90:93], v[162:165], v[174:177]
	v_mfma_f32_16x16x32_bf16 v[170:173], v[114:117], v[162:165], v[170:173]
	v_mfma_f32_16x16x32_bf16 v[170:173], v[102:105], v[158:161], v[170:173]
	v_mfma_f32_16x16x32_bf16 v[150:153], v[126:129], v[158:161], v[150:153]
	v_mfma_f32_16x16x32_bf16 v[150:153], v[134:137], v[162:165], v[150:153]
	v_mfma_f32_16x16x32_bf16 v[146:149], v[154:157], v[162:165], v[146:149]
	v_mfma_f32_16x16x32_bf16 v[146:149], v[142:145], v[158:161], v[146:149]
	v_mfma_f32_16x16x32_bf16 v[118:121], v[142:145], v[166:169], v[118:121]
	v_mfma_f32_16x16x32_bf16 v[118:121], v[154:157], v[178:181], v[118:121]
	v_mfma_f32_16x16x32_bf16 v[122:125], v[134:137], v[178:181], v[122:125]
	v_mfma_f32_16x16x32_bf16 v[122:125], v[126:129], v[166:169], v[122:125]
	v_mfma_f32_16x16x32_bf16 v[130:133], v[102:105], v[166:169], v[130:133]
	v_mfma_f32_16x16x32_bf16 v[130:133], v[114:117], v[178:181], v[130:133]
	v_mfma_f32_16x16x32_bf16 v[138:141], v[90:93], v[178:181], v[138:141]
	v_mfma_f32_16x16x32_bf16 v[138:141], v[78:81], v[166:169], v[138:141]
	v_mfma_f32_16x16x32_bf16 v[110:113], v[78:81], v[182:185], v[110:113]
	v_mfma_f32_16x16x32_bf16 v[110:113], v[90:93], v[186:189], v[110:113]
	v_mfma_f32_16x16x32_bf16 v[106:109], v[114:117], v[186:189], v[106:109]
	v_mfma_f32_16x16x32_bf16 v[106:109], v[102:105], v[182:185], v[106:109]
	v_mfma_f32_16x16x32_bf16 v[98:101], v[126:129], v[182:185], v[98:101]
	v_mfma_f32_16x16x32_bf16 v[98:101], v[134:137], v[186:189], v[98:101]
	v_mfma_f32_16x16x32_bf16 v[94:97], v[154:157], v[186:189], v[94:97]
	v_mfma_f32_16x16x32_bf16 v[94:97], v[142:145], v[182:185], v[94:97]
	v_mfma_f32_16x16x32_bf16 v[66:69], v[142:145], v[190:193], v[66:69]
	v_mfma_f32_16x16x32_bf16 v[66:69], v[154:157], v[214:217], v[66:69]
	v_mfma_f32_16x16x32_bf16 v[74:77], v[134:137], v[214:217], v[74:77]
	v_mfma_f32_16x16x32_bf16 v[74:77], v[126:129], v[190:193], v[74:77]
	v_mfma_f32_16x16x32_bf16 v[82:85], v[102:105], v[190:193], v[82:85]
	v_mfma_f32_16x16x32_bf16 v[82:85], v[114:117], v[214:217], v[82:85]
	v_mfma_f32_16x16x32_bf16 v[86:89], v[90:93], v[214:217], v[86:89]
	v_mfma_f32_16x16x32_bf16 v[86:89], v[78:81], v[190:193], v[86:89]
	s_setprio 0
	s_barrier
	s_add_u32 s98, s70, 0x80
	s_addc_u32 s99, s71, 0
	s_add_u32 s100, vcc_lo, 0x80
	s_addc_u32 s101, vcc_hi, 0
	s_add_i32 s0, s18, s28
	s_mov_b32 m0, s0
	s_nop 0
	global_load_lds_dwordx4 v194, s[98:99]
	s_add_i32 m0, s0, 0x2000
	s_add_u32 s0, s70, 0x80080
	s_addc_u32 s1, s71, 0
	s_add_i32 s18, s19, s28
	global_load_lds_dwordx4 v204, s[98:99]
	s_mov_b32 m0, s18
	s_nop 0
	global_load_lds_dwordx4 v194, s[0:1]
	s_add_i32 m0, s18, 0x2000
	s_nop 0
	global_load_lds_dwordx4 v204, s[0:1]
	s_mov_b32 m0, s68
	s_nop 0
	global_load_lds_dwordx4 v194, s[100:101]
	s_mov_b32 m0, s79
	s_nop 0
	global_load_lds_dwordx4 v204, s[100:101]
	ds_read_b128 v[158:161], v237 offset:49152
	ds_read_b128 v[162:165], v237 offset:50176
	ds_read_b128 v[166:169], v237 offset:51200
	ds_read_b128 v[178:181], v237 offset:52224
	ds_read_b128 v[182:185], v237 offset:53248
	ds_read_b128 v[186:189], v237 offset:54272
	ds_read_b128 v[190:193], v237 offset:55296
	ds_read_b128 v[214:217], v237 offset:56320
	s_waitcnt vmcnt(8)
	s_waitcnt lgkmcnt(0)
	s_barrier
	s_setprio 1
	s_waitcnt lgkmcnt(0)
	v_mfma_f32_16x16x32_bf16 v[62:65], v[78:81], v[158:161], v[62:65]
	v_mfma_f32_16x16x32_bf16 v[62:65], v[90:93], v[162:165], v[62:65]
	v_mfma_f32_16x16x32_bf16 v[58:61], v[114:117], v[162:165], v[58:61]
	v_mfma_f32_16x16x32_bf16 v[58:61], v[102:105], v[158:161], v[58:61]
	v_mfma_f32_16x16x32_bf16 v[54:57], v[126:129], v[158:161], v[54:57]
	v_mfma_f32_16x16x32_bf16 v[54:57], v[134:137], v[162:165], v[54:57]
	v_mfma_f32_16x16x32_bf16 v[50:53], v[154:157], v[162:165], v[50:53]
	v_mfma_f32_16x16x32_bf16 v[50:53], v[142:145], v[158:161], v[50:53]
	v_mfma_f32_16x16x32_bf16 v[34:37], v[142:145], v[166:169], v[34:37]
	v_mfma_f32_16x16x32_bf16 v[34:37], v[154:157], v[178:181], v[34:37]
	v_mfma_f32_16x16x32_bf16 v[38:41], v[134:137], v[178:181], v[38:41]
	v_mfma_f32_16x16x32_bf16 v[38:41], v[126:129], v[166:169], v[38:41]
	v_mfma_f32_16x16x32_bf16 v[42:45], v[102:105], v[166:169], v[42:45]
	v_mfma_f32_16x16x32_bf16 v[42:45], v[114:117], v[178:181], v[42:45]
	v_mfma_f32_16x16x32_bf16 v[46:49], v[90:93], v[178:181], v[46:49]
	v_mfma_f32_16x16x32_bf16 v[46:49], v[78:81], v[166:169], v[46:49]
	v_mfma_f32_16x16x32_bf16 v[30:33], v[78:81], v[182:185], v[30:33]
	v_mfma_f32_16x16x32_bf16 v[30:33], v[90:93], v[186:189], v[30:33]
	v_mfma_f32_16x16x32_bf16 v[26:29], v[114:117], v[186:189], v[26:29]
	v_mfma_f32_16x16x32_bf16 v[26:29], v[102:105], v[182:185], v[26:29]
	v_mfma_f32_16x16x32_bf16 v[22:25], v[126:129], v[182:185], v[22:25]
	v_mfma_f32_16x16x32_bf16 v[22:25], v[134:137], v[186:189], v[22:25]
	v_mfma_f32_16x16x32_bf16 v[18:21], v[154:157], v[186:189], v[18:21]
	v_mfma_f32_16x16x32_bf16 v[18:21], v[142:145], v[182:185], v[18:21]
	v_mfma_f32_16x16x32_bf16 v[2:5], v[142:145], v[190:193], v[2:5]
	v_mfma_f32_16x16x32_bf16 v[2:5], v[154:157], v[214:217], v[2:5]
	v_mfma_f32_16x16x32_bf16 v[6:9], v[134:137], v[214:217], v[6:9]
	v_mfma_f32_16x16x32_bf16 v[6:9], v[126:129], v[190:193], v[6:9]
	v_mfma_f32_16x16x32_bf16 v[10:13], v[102:105], v[190:193], v[10:13]
	v_mfma_f32_16x16x32_bf16 v[10:13], v[114:117], v[214:217], v[10:13]
	v_mfma_f32_16x16x32_bf16 v[14:17], v[90:93], v[214:217], v[14:17]
	v_mfma_f32_16x16x32_bf16 v[14:17], v[78:81], v[190:193], v[14:17]
	s_setprio 0
	s_barrier
	s_add_i32 s57, s57, 2
	s_add_u32 s51, s51, 0x100
	s_addc_u32 s53, s53, 0
	s_cmp_gt_u32 s57, 29
	s_mov_b64 s[76:77], s[90:91]
	s_cbranch_scc1 .LBB0_512

.Lpeel_disp_out:
	s_cmp_lg_u32 s57, -2
	s_cbranch_scc1 .LBB0_509
	s_add_u32 s90, s76, 0x100
	s_addc_u32 s91, s77, 0
	s_and_b64 s[0:1], s[70:71], exec
	s_cselect_b32 vcc_hi, s22, s91
	s_cselect_b32 vcc_lo, s23, s90
	s_cselect_b32 s71, s41, s53
	s_cselect_b32 s70, s44, s51
	s_add_i32 s0, 0, 0x10000
	s_add_i32 s18, 0, 0x14000
	s_add_i32 m0, s29, 0xc000
	s_nop 0
	global_load_lds_dwordx4 v210, s[76:77]
	s_add_i32 m0, s29, 0xe000
	s_nop 0
	global_load_lds_dwordx4 v212, s[76:77]
	v_add_u32_e32 v114, s0, v1
	v_add_u32_e32 v154, s18, v1
	ds_read_b128 v[78:81], v114
	ds_read_b128 v[90:93], v114 offset:1024
	ds_read_b128 v[102:105], v114 offset:2048
	ds_read_b128 v[114:117], v114 offset:3072
	ds_read_b128 v[126:129], v154
	ds_read_b128 v[134:137], v154 offset:1024
	ds_read_b128 v[142:145], v154 offset:2048
	ds_read_b128 v[154:157], v154 offset:3072
	ds_read_b128 v[158:161], v237
	ds_read_b128 v[162:165], v237 offset:1024
	ds_read_b128 v[166:169], v237 offset:2048
	ds_read_b128 v[178:181], v237 offset:3072
	ds_read_b128 v[182:185], v237 offset:4096
	ds_read_b128 v[186:189], v237 offset:5120
	ds_read_b128 v[190:193], v237 offset:6144
	ds_read_b128 v[214:217], v237 offset:7168
	s_waitcnt vmcnt(8)
	s_waitcnt lgkmcnt(0)
	s_barrier
	s_setprio 1
	s_waitcnt lgkmcnt(0)
	v_mfma_f32_16x16x32_bf16 v[174:177], v[78:81], v[158:161], 0
	v_mfma_f32_16x16x32_bf16 v[174:177], v[90:93], v[162:165], v[174:177]
	v_mfma_f32_16x16x32_bf16 v[170:173], v[114:117], v[162:165], 0
	v_mfma_f32_16x16x32_bf16 v[170:173], v[102:105], v[158:161], v[170:173]
	v_mfma_f32_16x16x32_bf16 v[150:153], v[126:129], v[158:161], 0
	v_mfma_f32_16x16x32_bf16 v[150:153], v[134:137], v[162:165], v[150:153]
	v_mfma_f32_16x16x32_bf16 v[146:149], v[154:157], v[162:165], 0
	v_mfma_f32_16x16x32_bf16 v[146:149], v[142:145], v[158:161], v[146:149]
	v_mfma_f32_16x16x32_bf16 v[118:121], v[142:145], v[166:169], 0
	v_mfma_f32_16x16x32_bf16 v[118:121], v[154:157], v[178:181], v[118:121]
	v_mfma_f32_16x16x32_bf16 v[122:125], v[134:137], v[178:181], 0
	v_mfma_f32_16x16x32_bf16 v[122:125], v[126:129], v[166:169], v[122:125]
	v_mfma_f32_16x16x32_bf16 v[130:133], v[102:105], v[166:169], 0
	v_mfma_f32_16x16x32_bf16 v[130:133], v[114:117], v[178:181], v[130:133]
	v_mfma_f32_16x16x32_bf16 v[138:141], v[90:93], v[178:181], 0
	v_mfma_f32_16x16x32_bf16 v[138:141], v[78:81], v[166:169], v[138:141]
	v_mfma_f32_16x16x32_bf16 v[110:113], v[78:81], v[182:185], 0
	v_mfma_f32_16x16x32_bf16 v[110:113], v[90:93], v[186:189], v[110:113]
	v_mfma_f32_16x16x32_bf16 v[106:109], v[114:117], v[186:189], 0
	v_mfma_f32_16x16x32_bf16 v[106:109], v[102:105], v[182:185], v[106:109]
	v_mfma_f32_16x16x32_bf16 v[98:101], v[126:129], v[182:185], 0
	v_mfma_f32_16x16x32_bf16 v[98:101], v[134:137], v[186:189], v[98:101]
	v_mfma_f32_16x16x32_bf16 v[94:97], v[154:157], v[186:189], 0
	v_mfma_f32_16x16x32_bf16 v[94:97], v[142:145], v[182:185], v[94:97]
	v_mfma_f32_16x16x32_bf16 v[66:69], v[142:145], v[190:193], 0
	v_mfma_f32_16x16x32_bf16 v[66:69], v[154:157], v[214:217], v[66:69]
	v_mfma_f32_16x16x32_bf16 v[74:77], v[134:137], v[214:217], 0
	v_mfma_f32_16x16x32_bf16 v[74:77], v[126:129], v[190:193], v[74:77]
	v_mfma_f32_16x16x32_bf16 v[82:85], v[102:105], v[190:193], 0
	v_mfma_f32_16x16x32_bf16 v[82:85], v[114:117], v[214:217], v[82:85]
	v_mfma_f32_16x16x32_bf16 v[86:89], v[90:93], v[214:217], 0
	v_mfma_f32_16x16x32_bf16 v[86:89], v[78:81], v[190:193], v[86:89]
	s_setprio 0
	s_barrier
	s_add_i32 s0, s0, s28
	s_mov_b32 m0, s0
	s_nop 0
	global_load_lds_dwordx4 v194, s[70:71]
	s_add_i32 m0, s0, 0x2000
	s_add_u32 s0, s70, 0x80000
	s_addc_u32 s1, s71, 0
	s_add_i32 s18, s18, s28
	global_load_lds_dwordx4 v204, s[70:71]
	s_mov_b32 m0, s18
	s_nop 0
	global_load_lds_dwordx4 v194, s[0:1]
	s_add_i32 m0, s18, 0x2000
	s_nop 0
	global_load_lds_dwordx4 v204, s[0:1]
	s_mov_b32 m0, s29
	s_nop 0
	global_load_lds_dwordx4 v194, vcc
	s_mov_b32 m0, s31
	s_nop 0
	global_load_lds_dwordx4 v204, vcc
	ds_read_b128 v[158:161], v237 offset:16384
	ds_read_b128 v[162:165], v237 offset:17408
	ds_read_b128 v[166:169], v237 offset:18432
	ds_read_b128 v[178:181], v237 offset:19456
	ds_read_b128 v[182:185], v237 offset:20480
	ds_read_b128 v[186:189], v237 offset:21504
	ds_read_b128 v[190:193], v237 offset:22528
	ds_read_b128 v[214:217], v237 offset:23552
	s_waitcnt vmcnt(8)
	s_waitcnt lgkmcnt(0)
	s_barrier
	s_setprio 1
	s_waitcnt lgkmcnt(0)
	v_mfma_f32_16x16x32_bf16 v[62:65], v[78:81], v[158:161], 0
	v_mfma_f32_16x16x32_bf16 v[62:65], v[90:93], v[162:165], v[62:65]
	v_mfma_f32_16x16x32_bf16 v[58:61], v[114:117], v[162:165], 0
	v_mfma_f32_16x16x32_bf16 v[58:61], v[102:105], v[158:161], v[58:61]
	v_mfma_f32_16x16x32_bf16 v[54:57], v[126:129], v[158:161], 0
	v_mfma_f32_16x16x32_bf16 v[54:57], v[134:137], v[162:165], v[54:57]
	v_mfma_f32_16x16x32_bf16 v[50:53], v[154:157], v[162:165], 0
	v_mfma_f32_16x16x32_bf16 v[50:53], v[142:145], v[158:161], v[50:53]
	v_mfma_f32_16x16x32_bf16 v[34:37], v[142:145], v[166:169], 0
	v_mfma_f32_16x16x32_bf16 v[34:37], v[154:157], v[178:181], v[34:37]
	v_mfma_f32_16x16x32_bf16 v[38:41], v[134:137], v[178:181], 0
	v_mfma_f32_16x16x32_bf16 v[38:41], v[126:129], v[166:169], v[38:41]
	v_mfma_f32_16x16x32_bf16 v[42:45], v[102:105], v[166:169], 0
	v_mfma_f32_16x16x32_bf16 v[42:45], v[114:117], v[178:181], v[42:45]
	v_mfma_f32_16x16x32_bf16 v[46:49], v[90:93], v[178:181], 0
	v_mfma_f32_16x16x32_bf16 v[46:49], v[78:81], v[166:169], v[46:49]
	v_mfma_f32_16x16x32_bf16 v[30:33], v[78:81], v[182:185], 0
	v_mfma_f32_16x16x32_bf16 v[30:33], v[90:93], v[186:189], v[30:33]
	v_mfma_f32_16x16x32_bf16 v[26:29], v[114:117], v[186:189], 0
	v_mfma_f32_16x16x32_bf16 v[26:29], v[102:105], v[182:185], v[26:29]
	v_mfma_f32_16x16x32_bf16 v[22:25], v[126:129], v[182:185], 0
	v_mfma_f32_16x16x32_bf16 v[22:25], v[134:137], v[186:189], v[22:25]
	v_mfma_f32_16x16x32_bf16 v[18:21], v[154:157], v[186:189], 0
	v_mfma_f32_16x16x32_bf16 v[18:21], v[142:145], v[182:185], v[18:21]
	v_mfma_f32_16x16x32_bf16 v[2:5], v[142:145], v[190:193], 0
	v_mfma_f32_16x16x32_bf16 v[2:5], v[154:157], v[214:217], v[2:5]
	v_mfma_f32_16x16x32_bf16 v[6:9], v[134:137], v[214:217], 0
	v_mfma_f32_16x16x32_bf16 v[6:9], v[126:129], v[190:193], v[6:9]
	v_mfma_f32_16x16x32_bf16 v[10:13], v[102:105], v[190:193], 0
	v_mfma_f32_16x16x32_bf16 v[10:13], v[114:117], v[214:217], v[10:13]
	v_mfma_f32_16x16x32_bf16 v[14:17], v[90:93], v[214:217], 0
	v_mfma_f32_16x16x32_bf16 v[14:17], v[78:81], v[190:193], v[14:17]
	s_setprio 0
	s_barrier
	s_add_i32 s18, 0, 0x18000
	s_add_i32 s19, 0, 0x1c000
	s_add_u32 s0, vcc_lo, 0x80000
	s_addc_u32 s1, vcc_hi, 0
	s_mov_b32 m0, s33
	s_nop 0
	global_load_lds_dwordx4 v194, s[0:1]
	s_mov_b32 m0, s43
	s_nop 0
	global_load_lds_dwordx4 v204, s[0:1]
	v_add_u32_e32 v114, s18, v1
	v_add_u32_e32 v154, s19, v1
	ds_read_b128 v[78:81], v114
	ds_read_b128 v[90:93], v114 offset:1024
	ds_read_b128 v[102:105], v114 offset:2048
	ds_read_b128 v[114:117], v114 offset:3072
	ds_read_b128 v[126:129], v154
	ds_read_b128 v[134:137], v154 offset:1024
	ds_read_b128 v[142:145], v154 offset:2048
	ds_read_b128 v[154:157], v154 offset:3072
	ds_read_b128 v[158:161], v237 offset:32768
	ds_read_b128 v[162:165], v237 offset:33792
	ds_read_b128 v[166:169], v237 offset:34816
	ds_read_b128 v[178:181], v237 offset:35840
	ds_read_b128 v[182:185], v237 offset:36864
	ds_read_b128 v[186:189], v237 offset:37888
	ds_read_b128 v[190:193], v237 offset:38912
	ds_read_b128 v[214:217], v237 offset:39936
	s_waitcnt vmcnt(8)
	s_waitcnt lgkmcnt(0)
	s_barrier
	s_setprio 1
	s_waitcnt lgkmcnt(0)
	v_mfma_f32_16x16x32_bf16 v[174:177], v[78:81], v[158:161], v[174:177]
	v_mfma_f32_16x16x32_bf16 v[174:177], v[90:93], v[162:165], v[174:177]
	v_mfma_f32_16x16x32_bf16 v[170:173], v[114:117], v[162:165], v[170:173]
	v_mfma_f32_16x16x32_bf16 v[170:173], v[102:105], v[158:161], v[170:173]
	v_mfma_f32_16x16x32_bf16 v[150:153], v[126:129], v[158:161], v[150:153]
	v_mfma_f32_16x16x32_bf16 v[150:153], v[134:137], v[162:165], v[150:153]
	v_mfma_f32_16x16x32_bf16 v[146:149], v[154:157], v[162:165], v[146:149]
	v_mfma_f32_16x16x32_bf16 v[146:149], v[142:145], v[158:161], v[146:149]
	v_mfma_f32_16x16x32_bf16 v[118:121], v[142:145], v[166:169], v[118:121]
	v_mfma_f32_16x16x32_bf16 v[118:121], v[154:157], v[178:181], v[118:121]
	v_mfma_f32_16x16x32_bf16 v[122:125], v[134:137], v[178:181], v[122:125]
	v_mfma_f32_16x16x32_bf16 v[122:125], v[126:129], v[166:169], v[122:125]
	v_mfma_f32_16x16x32_bf16 v[130:133], v[102:105], v[166:169], v[130:133]
	v_mfma_f32_16x16x32_bf16 v[130:133], v[114:117], v[178:181], v[130:133]
	v_mfma_f32_16x16x32_bf16 v[138:141], v[90:93], v[178:181], v[138:141]
	v_mfma_f32_16x16x32_bf16 v[138:141], v[78:81], v[166:169], v[138:141]
	v_mfma_f32_16x16x32_bf16 v[110:113], v[78:81], v[182:185], v[110:113]
	v_mfma_f32_16x16x32_bf16 v[110:113], v[90:93], v[186:189], v[110:113]
	v_mfma_f32_16x16x32_bf16 v[106:109], v[114:117], v[186:189], v[106:109]
	v_mfma_f32_16x16x32_bf16 v[106:109], v[102:105], v[182:185], v[106:109]
	v_mfma_f32_16x16x32_bf16 v[98:101], v[126:129], v[182:185], v[98:101]
	v_mfma_f32_16x16x32_bf16 v[98:101], v[134:137], v[186:189], v[98:101]
	v_mfma_f32_16x16x32_bf16 v[94:97], v[154:157], v[186:189], v[94:97]
	v_mfma_f32_16x16x32_bf16 v[94:97], v[142:145], v[182:185], v[94:97]
	v_mfma_f32_16x16x32_bf16 v[66:69], v[142:145], v[190:193], v[66:69]
	v_mfma_f32_16x16x32_bf16 v[66:69], v[154:157], v[214:217], v[66:69]
	v_mfma_f32_16x16x32_bf16 v[74:77], v[134:137], v[214:217], v[74:77]
	v_mfma_f32_16x16x32_bf16 v[74:77], v[126:129], v[190:193], v[74:77]
	v_mfma_f32_16x16x32_bf16 v[82:85], v[102:105], v[190:193], v[82:85]
	v_mfma_f32_16x16x32_bf16 v[82:85], v[114:117], v[214:217], v[82:85]
	v_mfma_f32_16x16x32_bf16 v[86:89], v[90:93], v[214:217], v[86:89]
	v_mfma_f32_16x16x32_bf16 v[86:89], v[78:81], v[190:193], v[86:89]
	s_setprio 0
	s_barrier
	s_add_u32 s98, s70, 0x80
	s_addc_u32 s99, s71, 0
	s_add_u32 s100, vcc_lo, 0x80
	s_addc_u32 s101, vcc_hi, 0
	s_add_i32 s0, s18, s28
	s_mov_b32 m0, s0
	s_nop 0
	global_load_lds_dwordx4 v194, s[98:99]
	s_add_i32 m0, s0, 0x2000
	s_add_u32 s0, s70, 0x80080
	s_addc_u32 s1, s71, 0
	s_add_i32 s18, s19, s28
	global_load_lds_dwordx4 v204, s[98:99]
	s_mov_b32 m0, s18
	s_nop 0
	global_load_lds_dwordx4 v194, s[0:1]
	s_add_i32 m0, s18, 0x2000
	s_nop 0
	global_load_lds_dwordx4 v204, s[0:1]
	s_mov_b32 m0, s68
	s_nop 0
	global_load_lds_dwordx4 v194, s[100:101]
	s_mov_b32 m0, s79
	s_nop 0
	global_load_lds_dwordx4 v204, s[100:101]
	ds_read_b128 v[158:161], v237 offset:49152
	ds_read_b128 v[162:165], v237 offset:50176
	ds_read_b128 v[166:169], v237 offset:51200
	ds_read_b128 v[178:181], v237 offset:52224
	ds_read_b128 v[182:185], v237 offset:53248
	ds_read_b128 v[186:189], v237 offset:54272
	ds_read_b128 v[190:193], v237 offset:55296
	ds_read_b128 v[214:217], v237 offset:56320
	s_waitcnt vmcnt(8)
	s_waitcnt lgkmcnt(0)
	s_barrier
	s_setprio 1
	s_waitcnt lgkmcnt(0)
	v_mfma_f32_16x16x32_bf16 v[62:65], v[78:81], v[158:161], v[62:65]
	v_mfma_f32_16x16x32_bf16 v[62:65], v[90:93], v[162:165], v[62:65]
	v_mfma_f32_16x16x32_bf16 v[58:61], v[114:117], v[162:165], v[58:61]
	v_mfma_f32_16x16x32_bf16 v[58:61], v[102:105], v[158:161], v[58:61]
	v_mfma_f32_16x16x32_bf16 v[54:57], v[126:129], v[158:161], v[54:57]
	v_mfma_f32_16x16x32_bf16 v[54:57], v[134:137], v[162:165], v[54:57]
	v_mfma_f32_16x16x32_bf16 v[50:53], v[154:157], v[162:165], v[50:53]
	v_mfma_f32_16x16x32_bf16 v[50:53], v[142:145], v[158:161], v[50:53]
	v_mfma_f32_16x16x32_bf16 v[34:37], v[142:145], v[166:169], v[34:37]
	v_mfma_f32_16x16x32_bf16 v[34:37], v[154:157], v[178:181], v[34:37]
	v_mfma_f32_16x16x32_bf16 v[38:41], v[134:137], v[178:181], v[38:41]
	v_mfma_f32_16x16x32_bf16 v[38:41], v[126:129], v[166:169], v[38:41]
	v_mfma_f32_16x16x32_bf16 v[42:45], v[102:105], v[166:169], v[42:45]
	v_mfma_f32_16x16x32_bf16 v[42:45], v[114:117], v[178:181], v[42:45]
	v_mfma_f32_16x16x32_bf16 v[46:49], v[90:93], v[178:181], v[46:49]
	v_mfma_f32_16x16x32_bf16 v[46:49], v[78:81], v[166:169], v[46:49]
	v_mfma_f32_16x16x32_bf16 v[30:33], v[78:81], v[182:185], v[30:33]
	v_mfma_f32_16x16x32_bf16 v[30:33], v[90:93], v[186:189], v[30:33]
	v_mfma_f32_16x16x32_bf16 v[26:29], v[114:117], v[186:189], v[26:29]
	v_mfma_f32_16x16x32_bf16 v[26:29], v[102:105], v[182:185], v[26:29]
	v_mfma_f32_16x16x32_bf16 v[22:25], v[126:129], v[182:185], v[22:25]
	v_mfma_f32_16x16x32_bf16 v[22:25], v[134:137], v[186:189], v[22:25]
	v_mfma_f32_16x16x32_bf16 v[18:21], v[154:157], v[186:189], v[18:21]
	v_mfma_f32_16x16x32_bf16 v[18:21], v[142:145], v[182:185], v[18:21]
	v_mfma_f32_16x16x32_bf16 v[2:5], v[142:145], v[190:193], v[2:5]
	v_mfma_f32_16x16x32_bf16 v[2:5], v[154:157], v[214:217], v[2:5]
	v_mfma_f32_16x16x32_bf16 v[6:9], v[134:137], v[214:217], v[6:9]
	v_mfma_f32_16x16x32_bf16 v[6:9], v[126:129], v[190:193], v[6:9]
	v_mfma_f32_16x16x32_bf16 v[10:13], v[102:105], v[190:193], v[10:13]
	v_mfma_f32_16x16x32_bf16 v[10:13], v[114:117], v[214:217], v[10:13]
	v_mfma_f32_16x16x32_bf16 v[14:17], v[90:93], v[214:217], v[14:17]
	v_mfma_f32_16x16x32_bf16 v[14:17], v[78:81], v[190:193], v[14:17]
	s_setprio 0
	s_barrier
	s_add_i32 s57, s57, 2
	s_add_u32 s51, s51, 0x100
	s_addc_u32 s53, s53, 0
	s_cmp_gt_u32 s57, 29
	s_mov_b64 s[76:77], s[90:91]
	s_cbranch_scc1 .LBB0_512
	s_branch .LBB0_510

.LBB0_581:
	s_add_u32 s18, s62, 0xfff80080
	s_addc_u32 s19, s63, -1
	s_and_b64 s[0:1], s[64:65], exec
	s_cselect_b32 s71, s22, s19
	s_cselect_b32 s70, s23, s18
	s_cselect_b32 s65, s39, s58
	s_cselect_b32 s64, s47, s53
	s_add_i32 s0, 0, 0x10000
	s_add_i32 s18, 0, 0x14000
	s_add_i32 m0, s29, 0xc000
	s_nop 0
	global_load_lds_dwordx4 v136, s[62:63]
	s_add_i32 m0, s29, 0xe000
	s_nop 0
	global_load_lds_dwordx4 v138, s[62:63]
	v_add_u32_e32 v153, s0, v1
	ds_read_b128 v[144:147], v153
	ds_read_b128 v[148:151], v153 offset:1024
	ds_read_b128 v[154:157], v153 offset:2048
	ds_read_b128 v[158:161], v153 offset:3072
	v_add_u32_e32 v153, s18, v1
	ds_read_b128 v[162:165], v153
	ds_read_b128 v[166:169], v153 offset:1024
	ds_read_b128 v[170:173], v153 offset:2048
	ds_read_b128 v[174:177], v153 offset:3072
	ds_read_b128 v[178:181], v152
	ds_read_b128 v[182:185], v152 offset:1024
	ds_read_b128 v[186:189], v152 offset:2048
	ds_read_b128 v[190:193], v152 offset:3072
	ds_read_b128 v[204:207], v152 offset:4096
	ds_read_b128 v[208:211], v152 offset:5120
	ds_read_b128 v[212:215], v152 offset:6144
	ds_read_b128 v[216:219], v152 offset:7168
	s_waitcnt vmcnt(8)
	s_waitcnt lgkmcnt(0)
	s_barrier
	s_setprio 1
	s_waitcnt lgkmcnt(0)
	v_mfma_f32_16x16x32_bf16 v[126:129], v[144:147], v[178:181], v[126:129]
	v_mfma_f32_16x16x32_bf16 v[126:129], v[148:151], v[182:185], v[126:129]
	v_mfma_f32_16x16x32_bf16 v[122:125], v[158:161], v[182:185], v[122:125]
	v_mfma_f32_16x16x32_bf16 v[122:125], v[154:157], v[178:181], v[122:125]
	v_mfma_f32_16x16x32_bf16 v[118:121], v[162:165], v[178:181], v[118:121]
	v_mfma_f32_16x16x32_bf16 v[118:121], v[166:169], v[182:185], v[118:121]
	v_mfma_f32_16x16x32_bf16 v[114:117], v[174:177], v[182:185], v[114:117]
	v_mfma_f32_16x16x32_bf16 v[114:117], v[170:173], v[178:181], v[114:117]
	v_mfma_f32_16x16x32_bf16 v[98:101], v[170:173], v[186:189], v[98:101]
	v_mfma_f32_16x16x32_bf16 v[98:101], v[174:177], v[190:193], v[98:101]
	v_mfma_f32_16x16x32_bf16 v[102:105], v[166:169], v[190:193], v[102:105]
	v_mfma_f32_16x16x32_bf16 v[102:105], v[162:165], v[186:189], v[102:105]
	v_mfma_f32_16x16x32_bf16 v[106:109], v[154:157], v[186:189], v[106:109]
	v_mfma_f32_16x16x32_bf16 v[106:109], v[158:161], v[190:193], v[106:109]
	v_mfma_f32_16x16x32_bf16 v[110:113], v[148:151], v[190:193], v[110:113]
	v_mfma_f32_16x16x32_bf16 v[110:113], v[144:147], v[186:189], v[110:113]
	v_mfma_f32_16x16x32_bf16 v[94:97], v[144:147], v[204:207], v[94:97]
	v_mfma_f32_16x16x32_bf16 v[94:97], v[148:151], v[208:211], v[94:97]
	v_mfma_f32_16x16x32_bf16 v[90:93], v[158:161], v[208:211], v[90:93]
	v_mfma_f32_16x16x32_bf16 v[90:93], v[154:157], v[204:207], v[90:93]
	v_mfma_f32_16x16x32_bf16 v[86:89], v[162:165], v[204:207], v[86:89]
	v_mfma_f32_16x16x32_bf16 v[86:89], v[166:169], v[208:211], v[86:89]
	v_mfma_f32_16x16x32_bf16 v[82:85], v[174:177], v[208:211], v[82:85]
	v_mfma_f32_16x16x32_bf16 v[82:85], v[170:173], v[204:207], v[82:85]
	v_mfma_f32_16x16x32_bf16 v[66:69], v[170:173], v[212:215], v[66:69]
	v_mfma_f32_16x16x32_bf16 v[66:69], v[174:177], v[216:219], v[66:69]
	v_mfma_f32_16x16x32_bf16 v[70:73], v[166:169], v[216:219], v[70:73]
	v_mfma_f32_16x16x32_bf16 v[70:73], v[162:165], v[212:215], v[70:73]
	v_mfma_f32_16x16x32_bf16 v[74:77], v[154:157], v[212:215], v[74:77]
	v_mfma_f32_16x16x32_bf16 v[74:77], v[158:161], v[216:219], v[74:77]
	v_mfma_f32_16x16x32_bf16 v[78:81], v[148:151], v[216:219], v[78:81]
	v_mfma_f32_16x16x32_bf16 v[78:81], v[144:147], v[212:215], v[78:81]
	s_setprio 0
	s_barrier
	s_add_i32 s0, s0, s28
	s_mov_b32 m0, s0
	s_nop 0
	global_load_lds_dwordx4 v194, s[64:65]
	s_add_i32 m0, s0, 0x2000
	s_add_u32 s0, s64, 0x80000
	s_addc_u32 s1, s65, 0
	s_add_i32 s18, s18, s28
	global_load_lds_dwordx4 v130, s[64:65]
	s_mov_b32 m0, s18
	s_nop 0
	global_load_lds_dwordx4 v194, s[0:1]
	s_add_i32 m0, s18, 0x2000
	s_nop 0
	global_load_lds_dwordx4 v130, s[0:1]
	s_mov_b32 m0, s29
	s_nop 0
	global_load_lds_dwordx4 v194, s[70:71]
	s_mov_b32 m0, s31
	s_nop 0
	global_load_lds_dwordx4 v130, s[70:71]
	ds_read_b128 v[178:181], v152 offset:16384
	ds_read_b128 v[182:185], v152 offset:17408
	ds_read_b128 v[186:189], v152 offset:18432
	ds_read_b128 v[190:193], v152 offset:19456
	ds_read_b128 v[204:207], v152 offset:20480
	ds_read_b128 v[208:211], v152 offset:21504
	ds_read_b128 v[212:215], v152 offset:22528
	ds_read_b128 v[216:219], v152 offset:23552
	s_waitcnt vmcnt(8)
	s_waitcnt lgkmcnt(0)
	s_barrier
	s_setprio 1
	s_waitcnt lgkmcnt(0)
	v_mfma_f32_16x16x32_bf16 v[62:65], v[144:147], v[178:181], v[62:65]
	v_mfma_f32_16x16x32_bf16 v[62:65], v[148:151], v[182:185], v[62:65]
	v_mfma_f32_16x16x32_bf16 v[58:61], v[158:161], v[182:185], v[58:61]
	v_mfma_f32_16x16x32_bf16 v[58:61], v[154:157], v[178:181], v[58:61]
	v_mfma_f32_16x16x32_bf16 v[54:57], v[162:165], v[178:181], v[54:57]
	v_mfma_f32_16x16x32_bf16 v[54:57], v[166:169], v[182:185], v[54:57]
	v_mfma_f32_16x16x32_bf16 v[50:53], v[174:177], v[182:185], v[50:53]
	v_mfma_f32_16x16x32_bf16 v[50:53], v[170:173], v[178:181], v[50:53]
	v_mfma_f32_16x16x32_bf16 v[34:37], v[170:173], v[186:189], v[34:37]
	v_mfma_f32_16x16x32_bf16 v[34:37], v[174:177], v[190:193], v[34:37]
	v_mfma_f32_16x16x32_bf16 v[38:41], v[166:169], v[190:193], v[38:41]
	v_mfma_f32_16x16x32_bf16 v[38:41], v[162:165], v[186:189], v[38:41]
	v_mfma_f32_16x16x32_bf16 v[42:45], v[154:157], v[186:189], v[42:45]
	v_mfma_f32_16x16x32_bf16 v[42:45], v[158:161], v[190:193], v[42:45]
	v_mfma_f32_16x16x32_bf16 v[46:49], v[148:151], v[190:193], v[46:49]
	v_mfma_f32_16x16x32_bf16 v[46:49], v[144:147], v[186:189], v[46:49]
	v_mfma_f32_16x16x32_bf16 v[30:33], v[144:147], v[204:207], v[30:33]
	v_mfma_f32_16x16x32_bf16 v[30:33], v[148:151], v[208:211], v[30:33]
	v_mfma_f32_16x16x32_bf16 v[26:29], v[158:161], v[208:211], v[26:29]
	v_mfma_f32_16x16x32_bf16 v[26:29], v[154:157], v[204:207], v[26:29]
	v_mfma_f32_16x16x32_bf16 v[22:25], v[162:165], v[204:207], v[22:25]
	v_mfma_f32_16x16x32_bf16 v[22:25], v[166:169], v[208:211], v[22:25]
	v_mfma_f32_16x16x32_bf16 v[18:21], v[174:177], v[208:211], v[18:21]
	v_mfma_f32_16x16x32_bf16 v[18:21], v[170:173], v[204:207], v[18:21]
	v_mfma_f32_16x16x32_bf16 v[2:5], v[170:173], v[212:215], v[2:5]
	v_mfma_f32_16x16x32_bf16 v[2:5], v[174:177], v[216:219], v[2:5]
	v_mfma_f32_16x16x32_bf16 v[6:9], v[166:169], v[216:219], v[6:9]
	v_mfma_f32_16x16x32_bf16 v[6:9], v[162:165], v[212:215], v[6:9]
	v_mfma_f32_16x16x32_bf16 v[10:13], v[154:157], v[212:215], v[10:13]
	v_mfma_f32_16x16x32_bf16 v[10:13], v[158:161], v[216:219], v[10:13]
	v_mfma_f32_16x16x32_bf16 v[14:17], v[148:151], v[216:219], v[14:17]
	v_mfma_f32_16x16x32_bf16 v[14:17], v[144:147], v[212:215], v[14:17]
	s_setprio 0
	s_barrier
	s_add_i32 s18, 0, 0x18000
	s_add_i32 s19, 0, 0x1c000
	s_add_u32 s0, s70, 0x80000
	s_addc_u32 s1, s71, 0
	s_mov_b32 m0, s33
	s_nop 0
	global_load_lds_dwordx4 v194, s[0:1]
	s_mov_b32 m0, s40
	s_nop 0
	global_load_lds_dwordx4 v130, s[0:1]
	v_add_u32_e32 v153, s18, v1
	ds_read_b128 v[144:147], v153
	ds_read_b128 v[148:151], v153 offset:1024
	ds_read_b128 v[154:157], v153 offset:2048
	ds_read_b128 v[158:161], v153 offset:3072
	v_add_u32_e32 v153, s19, v1
	ds_read_b128 v[162:165], v153
	ds_read_b128 v[166:169], v153 offset:1024
	ds_read_b128 v[170:173], v153 offset:2048
	ds_read_b128 v[174:177], v153 offset:3072
	ds_read_b128 v[178:181], v152 offset:32768
	ds_read_b128 v[182:185], v152 offset:33792
	ds_read_b128 v[186:189], v152 offset:34816
	ds_read_b128 v[190:193], v152 offset:35840
	ds_read_b128 v[204:207], v152 offset:36864
	ds_read_b128 v[208:211], v152 offset:37888
	ds_read_b128 v[212:215], v152 offset:38912
	ds_read_b128 v[216:219], v152 offset:39936
	s_waitcnt vmcnt(8)
	s_waitcnt lgkmcnt(0)
	s_barrier
	s_setprio 1
	s_waitcnt lgkmcnt(0)
	v_mfma_f32_16x16x32_bf16 v[126:129], v[144:147], v[178:181], v[126:129]
	v_mfma_f32_16x16x32_bf16 v[126:129], v[148:151], v[182:185], v[126:129]
	v_mfma_f32_16x16x32_bf16 v[122:125], v[158:161], v[182:185], v[122:125]
	v_mfma_f32_16x16x32_bf16 v[122:125], v[154:157], v[178:181], v[122:125]
	v_mfma_f32_16x16x32_bf16 v[118:121], v[162:165], v[178:181], v[118:121]
	v_mfma_f32_16x16x32_bf16 v[118:121], v[166:169], v[182:185], v[118:121]
	v_mfma_f32_16x16x32_bf16 v[114:117], v[174:177], v[182:185], v[114:117]
	v_mfma_f32_16x16x32_bf16 v[114:117], v[170:173], v[178:181], v[114:117]
	v_mfma_f32_16x16x32_bf16 v[98:101], v[170:173], v[186:189], v[98:101]
	v_mfma_f32_16x16x32_bf16 v[98:101], v[174:177], v[190:193], v[98:101]
	v_mfma_f32_16x16x32_bf16 v[102:105], v[166:169], v[190:193], v[102:105]
	v_mfma_f32_16x16x32_bf16 v[102:105], v[162:165], v[186:189], v[102:105]
	v_mfma_f32_16x16x32_bf16 v[106:109], v[154:157], v[186:189], v[106:109]
	v_mfma_f32_16x16x32_bf16 v[106:109], v[158:161], v[190:193], v[106:109]
	v_mfma_f32_16x16x32_bf16 v[110:113], v[148:151], v[190:193], v[110:113]
	v_mfma_f32_16x16x32_bf16 v[110:113], v[144:147], v[186:189], v[110:113]
	v_mfma_f32_16x16x32_bf16 v[94:97], v[144:147], v[204:207], v[94:97]
	v_mfma_f32_16x16x32_bf16 v[94:97], v[148:151], v[208:211], v[94:97]
	v_mfma_f32_16x16x32_bf16 v[90:93], v[158:161], v[208:211], v[90:93]
	v_mfma_f32_16x16x32_bf16 v[90:93], v[154:157], v[204:207], v[90:93]
	v_mfma_f32_16x16x32_bf16 v[86:89], v[162:165], v[204:207], v[86:89]
	v_mfma_f32_16x16x32_bf16 v[86:89], v[166:169], v[208:211], v[86:89]
	v_mfma_f32_16x16x32_bf16 v[82:85], v[174:177], v[208:211], v[82:85]
	v_mfma_f32_16x16x32_bf16 v[82:85], v[170:173], v[204:207], v[82:85]
	v_mfma_f32_16x16x32_bf16 v[66:69], v[170:173], v[212:215], v[66:69]
	v_mfma_f32_16x16x32_bf16 v[66:69], v[174:177], v[216:219], v[66:69]
	v_mfma_f32_16x16x32_bf16 v[70:73], v[166:169], v[216:219], v[70:73]
	v_mfma_f32_16x16x32_bf16 v[70:73], v[162:165], v[212:215], v[70:73]
	v_mfma_f32_16x16x32_bf16 v[74:77], v[154:157], v[212:215], v[74:77]
	v_mfma_f32_16x16x32_bf16 v[74:77], v[158:161], v[216:219], v[74:77]
	v_mfma_f32_16x16x32_bf16 v[78:81], v[148:151], v[216:219], v[78:81]
	v_mfma_f32_16x16x32_bf16 v[78:81], v[144:147], v[212:215], v[78:81]
	s_setprio 0
	s_barrier
	s_add_u32 s98, s64, 0x80
	s_addc_u32 s99, s65, 0
	s_add_u32 s100, s70, 0x80
	s_addc_u32 s101, s71, 0
	s_add_i32 s0, s18, s28
	s_mov_b32 m0, s0
	s_nop 0
	global_load_lds_dwordx4 v194, s[98:99]
	s_add_i32 m0, s0, 0x2000
	s_add_u32 s0, s64, 0x80080
	s_addc_u32 s1, s65, 0
	s_add_i32 s18, s19, s28
	global_load_lds_dwordx4 v130, s[98:99]
	s_mov_b32 m0, s18
	s_nop 0
	global_load_lds_dwordx4 v194, s[0:1]
	s_add_i32 m0, s18, 0x2000
	s_nop 0
	global_load_lds_dwordx4 v130, s[0:1]
	s_mov_b32 m0, s54
	s_nop 0
	global_load_lds_dwordx4 v194, s[100:101]
	s_mov_b32 m0, s57
	s_nop 0
	global_load_lds_dwordx4 v130, s[100:101]
	ds_read_b128 v[178:181], v152 offset:49152
	ds_read_b128 v[182:185], v152 offset:50176
	ds_read_b128 v[186:189], v152 offset:51200
	ds_read_b128 v[190:193], v152 offset:52224
	ds_read_b128 v[204:207], v152 offset:53248
	ds_read_b128 v[208:211], v152 offset:54272
	ds_read_b128 v[212:215], v152 offset:55296
	ds_read_b128 v[216:219], v152 offset:56320
	s_waitcnt vmcnt(8)
	s_waitcnt lgkmcnt(0)
	s_barrier
	s_setprio 1
	s_waitcnt lgkmcnt(0)
	v_mfma_f32_16x16x32_bf16 v[62:65], v[144:147], v[178:181], v[62:65]
	v_mfma_f32_16x16x32_bf16 v[62:65], v[148:151], v[182:185], v[62:65]
	v_mfma_f32_16x16x32_bf16 v[58:61], v[158:161], v[182:185], v[58:61]
	v_mfma_f32_16x16x32_bf16 v[58:61], v[154:157], v[178:181], v[58:61]
	v_mfma_f32_16x16x32_bf16 v[54:57], v[162:165], v[178:181], v[54:57]
	v_mfma_f32_16x16x32_bf16 v[54:57], v[166:169], v[182:185], v[54:57]
	v_mfma_f32_16x16x32_bf16 v[50:53], v[174:177], v[182:185], v[50:53]
	v_mfma_f32_16x16x32_bf16 v[50:53], v[170:173], v[178:181], v[50:53]
	v_mfma_f32_16x16x32_bf16 v[34:37], v[170:173], v[186:189], v[34:37]
	v_mfma_f32_16x16x32_bf16 v[34:37], v[174:177], v[190:193], v[34:37]
	v_mfma_f32_16x16x32_bf16 v[38:41], v[166:169], v[190:193], v[38:41]
	v_mfma_f32_16x16x32_bf16 v[38:41], v[162:165], v[186:189], v[38:41]
	v_mfma_f32_16x16x32_bf16 v[42:45], v[154:157], v[186:189], v[42:45]
	v_mfma_f32_16x16x32_bf16 v[42:45], v[158:161], v[190:193], v[42:45]
	v_mfma_f32_16x16x32_bf16 v[46:49], v[148:151], v[190:193], v[46:49]
	v_mfma_f32_16x16x32_bf16 v[46:49], v[144:147], v[186:189], v[46:49]
	v_mfma_f32_16x16x32_bf16 v[30:33], v[144:147], v[204:207], v[30:33]
	v_mfma_f32_16x16x32_bf16 v[30:33], v[148:151], v[208:211], v[30:33]
	v_mfma_f32_16x16x32_bf16 v[26:29], v[158:161], v[208:211], v[26:29]
	v_mfma_f32_16x16x32_bf16 v[26:29], v[154:157], v[204:207], v[26:29]
	v_mfma_f32_16x16x32_bf16 v[22:25], v[162:165], v[204:207], v[22:25]
	v_mfma_f32_16x16x32_bf16 v[22:25], v[166:169], v[208:211], v[22:25]
	v_mfma_f32_16x16x32_bf16 v[18:21], v[174:177], v[208:211], v[18:21]
	v_mfma_f32_16x16x32_bf16 v[18:21], v[170:173], v[204:207], v[18:21]
	v_mfma_f32_16x16x32_bf16 v[2:5], v[170:173], v[212:215], v[2:5]
	v_mfma_f32_16x16x32_bf16 v[2:5], v[174:177], v[216:219], v[2:5]
	v_mfma_f32_16x16x32_bf16 v[6:9], v[166:169], v[216:219], v[6:9]
	v_mfma_f32_16x16x32_bf16 v[6:9], v[162:165], v[212:215], v[6:9]
	v_mfma_f32_16x16x32_bf16 v[10:13], v[154:157], v[212:215], v[10:13]
	v_mfma_f32_16x16x32_bf16 v[10:13], v[158:161], v[216:219], v[10:13]
	v_mfma_f32_16x16x32_bf16 v[14:17], v[148:151], v[216:219], v[14:17]
	v_mfma_f32_16x16x32_bf16 v[14:17], v[144:147], v[212:215], v[14:17]
	s_setprio 0
	s_barrier
	s_add_i32 s76, s76, 2
	s_add_u32 s62, s62, 0x100
	s_addc_u32 s63, s63, 0
	s_add_u32 s53, s53, 0x100
	s_addc_u32 s58, s58, 0
	s_cmp_gt_u32 s76, 29
	s_cbranch_scc1 .LBB0_584

.Lpeel_disp_gu:
	s_cmp_lg_u32 s76, -2
	s_cbranch_scc1 .LBB0_581
	s_add_u32 s18, s62, 0xfff80080
	s_addc_u32 s19, s63, -1
	s_and_b64 s[0:1], s[64:65], exec
	s_cselect_b32 s71, s22, s19
	s_cselect_b32 s70, s23, s18
	s_cselect_b32 s65, s39, s58
	s_cselect_b32 s64, s47, s53
	s_add_i32 s0, 0, 0x10000
	s_add_i32 s18, 0, 0x14000
	s_add_i32 m0, s29, 0xc000
	s_nop 0
	global_load_lds_dwordx4 v136, s[62:63]
	s_add_i32 m0, s29, 0xe000
	s_nop 0
	global_load_lds_dwordx4 v138, s[62:63]
	v_add_u32_e32 v153, s0, v1
	ds_read_b128 v[144:147], v153
	ds_read_b128 v[148:151], v153 offset:1024
	ds_read_b128 v[154:157], v153 offset:2048
	ds_read_b128 v[158:161], v153 offset:3072
	v_add_u32_e32 v153, s18, v1
	ds_read_b128 v[162:165], v153
	ds_read_b128 v[166:169], v153 offset:1024
	ds_read_b128 v[170:173], v153 offset:2048
	ds_read_b128 v[174:177], v153 offset:3072
	ds_read_b128 v[178:181], v152
	ds_read_b128 v[182:185], v152 offset:1024
	ds_read_b128 v[186:189], v152 offset:2048
	ds_read_b128 v[190:193], v152 offset:3072
	ds_read_b128 v[204:207], v152 offset:4096
	ds_read_b128 v[208:211], v152 offset:5120
	ds_read_b128 v[212:215], v152 offset:6144
	ds_read_b128 v[216:219], v152 offset:7168
	s_waitcnt vmcnt(8)
	s_waitcnt lgkmcnt(0)
	s_barrier
	s_setprio 1
	s_waitcnt lgkmcnt(0)
	v_mfma_f32_16x16x32_bf16 v[126:129], v[144:147], v[178:181], 0
	v_mfma_f32_16x16x32_bf16 v[126:129], v[148:151], v[182:185], v[126:129]
	v_mfma_f32_16x16x32_bf16 v[122:125], v[158:161], v[182:185], 0
	v_mfma_f32_16x16x32_bf16 v[122:125], v[154:157], v[178:181], v[122:125]
	v_mfma_f32_16x16x32_bf16 v[118:121], v[162:165], v[178:181], 0
	v_mfma_f32_16x16x32_bf16 v[118:121], v[166:169], v[182:185], v[118:121]
	v_mfma_f32_16x16x32_bf16 v[114:117], v[174:177], v[182:185], 0
	v_mfma_f32_16x16x32_bf16 v[114:117], v[170:173], v[178:181], v[114:117]
	v_mfma_f32_16x16x32_bf16 v[98:101], v[170:173], v[186:189], 0
	v_mfma_f32_16x16x32_bf16 v[98:101], v[174:177], v[190:193], v[98:101]
	v_mfma_f32_16x16x32_bf16 v[102:105], v[166:169], v[190:193], 0
	v_mfma_f32_16x16x32_bf16 v[102:105], v[162:165], v[186:189], v[102:105]
	v_mfma_f32_16x16x32_bf16 v[106:109], v[154:157], v[186:189], 0
	v_mfma_f32_16x16x32_bf16 v[106:109], v[158:161], v[190:193], v[106:109]
	v_mfma_f32_16x16x32_bf16 v[110:113], v[148:151], v[190:193], 0
	v_mfma_f32_16x16x32_bf16 v[110:113], v[144:147], v[186:189], v[110:113]
	v_mfma_f32_16x16x32_bf16 v[94:97], v[144:147], v[204:207], 0
	v_mfma_f32_16x16x32_bf16 v[94:97], v[148:151], v[208:211], v[94:97]
	v_mfma_f32_16x16x32_bf16 v[90:93], v[158:161], v[208:211], 0
	v_mfma_f32_16x16x32_bf16 v[90:93], v[154:157], v[204:207], v[90:93]
	v_mfma_f32_16x16x32_bf16 v[86:89], v[162:165], v[204:207], 0
	v_mfma_f32_16x16x32_bf16 v[86:89], v[166:169], v[208:211], v[86:89]
	v_mfma_f32_16x16x32_bf16 v[82:85], v[174:177], v[208:211], 0
	v_mfma_f32_16x16x32_bf16 v[82:85], v[170:173], v[204:207], v[82:85]
	v_mfma_f32_16x16x32_bf16 v[66:69], v[170:173], v[212:215], 0
	v_mfma_f32_16x16x32_bf16 v[66:69], v[174:177], v[216:219], v[66:69]
	v_mfma_f32_16x16x32_bf16 v[70:73], v[166:169], v[216:219], 0
	v_mfma_f32_16x16x32_bf16 v[70:73], v[162:165], v[212:215], v[70:73]
	v_mfma_f32_16x16x32_bf16 v[74:77], v[154:157], v[212:215], 0
	v_mfma_f32_16x16x32_bf16 v[74:77], v[158:161], v[216:219], v[74:77]
	v_mfma_f32_16x16x32_bf16 v[78:81], v[148:151], v[216:219], 0
	v_mfma_f32_16x16x32_bf16 v[78:81], v[144:147], v[212:215], v[78:81]
	s_setprio 0
	s_barrier
	s_add_i32 s0, s0, s28
	s_mov_b32 m0, s0
	s_nop 0
	global_load_lds_dwordx4 v194, s[64:65]
	s_add_i32 m0, s0, 0x2000
	s_add_u32 s0, s64, 0x80000
	s_addc_u32 s1, s65, 0
	s_add_i32 s18, s18, s28
	global_load_lds_dwordx4 v130, s[64:65]
	s_mov_b32 m0, s18
	s_nop 0
	global_load_lds_dwordx4 v194, s[0:1]
	s_add_i32 m0, s18, 0x2000
	s_nop 0
	global_load_lds_dwordx4 v130, s[0:1]
	s_mov_b32 m0, s29
	s_nop 0
	global_load_lds_dwordx4 v194, s[70:71]
	s_mov_b32 m0, s31
	s_nop 0
	global_load_lds_dwordx4 v130, s[70:71]
	ds_read_b128 v[178:181], v152 offset:16384
	ds_read_b128 v[182:185], v152 offset:17408
	ds_read_b128 v[186:189], v152 offset:18432
	ds_read_b128 v[190:193], v152 offset:19456
	ds_read_b128 v[204:207], v152 offset:20480
	ds_read_b128 v[208:211], v152 offset:21504
	ds_read_b128 v[212:215], v152 offset:22528
	ds_read_b128 v[216:219], v152 offset:23552
	s_waitcnt vmcnt(8)
	s_waitcnt lgkmcnt(0)
	s_barrier
	s_setprio 1
	s_waitcnt lgkmcnt(0)
	v_mfma_f32_16x16x32_bf16 v[62:65], v[144:147], v[178:181], 0
	v_mfma_f32_16x16x32_bf16 v[62:65], v[148:151], v[182:185], v[62:65]
	v_mfma_f32_16x16x32_bf16 v[58:61], v[158:161], v[182:185], 0
	v_mfma_f32_16x16x32_bf16 v[58:61], v[154:157], v[178:181], v[58:61]
	v_mfma_f32_16x16x32_bf16 v[54:57], v[162:165], v[178:181], 0
	v_mfma_f32_16x16x32_bf16 v[54:57], v[166:169], v[182:185], v[54:57]
	v_mfma_f32_16x16x32_bf16 v[50:53], v[174:177], v[182:185], 0
	v_mfma_f32_16x16x32_bf16 v[50:53], v[170:173], v[178:181], v[50:53]
	v_mfma_f32_16x16x32_bf16 v[34:37], v[170:173], v[186:189], 0
	v_mfma_f32_16x16x32_bf16 v[34:37], v[174:177], v[190:193], v[34:37]
	v_mfma_f32_16x16x32_bf16 v[38:41], v[166:169], v[190:193], 0
	v_mfma_f32_16x16x32_bf16 v[38:41], v[162:165], v[186:189], v[38:41]
	v_mfma_f32_16x16x32_bf16 v[42:45], v[154:157], v[186:189], 0
	v_mfma_f32_16x16x32_bf16 v[42:45], v[158:161], v[190:193], v[42:45]
	v_mfma_f32_16x16x32_bf16 v[46:49], v[148:151], v[190:193], 0
	v_mfma_f32_16x16x32_bf16 v[46:49], v[144:147], v[186:189], v[46:49]
	v_mfma_f32_16x16x32_bf16 v[30:33], v[144:147], v[204:207], 0
	v_mfma_f32_16x16x32_bf16 v[30:33], v[148:151], v[208:211], v[30:33]
	v_mfma_f32_16x16x32_bf16 v[26:29], v[158:161], v[208:211], 0
	v_mfma_f32_16x16x32_bf16 v[26:29], v[154:157], v[204:207], v[26:29]
	v_mfma_f32_16x16x32_bf16 v[22:25], v[162:165], v[204:207], 0
	v_mfma_f32_16x16x32_bf16 v[22:25], v[166:169], v[208:211], v[22:25]
	v_mfma_f32_16x16x32_bf16 v[18:21], v[174:177], v[208:211], 0
	v_mfma_f32_16x16x32_bf16 v[18:21], v[170:173], v[204:207], v[18:21]
	v_mfma_f32_16x16x32_bf16 v[2:5], v[170:173], v[212:215], 0
	v_mfma_f32_16x16x32_bf16 v[2:5], v[174:177], v[216:219], v[2:5]
	v_mfma_f32_16x16x32_bf16 v[6:9], v[166:169], v[216:219], 0
	v_mfma_f32_16x16x32_bf16 v[6:9], v[162:165], v[212:215], v[6:9]
	v_mfma_f32_16x16x32_bf16 v[10:13], v[154:157], v[212:215], 0
	v_mfma_f32_16x16x32_bf16 v[10:13], v[158:161], v[216:219], v[10:13]
	v_mfma_f32_16x16x32_bf16 v[14:17], v[148:151], v[216:219], 0
	v_mfma_f32_16x16x32_bf16 v[14:17], v[144:147], v[212:215], v[14:17]
	s_setprio 0
	s_barrier
	s_add_i32 s18, 0, 0x18000
	s_add_i32 s19, 0, 0x1c000
	s_add_u32 s0, s70, 0x80000
	s_addc_u32 s1, s71, 0
	s_mov_b32 m0, s33
	s_nop 0
	global_load_lds_dwordx4 v194, s[0:1]
	s_mov_b32 m0, s40
	s_nop 0
	global_load_lds_dwordx4 v130, s[0:1]
	v_add_u32_e32 v153, s18, v1
	ds_read_b128 v[144:147], v153
	ds_read_b128 v[148:151], v153 offset:1024
	ds_read_b128 v[154:157], v153 offset:2048
	ds_read_b128 v[158:161], v153 offset:3072
	v_add_u32_e32 v153, s19, v1
	ds_read_b128 v[162:165], v153
	ds_read_b128 v[166:169], v153 offset:1024
	ds_read_b128 v[170:173], v153 offset:2048
	ds_read_b128 v[174:177], v153 offset:3072
	ds_read_b128 v[178:181], v152 offset:32768
	ds_read_b128 v[182:185], v152 offset:33792
	ds_read_b128 v[186:189], v152 offset:34816
	ds_read_b128 v[190:193], v152 offset:35840
	ds_read_b128 v[204:207], v152 offset:36864
	ds_read_b128 v[208:211], v152 offset:37888
	ds_read_b128 v[212:215], v152 offset:38912
	ds_read_b128 v[216:219], v152 offset:39936
	s_waitcnt vmcnt(8)
	s_waitcnt lgkmcnt(0)
	s_barrier
	s_setprio 1
	s_waitcnt lgkmcnt(0)
	v_mfma_f32_16x16x32_bf16 v[126:129], v[144:147], v[178:181], v[126:129]
	v_mfma_f32_16x16x32_bf16 v[126:129], v[148:151], v[182:185], v[126:129]
	v_mfma_f32_16x16x32_bf16 v[122:125], v[158:161], v[182:185], v[122:125]
	v_mfma_f32_16x16x32_bf16 v[122:125], v[154:157], v[178:181], v[122:125]
	v_mfma_f32_16x16x32_bf16 v[118:121], v[162:165], v[178:181], v[118:121]
	v_mfma_f32_16x16x32_bf16 v[118:121], v[166:169], v[182:185], v[118:121]
	v_mfma_f32_16x16x32_bf16 v[114:117], v[174:177], v[182:185], v[114:117]
	v_mfma_f32_16x16x32_bf16 v[114:117], v[170:173], v[178:181], v[114:117]
	v_mfma_f32_16x16x32_bf16 v[98:101], v[170:173], v[186:189], v[98:101]
	v_mfma_f32_16x16x32_bf16 v[98:101], v[174:177], v[190:193], v[98:101]
	v_mfma_f32_16x16x32_bf16 v[102:105], v[166:169], v[190:193], v[102:105]
	v_mfma_f32_16x16x32_bf16 v[102:105], v[162:165], v[186:189], v[102:105]
	v_mfma_f32_16x16x32_bf16 v[106:109], v[154:157], v[186:189], v[106:109]
	v_mfma_f32_16x16x32_bf16 v[106:109], v[158:161], v[190:193], v[106:109]
	v_mfma_f32_16x16x32_bf16 v[110:113], v[148:151], v[190:193], v[110:113]
	v_mfma_f32_16x16x32_bf16 v[110:113], v[144:147], v[186:189], v[110:113]
	v_mfma_f32_16x16x32_bf16 v[94:97], v[144:147], v[204:207], v[94:97]
	v_mfma_f32_16x16x32_bf16 v[94:97], v[148:151], v[208:211], v[94:97]
	v_mfma_f32_16x16x32_bf16 v[90:93], v[158:161], v[208:211], v[90:93]
	v_mfma_f32_16x16x32_bf16 v[90:93], v[154:157], v[204:207], v[90:93]
	v_mfma_f32_16x16x32_bf16 v[86:89], v[162:165], v[204:207], v[86:89]
	v_mfma_f32_16x16x32_bf16 v[86:89], v[166:169], v[208:211], v[86:89]
	v_mfma_f32_16x16x32_bf16 v[82:85], v[174:177], v[208:211], v[82:85]
	v_mfma_f32_16x16x32_bf16 v[82:85], v[170:173], v[204:207], v[82:85]
	v_mfma_f32_16x16x32_bf16 v[66:69], v[170:173], v[212:215], v[66:69]
	v_mfma_f32_16x16x32_bf16 v[66:69], v[174:177], v[216:219], v[66:69]
	v_mfma_f32_16x16x32_bf16 v[70:73], v[166:169], v[216:219], v[70:73]
	v_mfma_f32_16x16x32_bf16 v[70:73], v[162:165], v[212:215], v[70:73]
	v_mfma_f32_16x16x32_bf16 v[74:77], v[154:157], v[212:215], v[74:77]
	v_mfma_f32_16x16x32_bf16 v[74:77], v[158:161], v[216:219], v[74:77]
	v_mfma_f32_16x16x32_bf16 v[78:81], v[148:151], v[216:219], v[78:81]
	v_mfma_f32_16x16x32_bf16 v[78:81], v[144:147], v[212:215], v[78:81]
	s_setprio 0
	s_barrier
	s_add_u32 s98, s64, 0x80
	s_addc_u32 s99, s65, 0
	s_add_u32 s100, s70, 0x80
	s_addc_u32 s101, s71, 0
	s_add_i32 s0, s18, s28
	s_mov_b32 m0, s0
	s_nop 0
	global_load_lds_dwordx4 v194, s[98:99]
	s_add_i32 m0, s0, 0x2000
	s_add_u32 s0, s64, 0x80080
	s_addc_u32 s1, s65, 0
	s_add_i32 s18, s19, s28
	global_load_lds_dwordx4 v130, s[98:99]
	s_mov_b32 m0, s18
	s_nop 0
	global_load_lds_dwordx4 v194, s[0:1]
	s_add_i32 m0, s18, 0x2000
	s_nop 0
	global_load_lds_dwordx4 v130, s[0:1]
	s_mov_b32 m0, s54
	s_nop 0
	global_load_lds_dwordx4 v194, s[100:101]
	s_mov_b32 m0, s57
	s_nop 0
	global_load_lds_dwordx4 v130, s[100:101]
	ds_read_b128 v[178:181], v152 offset:49152
	ds_read_b128 v[182:185], v152 offset:50176
	ds_read_b128 v[186:189], v152 offset:51200
	ds_read_b128 v[190:193], v152 offset:52224
	ds_read_b128 v[204:207], v152 offset:53248
	ds_read_b128 v[208:211], v152 offset:54272
	ds_read_b128 v[212:215], v152 offset:55296
	ds_read_b128 v[216:219], v152 offset:56320
	s_waitcnt vmcnt(8)
	s_waitcnt lgkmcnt(0)
	s_barrier
	s_setprio 1
	s_waitcnt lgkmcnt(0)
	v_mfma_f32_16x16x32_bf16 v[62:65], v[144:147], v[178:181], v[62:65]
	v_mfma_f32_16x16x32_bf16 v[62:65], v[148:151], v[182:185], v[62:65]
	v_mfma_f32_16x16x32_bf16 v[58:61], v[158:161], v[182:185], v[58:61]
	v_mfma_f32_16x16x32_bf16 v[58:61], v[154:157], v[178:181], v[58:61]
	v_mfma_f32_16x16x32_bf16 v[54:57], v[162:165], v[178:181], v[54:57]
	v_mfma_f32_16x16x32_bf16 v[54:57], v[166:169], v[182:185], v[54:57]
	v_mfma_f32_16x16x32_bf16 v[50:53], v[174:177], v[182:185], v[50:53]
	v_mfma_f32_16x16x32_bf16 v[50:53], v[170:173], v[178:181], v[50:53]
	v_mfma_f32_16x16x32_bf16 v[34:37], v[170:173], v[186:189], v[34:37]
	v_mfma_f32_16x16x32_bf16 v[34:37], v[174:177], v[190:193], v[34:37]
	v_mfma_f32_16x16x32_bf16 v[38:41], v[166:169], v[190:193], v[38:41]
	v_mfma_f32_16x16x32_bf16 v[38:41], v[162:165], v[186:189], v[38:41]
	v_mfma_f32_16x16x32_bf16 v[42:45], v[154:157], v[186:189], v[42:45]
	v_mfma_f32_16x16x32_bf16 v[42:45], v[158:161], v[190:193], v[42:45]
	v_mfma_f32_16x16x32_bf16 v[46:49], v[148:151], v[190:193], v[46:49]
	v_mfma_f32_16x16x32_bf16 v[46:49], v[144:147], v[186:189], v[46:49]
	v_mfma_f32_16x16x32_bf16 v[30:33], v[144:147], v[204:207], v[30:33]
	v_mfma_f32_16x16x32_bf16 v[30:33], v[148:151], v[208:211], v[30:33]
	v_mfma_f32_16x16x32_bf16 v[26:29], v[158:161], v[208:211], v[26:29]
	v_mfma_f32_16x16x32_bf16 v[26:29], v[154:157], v[204:207], v[26:29]
	v_mfma_f32_16x16x32_bf16 v[22:25], v[162:165], v[204:207], v[22:25]
	v_mfma_f32_16x16x32_bf16 v[22:25], v[166:169], v[208:211], v[22:25]
	v_mfma_f32_16x16x32_bf16 v[18:21], v[174:177], v[208:211], v[18:21]
	v_mfma_f32_16x16x32_bf16 v[18:21], v[170:173], v[204:207], v[18:21]
	v_mfma_f32_16x16x32_bf16 v[2:5], v[170:173], v[212:215], v[2:5]
	v_mfma_f32_16x16x32_bf16 v[2:5], v[174:177], v[216:219], v[2:5]
	v_mfma_f32_16x16x32_bf16 v[6:9], v[166:169], v[216:219], v[6:9]
	v_mfma_f32_16x16x32_bf16 v[6:9], v[162:165], v[212:215], v[6:9]
	v_mfma_f32_16x16x32_bf16 v[10:13], v[154:157], v[212:215], v[10:13]
	v_mfma_f32_16x16x32_bf16 v[10:13], v[158:161], v[216:219], v[10:13]
	v_mfma_f32_16x16x32_bf16 v[14:17], v[148:151], v[216:219], v[14:17]
	v_mfma_f32_16x16x32_bf16 v[14:17], v[144:147], v[212:215], v[14:17]
	s_setprio 0
	s_barrier
	s_add_i32 s76, s76, 2
	s_add_u32 s62, s62, 0x100
	s_addc_u32 s63, s63, 0
	s_add_u32 s53, s53, 0x100
	s_addc_u32 s58, s58, 0
	s_cmp_gt_u32 s76, 29
	s_cbranch_scc1 .LBB0_584
	s_branch .LBB0_582

.LBB0_645:
	s_add_u32 s64, s8, 0x100
	s_addc_u32 s65, s9, 0
	s_and_b64 s[0:1], s[70:71], exec
	s_cselect_b32 s77, s63, s65
	s_cselect_b32 s76, s62, s64
	s_cselect_b32 s71, s85, s23
	s_cselect_b32 s70, s84, s7
	s_add_i32 s0, 0, 0x10000
	s_add_i32 s18, 0, 0x14000
	s_add_i32 m0, s29, 0xc000
	s_nop 0
	global_load_lds_dwordx4 v206, s[8:9]
	s_add_i32 m0, s29, 0xe000
	s_nop 0
	global_load_lds_dwordx4 v208, s[8:9]
	v_add_u32_e32 v106, s0, v1
	v_add_u32_e32 v154, s18, v1
	ds_read_b128 v[70:73], v106
	ds_read_b128 v[82:85], v106 offset:1024
	ds_read_b128 v[94:97], v106 offset:2048
	ds_read_b128 v[106:109], v106 offset:3072
	ds_read_b128 v[118:121], v154
	ds_read_b128 v[130:133], v154 offset:1024
	ds_read_b128 v[142:145], v154 offset:2048
	ds_read_b128 v[154:157], v154 offset:3072
	ds_read_b128 v[158:161], v237
	ds_read_b128 v[170:173], v237 offset:1024
	ds_read_b128 v[174:177], v237 offset:2048
	ds_read_b128 v[178:181], v237 offset:3072
	ds_read_b128 v[182:185], v237 offset:4096
	ds_read_b128 v[186:189], v237 offset:5120
	ds_read_b128 v[210:213], v237 offset:6144
	ds_read_b128 v[214:217], v237 offset:7168
	s_waitcnt vmcnt(8)
	s_waitcnt lgkmcnt(0)
	s_barrier
	s_setprio 1
	s_waitcnt lgkmcnt(0)
	v_mfma_f32_16x16x32_bf16 v[166:169], v[70:73], v[158:161], v[166:169]
	v_mfma_f32_16x16x32_bf16 v[166:169], v[82:85], v[170:173], v[166:169]
	v_mfma_f32_16x16x32_bf16 v[162:165], v[106:109], v[170:173], v[162:165]
	v_mfma_f32_16x16x32_bf16 v[162:165], v[94:97], v[158:161], v[162:165]
	v_mfma_f32_16x16x32_bf16 v[150:153], v[118:121], v[158:161], v[150:153]
	v_mfma_f32_16x16x32_bf16 v[150:153], v[130:133], v[170:173], v[150:153]
	v_mfma_f32_16x16x32_bf16 v[146:149], v[154:157], v[170:173], v[146:149]
	v_mfma_f32_16x16x32_bf16 v[146:149], v[142:145], v[158:161], v[146:149]
	v_mfma_f32_16x16x32_bf16 v[122:125], v[142:145], v[174:177], v[122:125]
	v_mfma_f32_16x16x32_bf16 v[122:125], v[154:157], v[178:181], v[122:125]
	v_mfma_f32_16x16x32_bf16 v[126:129], v[130:133], v[178:181], v[126:129]
	v_mfma_f32_16x16x32_bf16 v[126:129], v[118:121], v[174:177], v[126:129]
	v_mfma_f32_16x16x32_bf16 v[134:137], v[94:97], v[174:177], v[134:137]
	v_mfma_f32_16x16x32_bf16 v[134:137], v[106:109], v[178:181], v[134:137]
	v_mfma_f32_16x16x32_bf16 v[138:141], v[82:85], v[178:181], v[138:141]
	v_mfma_f32_16x16x32_bf16 v[138:141], v[70:73], v[174:177], v[138:141]
	v_mfma_f32_16x16x32_bf16 v[114:117], v[70:73], v[182:185], v[114:117]
	v_mfma_f32_16x16x32_bf16 v[114:117], v[82:85], v[186:189], v[114:117]
	v_mfma_f32_16x16x32_bf16 v[110:113], v[106:109], v[186:189], v[110:113]
	v_mfma_f32_16x16x32_bf16 v[110:113], v[94:97], v[182:185], v[110:113]
	v_mfma_f32_16x16x32_bf16 v[102:105], v[118:121], v[182:185], v[102:105]
	v_mfma_f32_16x16x32_bf16 v[102:105], v[130:133], v[186:189], v[102:105]
	v_mfma_f32_16x16x32_bf16 v[98:101], v[154:157], v[186:189], v[98:101]
	v_mfma_f32_16x16x32_bf16 v[98:101], v[142:145], v[182:185], v[98:101]
	v_mfma_f32_16x16x32_bf16 v[74:77], v[142:145], v[210:213], v[74:77]
	v_mfma_f32_16x16x32_bf16 v[74:77], v[154:157], v[214:217], v[74:77]
	v_mfma_f32_16x16x32_bf16 v[78:81], v[130:133], v[214:217], v[78:81]
	v_mfma_f32_16x16x32_bf16 v[78:81], v[118:121], v[210:213], v[78:81]
	v_mfma_f32_16x16x32_bf16 v[86:89], v[94:97], v[210:213], v[86:89]
	v_mfma_f32_16x16x32_bf16 v[86:89], v[106:109], v[214:217], v[86:89]
	v_mfma_f32_16x16x32_bf16 v[90:93], v[82:85], v[214:217], v[90:93]
	v_mfma_f32_16x16x32_bf16 v[90:93], v[70:73], v[210:213], v[90:93]
	s_setprio 0
	s_barrier
	s_add_i32 s0, s0, s28
	s_mov_b32 m0, s0
	s_nop 0
	global_load_lds_dwordx4 v192, s[70:71]
	s_add_i32 m0, s0, 0x2000
	s_add_u32 s0, s70, 0x160000
	s_addc_u32 s1, s71, 0
	s_add_i32 s8, s18, s28
	global_load_lds_dwordx4 v190, s[70:71]
	s_mov_b32 m0, s8
	s_nop 0
	global_load_lds_dwordx4 v192, s[0:1]
	s_add_i32 m0, s8, 0x2000
	s_nop 0
	global_load_lds_dwordx4 v190, s[0:1]
	s_mov_b32 m0, s29
	s_nop 0
	global_load_lds_dwordx4 v192, s[76:77]
	s_mov_b32 m0, s31
	s_nop 0
	global_load_lds_dwordx4 v190, s[76:77]
	ds_read_b128 v[158:161], v237 offset:16384
	ds_read_b128 v[170:173], v237 offset:17408
	ds_read_b128 v[174:177], v237 offset:18432
	ds_read_b128 v[178:181], v237 offset:19456
	ds_read_b128 v[182:185], v237 offset:20480
	ds_read_b128 v[186:189], v237 offset:21504
	ds_read_b128 v[210:213], v237 offset:22528
	ds_read_b128 v[214:217], v237 offset:23552
	s_waitcnt vmcnt(8)
	s_waitcnt lgkmcnt(0)
	s_barrier
	s_setprio 1
	s_waitcnt lgkmcnt(0)
	v_mfma_f32_16x16x32_bf16 v[62:65], v[70:73], v[158:161], v[62:65]
	v_mfma_f32_16x16x32_bf16 v[62:65], v[82:85], v[170:173], v[62:65]
	v_mfma_f32_16x16x32_bf16 v[58:61], v[106:109], v[170:173], v[58:61]
	v_mfma_f32_16x16x32_bf16 v[58:61], v[94:97], v[158:161], v[58:61]
	v_mfma_f32_16x16x32_bf16 v[54:57], v[118:121], v[158:161], v[54:57]
	v_mfma_f32_16x16x32_bf16 v[54:57], v[130:133], v[170:173], v[54:57]
	v_mfma_f32_16x16x32_bf16 v[50:53], v[154:157], v[170:173], v[50:53]
	v_mfma_f32_16x16x32_bf16 v[50:53], v[142:145], v[158:161], v[50:53]
	v_mfma_f32_16x16x32_bf16 v[34:37], v[142:145], v[174:177], v[34:37]
	v_mfma_f32_16x16x32_bf16 v[34:37], v[154:157], v[178:181], v[34:37]
	v_mfma_f32_16x16x32_bf16 v[38:41], v[130:133], v[178:181], v[38:41]
	v_mfma_f32_16x16x32_bf16 v[38:41], v[118:121], v[174:177], v[38:41]
	v_mfma_f32_16x16x32_bf16 v[42:45], v[94:97], v[174:177], v[42:45]
	v_mfma_f32_16x16x32_bf16 v[42:45], v[106:109], v[178:181], v[42:45]
	v_mfma_f32_16x16x32_bf16 v[46:49], v[82:85], v[178:181], v[46:49]
	v_mfma_f32_16x16x32_bf16 v[46:49], v[70:73], v[174:177], v[46:49]
	v_mfma_f32_16x16x32_bf16 v[30:33], v[70:73], v[182:185], v[30:33]
	v_mfma_f32_16x16x32_bf16 v[30:33], v[82:85], v[186:189], v[30:33]
	v_mfma_f32_16x16x32_bf16 v[26:29], v[106:109], v[186:189], v[26:29]
	v_mfma_f32_16x16x32_bf16 v[26:29], v[94:97], v[182:185], v[26:29]
	v_mfma_f32_16x16x32_bf16 v[22:25], v[118:121], v[182:185], v[22:25]
	v_mfma_f32_16x16x32_bf16 v[22:25], v[130:133], v[186:189], v[22:25]
	v_mfma_f32_16x16x32_bf16 v[18:21], v[154:157], v[186:189], v[18:21]
	v_mfma_f32_16x16x32_bf16 v[18:21], v[142:145], v[182:185], v[18:21]
	v_mfma_f32_16x16x32_bf16 v[2:5], v[142:145], v[210:213], v[2:5]
	v_mfma_f32_16x16x32_bf16 v[2:5], v[154:157], v[214:217], v[2:5]
	v_mfma_f32_16x16x32_bf16 v[6:9], v[130:133], v[214:217], v[6:9]
	v_mfma_f32_16x16x32_bf16 v[6:9], v[118:121], v[210:213], v[6:9]
	v_mfma_f32_16x16x32_bf16 v[10:13], v[94:97], v[210:213], v[10:13]
	v_mfma_f32_16x16x32_bf16 v[10:13], v[106:109], v[214:217], v[10:13]
	v_mfma_f32_16x16x32_bf16 v[14:17], v[82:85], v[214:217], v[14:17]
	v_mfma_f32_16x16x32_bf16 v[14:17], v[70:73], v[210:213], v[14:17]
	s_setprio 0
	s_barrier
	s_add_i32 s8, 0, 0x18000
	s_add_i32 s9, 0, 0x1c000
	s_add_u32 s0, s76, 0x160000
	s_addc_u32 s1, s77, 0
	s_mov_b32 m0, s33
	s_nop 0
	global_load_lds_dwordx4 v192, s[0:1]
	s_mov_b32 m0, s43
	s_nop 0
	global_load_lds_dwordx4 v190, s[0:1]
	v_add_u32_e32 v106, s8, v1
	v_add_u32_e32 v154, s9, v1
	ds_read_b128 v[70:73], v106
	ds_read_b128 v[82:85], v106 offset:1024
	ds_read_b128 v[94:97], v106 offset:2048
	ds_read_b128 v[106:109], v106 offset:3072
	ds_read_b128 v[118:121], v154
	ds_read_b128 v[130:133], v154 offset:1024
	ds_read_b128 v[142:145], v154 offset:2048
	ds_read_b128 v[154:157], v154 offset:3072
	ds_read_b128 v[158:161], v237 offset:32768
	ds_read_b128 v[170:173], v237 offset:33792
	ds_read_b128 v[174:177], v237 offset:34816
	ds_read_b128 v[178:181], v237 offset:35840
	ds_read_b128 v[182:185], v237 offset:36864
	ds_read_b128 v[186:189], v237 offset:37888
	ds_read_b128 v[210:213], v237 offset:38912
	ds_read_b128 v[214:217], v237 offset:39936
	s_waitcnt vmcnt(8)
	s_waitcnt lgkmcnt(0)
	s_barrier
	s_setprio 1
	s_waitcnt lgkmcnt(0)
	v_mfma_f32_16x16x32_bf16 v[166:169], v[70:73], v[158:161], v[166:169]
	v_mfma_f32_16x16x32_bf16 v[166:169], v[82:85], v[170:173], v[166:169]
	v_mfma_f32_16x16x32_bf16 v[162:165], v[106:109], v[170:173], v[162:165]
	v_mfma_f32_16x16x32_bf16 v[162:165], v[94:97], v[158:161], v[162:165]
	v_mfma_f32_16x16x32_bf16 v[150:153], v[118:121], v[158:161], v[150:153]
	v_mfma_f32_16x16x32_bf16 v[150:153], v[130:133], v[170:173], v[150:153]
	v_mfma_f32_16x16x32_bf16 v[146:149], v[154:157], v[170:173], v[146:149]
	v_mfma_f32_16x16x32_bf16 v[146:149], v[142:145], v[158:161], v[146:149]
	v_mfma_f32_16x16x32_bf16 v[122:125], v[142:145], v[174:177], v[122:125]
	v_mfma_f32_16x16x32_bf16 v[122:125], v[154:157], v[178:181], v[122:125]
	v_mfma_f32_16x16x32_bf16 v[126:129], v[130:133], v[178:181], v[126:129]
	v_mfma_f32_16x16x32_bf16 v[126:129], v[118:121], v[174:177], v[126:129]
	v_mfma_f32_16x16x32_bf16 v[134:137], v[94:97], v[174:177], v[134:137]
	v_mfma_f32_16x16x32_bf16 v[134:137], v[106:109], v[178:181], v[134:137]
	v_mfma_f32_16x16x32_bf16 v[138:141], v[82:85], v[178:181], v[138:141]
	v_mfma_f32_16x16x32_bf16 v[138:141], v[70:73], v[174:177], v[138:141]
	v_mfma_f32_16x16x32_bf16 v[114:117], v[70:73], v[182:185], v[114:117]
	v_mfma_f32_16x16x32_bf16 v[114:117], v[82:85], v[186:189], v[114:117]
	v_mfma_f32_16x16x32_bf16 v[110:113], v[106:109], v[186:189], v[110:113]
	v_mfma_f32_16x16x32_bf16 v[110:113], v[94:97], v[182:185], v[110:113]
	v_mfma_f32_16x16x32_bf16 v[102:105], v[118:121], v[182:185], v[102:105]
	v_mfma_f32_16x16x32_bf16 v[102:105], v[130:133], v[186:189], v[102:105]
	v_mfma_f32_16x16x32_bf16 v[98:101], v[154:157], v[186:189], v[98:101]
	v_mfma_f32_16x16x32_bf16 v[98:101], v[142:145], v[182:185], v[98:101]
	v_mfma_f32_16x16x32_bf16 v[74:77], v[142:145], v[210:213], v[74:77]
	v_mfma_f32_16x16x32_bf16 v[74:77], v[154:157], v[214:217], v[74:77]
	v_mfma_f32_16x16x32_bf16 v[78:81], v[130:133], v[214:217], v[78:81]
	v_mfma_f32_16x16x32_bf16 v[78:81], v[118:121], v[210:213], v[78:81]
	v_mfma_f32_16x16x32_bf16 v[86:89], v[94:97], v[210:213], v[86:89]
	v_mfma_f32_16x16x32_bf16 v[86:89], v[106:109], v[214:217], v[86:89]
	v_mfma_f32_16x16x32_bf16 v[90:93], v[82:85], v[214:217], v[90:93]
	v_mfma_f32_16x16x32_bf16 v[90:93], v[70:73], v[210:213], v[90:93]
	s_setprio 0
	s_barrier
	s_add_u32 s98, s70, 0x80
	s_addc_u32 s99, s71, 0
	s_add_u32 s100, s76, 0x80
	s_addc_u32 s101, s77, 0
	s_add_i32 s0, s8, s28
	s_mov_b32 m0, s0
	s_nop 0
	global_load_lds_dwordx4 v192, s[98:99]
	s_add_i32 m0, s0, 0x2000
	s_add_u32 s0, s70, 0x160080
	s_addc_u32 s1, s71, 0
	s_add_i32 s8, s9, s28
	global_load_lds_dwordx4 v190, s[98:99]
	s_mov_b32 m0, s8
	s_nop 0
	global_load_lds_dwordx4 v192, s[0:1]
	s_add_i32 m0, s8, 0x2000
	s_nop 0
	global_load_lds_dwordx4 v190, s[0:1]
	s_mov_b32 m0, s68
	s_nop 0
	global_load_lds_dwordx4 v192, s[100:101]
	s_mov_b32 m0, s79
	s_nop 0
	global_load_lds_dwordx4 v190, s[100:101]
	ds_read_b128 v[158:161], v237 offset:49152
	ds_read_b128 v[170:173], v237 offset:50176
	ds_read_b128 v[174:177], v237 offset:51200
	ds_read_b128 v[178:181], v237 offset:52224
	ds_read_b128 v[182:185], v237 offset:53248
	ds_read_b128 v[186:189], v237 offset:54272
	ds_read_b128 v[210:213], v237 offset:55296
	ds_read_b128 v[214:217], v237 offset:56320
	s_waitcnt vmcnt(8)
	s_waitcnt lgkmcnt(0)
	s_barrier
	s_setprio 1
	s_waitcnt lgkmcnt(0)
	v_mfma_f32_16x16x32_bf16 v[62:65], v[70:73], v[158:161], v[62:65]
	v_mfma_f32_16x16x32_bf16 v[62:65], v[82:85], v[170:173], v[62:65]
	v_mfma_f32_16x16x32_bf16 v[58:61], v[106:109], v[170:173], v[58:61]
	v_mfma_f32_16x16x32_bf16 v[58:61], v[94:97], v[158:161], v[58:61]
	v_mfma_f32_16x16x32_bf16 v[54:57], v[118:121], v[158:161], v[54:57]
	v_mfma_f32_16x16x32_bf16 v[54:57], v[130:133], v[170:173], v[54:57]
	v_mfma_f32_16x16x32_bf16 v[50:53], v[154:157], v[170:173], v[50:53]
	v_mfma_f32_16x16x32_bf16 v[50:53], v[142:145], v[158:161], v[50:53]
	v_mfma_f32_16x16x32_bf16 v[34:37], v[142:145], v[174:177], v[34:37]
	v_mfma_f32_16x16x32_bf16 v[34:37], v[154:157], v[178:181], v[34:37]
	v_mfma_f32_16x16x32_bf16 v[38:41], v[130:133], v[178:181], v[38:41]
	v_mfma_f32_16x16x32_bf16 v[38:41], v[118:121], v[174:177], v[38:41]
	v_mfma_f32_16x16x32_bf16 v[42:45], v[94:97], v[174:177], v[42:45]
	v_mfma_f32_16x16x32_bf16 v[42:45], v[106:109], v[178:181], v[42:45]
	v_mfma_f32_16x16x32_bf16 v[46:49], v[82:85], v[178:181], v[46:49]
	v_mfma_f32_16x16x32_bf16 v[46:49], v[70:73], v[174:177], v[46:49]
	v_mfma_f32_16x16x32_bf16 v[30:33], v[70:73], v[182:185], v[30:33]
	v_mfma_f32_16x16x32_bf16 v[30:33], v[82:85], v[186:189], v[30:33]
	v_mfma_f32_16x16x32_bf16 v[26:29], v[106:109], v[186:189], v[26:29]
	v_mfma_f32_16x16x32_bf16 v[26:29], v[94:97], v[182:185], v[26:29]
	v_mfma_f32_16x16x32_bf16 v[22:25], v[118:121], v[182:185], v[22:25]
	v_mfma_f32_16x16x32_bf16 v[22:25], v[130:133], v[186:189], v[22:25]
	v_mfma_f32_16x16x32_bf16 v[18:21], v[154:157], v[186:189], v[18:21]
	v_mfma_f32_16x16x32_bf16 v[18:21], v[142:145], v[182:185], v[18:21]
	v_mfma_f32_16x16x32_bf16 v[2:5], v[142:145], v[210:213], v[2:5]
	v_mfma_f32_16x16x32_bf16 v[2:5], v[154:157], v[214:217], v[2:5]
	v_mfma_f32_16x16x32_bf16 v[6:9], v[130:133], v[214:217], v[6:9]
	v_mfma_f32_16x16x32_bf16 v[6:9], v[118:121], v[210:213], v[6:9]
	v_mfma_f32_16x16x32_bf16 v[10:13], v[94:97], v[210:213], v[10:13]
	v_mfma_f32_16x16x32_bf16 v[10:13], v[106:109], v[214:217], v[10:13]
	v_mfma_f32_16x16x32_bf16 v[14:17], v[82:85], v[214:217], v[14:17]
	v_mfma_f32_16x16x32_bf16 v[14:17], v[70:73], v[210:213], v[14:17]
	s_setprio 0
	s_barrier
	s_add_i32 s41, s41, 2
	s_add_u32 s7, s7, 0x100
	s_addc_u32 s23, s23, 0
	s_cmpk_gt_u32 s41, 0x55
	s_mov_b64 s[8:9], s[64:65]
	s_cbranch_scc1 .LBB0_648

.Lpeel_disp_down:
	s_cmp_lg_u32 s41, -2
	s_cbranch_scc1 .LBB0_645
	s_add_u32 s64, s8, 0x100
	s_addc_u32 s65, s9, 0
	s_and_b64 s[0:1], s[70:71], exec
	s_cselect_b32 s77, s63, s65
	s_cselect_b32 s76, s62, s64
	s_cselect_b32 s71, s85, s23
	s_cselect_b32 s70, s84, s7
	s_add_i32 s0, 0, 0x10000
	s_add_i32 s18, 0, 0x14000
	s_add_i32 m0, s29, 0xc000
	s_nop 0
	global_load_lds_dwordx4 v206, s[8:9]
	s_add_i32 m0, s29, 0xe000
	s_nop 0
	global_load_lds_dwordx4 v208, s[8:9]
	v_add_u32_e32 v106, s0, v1
	v_add_u32_e32 v154, s18, v1
	ds_read_b128 v[70:73], v106
	ds_read_b128 v[82:85], v106 offset:1024
	ds_read_b128 v[94:97], v106 offset:2048
	ds_read_b128 v[106:109], v106 offset:3072
	ds_read_b128 v[118:121], v154
	ds_read_b128 v[130:133], v154 offset:1024
	ds_read_b128 v[142:145], v154 offset:2048
	ds_read_b128 v[154:157], v154 offset:3072
	ds_read_b128 v[158:161], v237
	ds_read_b128 v[170:173], v237 offset:1024
	ds_read_b128 v[174:177], v237 offset:2048
	ds_read_b128 v[178:181], v237 offset:3072
	ds_read_b128 v[182:185], v237 offset:4096
	ds_read_b128 v[186:189], v237 offset:5120
	ds_read_b128 v[210:213], v237 offset:6144
	ds_read_b128 v[214:217], v237 offset:7168
	s_waitcnt vmcnt(8)
	s_waitcnt lgkmcnt(0)
	s_barrier
	s_setprio 1
	s_waitcnt lgkmcnt(0)
	v_mfma_f32_16x16x32_bf16 v[166:169], v[70:73], v[158:161], 0
	v_mfma_f32_16x16x32_bf16 v[166:169], v[82:85], v[170:173], v[166:169]
	v_mfma_f32_16x16x32_bf16 v[162:165], v[106:109], v[170:173], 0
	v_mfma_f32_16x16x32_bf16 v[162:165], v[94:97], v[158:161], v[162:165]
	v_mfma_f32_16x16x32_bf16 v[150:153], v[118:121], v[158:161], 0
	v_mfma_f32_16x16x32_bf16 v[150:153], v[130:133], v[170:173], v[150:153]
	v_mfma_f32_16x16x32_bf16 v[146:149], v[154:157], v[170:173], 0
	v_mfma_f32_16x16x32_bf16 v[146:149], v[142:145], v[158:161], v[146:149]
	v_mfma_f32_16x16x32_bf16 v[122:125], v[142:145], v[174:177], 0
	v_mfma_f32_16x16x32_bf16 v[122:125], v[154:157], v[178:181], v[122:125]
	v_mfma_f32_16x16x32_bf16 v[126:129], v[130:133], v[178:181], 0
	v_mfma_f32_16x16x32_bf16 v[126:129], v[118:121], v[174:177], v[126:129]
	v_mfma_f32_16x16x32_bf16 v[134:137], v[94:97], v[174:177], 0
	v_mfma_f32_16x16x32_bf16 v[134:137], v[106:109], v[178:181], v[134:137]
	v_mfma_f32_16x16x32_bf16 v[138:141], v[82:85], v[178:181], 0
	v_mfma_f32_16x16x32_bf16 v[138:141], v[70:73], v[174:177], v[138:141]
	v_mfma_f32_16x16x32_bf16 v[114:117], v[70:73], v[182:185], 0
	v_mfma_f32_16x16x32_bf16 v[114:117], v[82:85], v[186:189], v[114:117]
	v_mfma_f32_16x16x32_bf16 v[110:113], v[106:109], v[186:189], 0
	v_mfma_f32_16x16x32_bf16 v[110:113], v[94:97], v[182:185], v[110:113]
	v_mfma_f32_16x16x32_bf16 v[102:105], v[118:121], v[182:185], 0
	v_mfma_f32_16x16x32_bf16 v[102:105], v[130:133], v[186:189], v[102:105]
	v_mfma_f32_16x16x32_bf16 v[98:101], v[154:157], v[186:189], 0
	v_mfma_f32_16x16x32_bf16 v[98:101], v[142:145], v[182:185], v[98:101]
	v_mfma_f32_16x16x32_bf16 v[74:77], v[142:145], v[210:213], 0
	v_mfma_f32_16x16x32_bf16 v[74:77], v[154:157], v[214:217], v[74:77]
	v_mfma_f32_16x16x32_bf16 v[78:81], v[130:133], v[214:217], 0
	v_mfma_f32_16x16x32_bf16 v[78:81], v[118:121], v[210:213], v[78:81]
	v_mfma_f32_16x16x32_bf16 v[86:89], v[94:97], v[210:213], 0
	v_mfma_f32_16x16x32_bf16 v[86:89], v[106:109], v[214:217], v[86:89]
	v_mfma_f32_16x16x32_bf16 v[90:93], v[82:85], v[214:217], 0
	v_mfma_f32_16x16x32_bf16 v[90:93], v[70:73], v[210:213], v[90:93]
	s_setprio 0
	s_barrier
	s_add_i32 s0, s0, s28
	s_mov_b32 m0, s0
	s_nop 0
	global_load_lds_dwordx4 v192, s[70:71]
	s_add_i32 m0, s0, 0x2000
	s_add_u32 s0, s70, 0x160000
	s_addc_u32 s1, s71, 0
	s_add_i32 s8, s18, s28
	global_load_lds_dwordx4 v190, s[70:71]
	s_mov_b32 m0, s8
	s_nop 0
	global_load_lds_dwordx4 v192, s[0:1]
	s_add_i32 m0, s8, 0x2000
	s_nop 0
	global_load_lds_dwordx4 v190, s[0:1]
	s_mov_b32 m0, s29
	s_nop 0
	global_load_lds_dwordx4 v192, s[76:77]
	s_mov_b32 m0, s31
	s_nop 0
	global_load_lds_dwordx4 v190, s[76:77]
	ds_read_b128 v[158:161], v237 offset:16384
	ds_read_b128 v[170:173], v237 offset:17408
	ds_read_b128 v[174:177], v237 offset:18432
	ds_read_b128 v[178:181], v237 offset:19456
	ds_read_b128 v[182:185], v237 offset:20480
	ds_read_b128 v[186:189], v237 offset:21504
	ds_read_b128 v[210:213], v237 offset:22528
	ds_read_b128 v[214:217], v237 offset:23552
	s_waitcnt vmcnt(8)
	s_waitcnt lgkmcnt(0)
	s_barrier
	s_setprio 1
	s_waitcnt lgkmcnt(0)
	v_mfma_f32_16x16x32_bf16 v[62:65], v[70:73], v[158:161], 0
	v_mfma_f32_16x16x32_bf16 v[62:65], v[82:85], v[170:173], v[62:65]
	v_mfma_f32_16x16x32_bf16 v[58:61], v[106:109], v[170:173], 0
	v_mfma_f32_16x16x32_bf16 v[58:61], v[94:97], v[158:161], v[58:61]
	v_mfma_f32_16x16x32_bf16 v[54:57], v[118:121], v[158:161], 0
	v_mfma_f32_16x16x32_bf16 v[54:57], v[130:133], v[170:173], v[54:57]
	v_mfma_f32_16x16x32_bf16 v[50:53], v[154:157], v[170:173], 0
	v_mfma_f32_16x16x32_bf16 v[50:53], v[142:145], v[158:161], v[50:53]
	v_mfma_f32_16x16x32_bf16 v[34:37], v[142:145], v[174:177], 0
	v_mfma_f32_16x16x32_bf16 v[34:37], v[154:157], v[178:181], v[34:37]
	v_mfma_f32_16x16x32_bf16 v[38:41], v[130:133], v[178:181], 0
	v_mfma_f32_16x16x32_bf16 v[38:41], v[118:121], v[174:177], v[38:41]
	v_mfma_f32_16x16x32_bf16 v[42:45], v[94:97], v[174:177], 0
	v_mfma_f32_16x16x32_bf16 v[42:45], v[106:109], v[178:181], v[42:45]
	v_mfma_f32_16x16x32_bf16 v[46:49], v[82:85], v[178:181], 0
	v_mfma_f32_16x16x32_bf16 v[46:49], v[70:73], v[174:177], v[46:49]
	v_mfma_f32_16x16x32_bf16 v[30:33], v[70:73], v[182:185], 0
	v_mfma_f32_16x16x32_bf16 v[30:33], v[82:85], v[186:189], v[30:33]
	v_mfma_f32_16x16x32_bf16 v[26:29], v[106:109], v[186:189], 0
	v_mfma_f32_16x16x32_bf16 v[26:29], v[94:97], v[182:185], v[26:29]
	v_mfma_f32_16x16x32_bf16 v[22:25], v[118:121], v[182:185], 0
	v_mfma_f32_16x16x32_bf16 v[22:25], v[130:133], v[186:189], v[22:25]
	v_mfma_f32_16x16x32_bf16 v[18:21], v[154:157], v[186:189], 0
	v_mfma_f32_16x16x32_bf16 v[18:21], v[142:145], v[182:185], v[18:21]
	v_mfma_f32_16x16x32_bf16 v[2:5], v[142:145], v[210:213], 0
	v_mfma_f32_16x16x32_bf16 v[2:5], v[154:157], v[214:217], v[2:5]
	v_mfma_f32_16x16x32_bf16 v[6:9], v[130:133], v[214:217], 0
	v_mfma_f32_16x16x32_bf16 v[6:9], v[118:121], v[210:213], v[6:9]
	v_mfma_f32_16x16x32_bf16 v[10:13], v[94:97], v[210:213], 0
	v_mfma_f32_16x16x32_bf16 v[10:13], v[106:109], v[214:217], v[10:13]
	v_mfma_f32_16x16x32_bf16 v[14:17], v[82:85], v[214:217], 0
	v_mfma_f32_16x16x32_bf16 v[14:17], v[70:73], v[210:213], v[14:17]
	s_setprio 0
	s_barrier
	s_add_i32 s8, 0, 0x18000
	s_add_i32 s9, 0, 0x1c000
	s_add_u32 s0, s76, 0x160000
	s_addc_u32 s1, s77, 0
	s_mov_b32 m0, s33
	s_nop 0
	global_load_lds_dwordx4 v192, s[0:1]
	s_mov_b32 m0, s43
	s_nop 0
	global_load_lds_dwordx4 v190, s[0:1]
	v_add_u32_e32 v106, s8, v1
	v_add_u32_e32 v154, s9, v1
	ds_read_b128 v[70:73], v106
	ds_read_b128 v[82:85], v106 offset:1024
	ds_read_b128 v[94:97], v106 offset:2048
	ds_read_b128 v[106:109], v106 offset:3072
	ds_read_b128 v[118:121], v154
	ds_read_b128 v[130:133], v154 offset:1024
	ds_read_b128 v[142:145], v154 offset:2048
	ds_read_b128 v[154:157], v154 offset:3072
	ds_read_b128 v[158:161], v237 offset:32768
	ds_read_b128 v[170:173], v237 offset:33792
	ds_read_b128 v[174:177], v237 offset:34816
	ds_read_b128 v[178:181], v237 offset:35840
	ds_read_b128 v[182:185], v237 offset:36864
	ds_read_b128 v[186:189], v237 offset:37888
	ds_read_b128 v[210:213], v237 offset:38912
	ds_read_b128 v[214:217], v237 offset:39936
	s_waitcnt vmcnt(8)
	s_waitcnt lgkmcnt(0)
	s_barrier
	s_setprio 1
	s_waitcnt lgkmcnt(0)
	v_mfma_f32_16x16x32_bf16 v[166:169], v[70:73], v[158:161], v[166:169]
	v_mfma_f32_16x16x32_bf16 v[166:169], v[82:85], v[170:173], v[166:169]
	v_mfma_f32_16x16x32_bf16 v[162:165], v[106:109], v[170:173], v[162:165]
	v_mfma_f32_16x16x32_bf16 v[162:165], v[94:97], v[158:161], v[162:165]
	v_mfma_f32_16x16x32_bf16 v[150:153], v[118:121], v[158:161], v[150:153]
	v_mfma_f32_16x16x32_bf16 v[150:153], v[130:133], v[170:173], v[150:153]
	v_mfma_f32_16x16x32_bf16 v[146:149], v[154:157], v[170:173], v[146:149]
	v_mfma_f32_16x16x32_bf16 v[146:149], v[142:145], v[158:161], v[146:149]
	v_mfma_f32_16x16x32_bf16 v[122:125], v[142:145], v[174:177], v[122:125]
	v_mfma_f32_16x16x32_bf16 v[122:125], v[154:157], v[178:181], v[122:125]
	v_mfma_f32_16x16x32_bf16 v[126:129], v[130:133], v[178:181], v[126:129]
	v_mfma_f32_16x16x32_bf16 v[126:129], v[118:121], v[174:177], v[126:129]
	v_mfma_f32_16x16x32_bf16 v[134:137], v[94:97], v[174:177], v[134:137]
	v_mfma_f32_16x16x32_bf16 v[134:137], v[106:109], v[178:181], v[134:137]
	v_mfma_f32_16x16x32_bf16 v[138:141], v[82:85], v[178:181], v[138:141]
	v_mfma_f32_16x16x32_bf16 v[138:141], v[70:73], v[174:177], v[138:141]
	v_mfma_f32_16x16x32_bf16 v[114:117], v[70:73], v[182:185], v[114:117]
	v_mfma_f32_16x16x32_bf16 v[114:117], v[82:85], v[186:189], v[114:117]
	v_mfma_f32_16x16x32_bf16 v[110:113], v[106:109], v[186:189], v[110:113]
	v_mfma_f32_16x16x32_bf16 v[110:113], v[94:97], v[182:185], v[110:113]
	v_mfma_f32_16x16x32_bf16 v[102:105], v[118:121], v[182:185], v[102:105]
	v_mfma_f32_16x16x32_bf16 v[102:105], v[130:133], v[186:189], v[102:105]
	v_mfma_f32_16x16x32_bf16 v[98:101], v[154:157], v[186:189], v[98:101]
	v_mfma_f32_16x16x32_bf16 v[98:101], v[142:145], v[182:185], v[98:101]
	v_mfma_f32_16x16x32_bf16 v[74:77], v[142:145], v[210:213], v[74:77]
	v_mfma_f32_16x16x32_bf16 v[74:77], v[154:157], v[214:217], v[74:77]
	v_mfma_f32_16x16x32_bf16 v[78:81], v[130:133], v[214:217], v[78:81]
	v_mfma_f32_16x16x32_bf16 v[78:81], v[118:121], v[210:213], v[78:81]
	v_mfma_f32_16x16x32_bf16 v[86:89], v[94:97], v[210:213], v[86:89]
	v_mfma_f32_16x16x32_bf16 v[86:89], v[106:109], v[214:217], v[86:89]
	v_mfma_f32_16x16x32_bf16 v[90:93], v[82:85], v[214:217], v[90:93]
	v_mfma_f32_16x16x32_bf16 v[90:93], v[70:73], v[210:213], v[90:93]
	s_setprio 0
	s_barrier
	s_add_u32 s98, s70, 0x80
	s_addc_u32 s99, s71, 0
	s_add_u32 s100, s76, 0x80
	s_addc_u32 s101, s77, 0
	s_add_i32 s0, s8, s28
	s_mov_b32 m0, s0
	s_nop 0
	global_load_lds_dwordx4 v192, s[98:99]
	s_add_i32 m0, s0, 0x2000
	s_add_u32 s0, s70, 0x160080
	s_addc_u32 s1, s71, 0
	s_add_i32 s8, s9, s28
	global_load_lds_dwordx4 v190, s[98:99]
	s_mov_b32 m0, s8
	s_nop 0
	global_load_lds_dwordx4 v192, s[0:1]
	s_add_i32 m0, s8, 0x2000
	s_nop 0
	global_load_lds_dwordx4 v190, s[0:1]
	s_mov_b32 m0, s68
	s_nop 0
	global_load_lds_dwordx4 v192, s[100:101]
	s_mov_b32 m0, s79
	s_nop 0
	global_load_lds_dwordx4 v190, s[100:101]
	ds_read_b128 v[158:161], v237 offset:49152
	ds_read_b128 v[170:173], v237 offset:50176
	ds_read_b128 v[174:177], v237 offset:51200
	ds_read_b128 v[178:181], v237 offset:52224
	ds_read_b128 v[182:185], v237 offset:53248
	ds_read_b128 v[186:189], v237 offset:54272
	ds_read_b128 v[210:213], v237 offset:55296
	ds_read_b128 v[214:217], v237 offset:56320
	s_waitcnt vmcnt(8)
	s_waitcnt lgkmcnt(0)
	s_barrier
	s_setprio 1
	s_waitcnt lgkmcnt(0)
	v_mfma_f32_16x16x32_bf16 v[62:65], v[70:73], v[158:161], v[62:65]
	v_mfma_f32_16x16x32_bf16 v[62:65], v[82:85], v[170:173], v[62:65]
	v_mfma_f32_16x16x32_bf16 v[58:61], v[106:109], v[170:173], v[58:61]
	v_mfma_f32_16x16x32_bf16 v[58:61], v[94:97], v[158:161], v[58:61]
	v_mfma_f32_16x16x32_bf16 v[54:57], v[118:121], v[158:161], v[54:57]
	v_mfma_f32_16x16x32_bf16 v[54:57], v[130:133], v[170:173], v[54:57]
	v_mfma_f32_16x16x32_bf16 v[50:53], v[154:157], v[170:173], v[50:53]
	v_mfma_f32_16x16x32_bf16 v[50:53], v[142:145], v[158:161], v[50:53]
	v_mfma_f32_16x16x32_bf16 v[34:37], v[142:145], v[174:177], v[34:37]
	v_mfma_f32_16x16x32_bf16 v[34:37], v[154:157], v[178:181], v[34:37]
	v_mfma_f32_16x16x32_bf16 v[38:41], v[130:133], v[178:181], v[38:41]
	v_mfma_f32_16x16x32_bf16 v[38:41], v[118:121], v[174:177], v[38:41]
	v_mfma_f32_16x16x32_bf16 v[42:45], v[94:97], v[174:177], v[42:45]
	v_mfma_f32_16x16x32_bf16 v[42:45], v[106:109], v[178:181], v[42:45]
	v_mfma_f32_16x16x32_bf16 v[46:49], v[82:85], v[178:181], v[46:49]
	v_mfma_f32_16x16x32_bf16 v[46:49], v[70:73], v[174:177], v[46:49]
	v_mfma_f32_16x16x32_bf16 v[30:33], v[70:73], v[182:185], v[30:33]
	v_mfma_f32_16x16x32_bf16 v[30:33], v[82:85], v[186:189], v[30:33]
	v_mfma_f32_16x16x32_bf16 v[26:29], v[106:109], v[186:189], v[26:29]
	v_mfma_f32_16x16x32_bf16 v[26:29], v[94:97], v[182:185], v[26:29]
	v_mfma_f32_16x16x32_bf16 v[22:25], v[118:121], v[182:185], v[22:25]
	v_mfma_f32_16x16x32_bf16 v[22:25], v[130:133], v[186:189], v[22:25]
	v_mfma_f32_16x16x32_bf16 v[18:21], v[154:157], v[186:189], v[18:21]
	v_mfma_f32_16x16x32_bf16 v[18:21], v[142:145], v[182:185], v[18:21]
	v_mfma_f32_16x16x32_bf16 v[2:5], v[142:145], v[210:213], v[2:5]
	v_mfma_f32_16x16x32_bf16 v[2:5], v[154:157], v[214:217], v[2:5]
	v_mfma_f32_16x16x32_bf16 v[6:9], v[130:133], v[214:217], v[6:9]
	v_mfma_f32_16x16x32_bf16 v[6:9], v[118:121], v[210:213], v[6:9]
	v_mfma_f32_16x16x32_bf16 v[10:13], v[94:97], v[210:213], v[10:13]
	v_mfma_f32_16x16x32_bf16 v[10:13], v[106:109], v[214:217], v[10:13]
	v_mfma_f32_16x16x32_bf16 v[14:17], v[82:85], v[214:217], v[14:17]
	v_mfma_f32_16x16x32_bf16 v[14:17], v[70:73], v[210:213], v[14:17]
	s_setprio 0
	s_barrier
	s_add_i32 s41, s41, 2
	s_add_u32 s7, s7, 0x100
	s_addc_u32 s23, s23, 0
	s_cmpk_gt_u32 s41, 0x55
	s_mov_b64 s[8:9], s[64:65]
	s_cbranch_scc1 .LBB0_648
	s_branch .LBB0_646
